# plus loader segments issue the LDS-DMA loads before the ds_reads in all K-loops
# speedup vs baseline: 1.0038x; 1.0038x over previous
; #define PG8_STAGE(bufoff, gbase, voff) do { _Pragma("unroll") for (int _i = 0; _i < 2; ++_i) \
;         __builtin_amdgcn_global_load_lds((const unsigned*)((const char*)(gbase) + (voff)[_i]), (LAS unsigned*)(lds + (bufoff) + ldsw + _i * 8192), 16, 0, 0); } while (0)
; #define PG8_LDA(dst, b, h) do { _Pragma("unroll") for (int m = 0; m < 4; ++m) _Pragma("unroll") for (int k = 0; k < 2; ++k) dst[m][k] = *(const LAS bf16x8*)(lds + PG8_SA(b, h) + aoff + m * 2048 + k * 1024); } while (0)
; #define PG8_LDB(dst, b, h) do { _Pragma("unroll") for (int n = 0; n < 2; ++n) _Pragma("unroll") for (int k = 0; k < 2; ++k) dst[n][k] = *(const LAS bf16x8*)(lds + PG8_SB(b, h) + boff + n * 2048 + k * 1024); } while (0)
; #define PG8_MMA(ai, bj, At, Bt) do { __builtin_amdgcn_s_setprio(1); _Pragma("unroll") for (int m = 0; m < 4; ++m) _Pragma("unroll") for (int n = 0; n < 2; ++n) _Pragma("unroll") for (int k = 0; k < 2; ++k) \
;         acc[ai][bj][m][n] = __builtin_amdgcn_mfma_f32_16x16x32_bf16(Bt[n][k], At[m][k], acc[ai][bj][m][n], 0, 0, 0); __builtin_amdgcn_s_setprio(0); } while (0)
; #define PG8_WAIT_V(n) asm volatile("s_waitcnt vmcnt(" #n ")" ::: "memory")
; #define PG8_WAIT_L(n) asm volatile("s_waitcnt lgkmcnt(" #n ")" ::: "memory")
; #define PG8_BAR __builtin_amdgcn_s_barrier()
; #define PG8_SCHED __builtin_amdgcn_sched_barrier(0)
; template <class Epi>
; __device__ __forceinline__ void gemm_phase(ldsp lds, const Gemm g, const StaticOrder& S, const Epi& E, int wave0) {
;     ...
;             const bool last = (t == nt - 2);
;             const char* a1 = cA + (size_t)(t + 1) * kstep;
;             const char* a2 = last ? nA : cA + (size_t)(t + 2) * kstep; const char* b2 = last ? nB : cB + (size_t)(t + 2) * kstep;
;             const char* a3 = a2 + kstep; const char* b3 = b2 + kstep;
;             PG8_LDB(B0, 0, 0); PG8_LDB(B1, 0, 1); PG8_SCHED; PG8_LDA(At, 0, 0); PG8_STAGE(PG8_SA(1, 1), a1 + hstep, voffA);
;             PG8_WAIT_V(8); PG8_WAIT_L(0); PG8_BAR; PG8_MMA(0, 0, At, B0); PG8_MMA(0, 1, At, B1); PG8_BAR; PG8_SCHED;
;             PG8_LDA(At, 0, 1); PG8_STAGE(PG8_SB(0, 0), b2, voffB); PG8_STAGE(PG8_SB(0, 1), b2 + hstep, voffB); PG8_STAGE(PG8_SA(0, 0), a2, voffA);
;             PG8_WAIT_V(8); PG8_WAIT_L(0); PG8_BAR; PG8_MMA(1, 0, At, B0); PG8_MMA(1, 1, At, B1); PG8_BAR; PG8_SCHED;
.LBB0_150:
	s_add_u32 s22, s20, 0xfff80080
	s_addc_u32 s23, s21, -1
	s_cmp_eq_u32 s54, 28
	s_cselect_b32 s25, s13, s23
	s_cselect_b32 s24, s50, s22
	s_cselect_b32 s23, s11, s53
	s_cselect_b32 s22, s51, s52
	s_add_i32 m0, s19, 0xc000
	s_nop 0
	global_load_lds_dwordx4 v138, s[20:21]
	s_add_i32 m0, s19, 0xe000
	s_nop 0
	global_load_lds_dwordx4 v136, s[20:21]
	ds_read_b128 v[152:155], v149
	ds_read_b128 v[156:159], v149 offset:1024
	ds_read_b128 v[160:163], v149 offset:2048
	ds_read_b128 v[164:167], v149 offset:3072
	ds_read_b128 v[168:171], v150
	ds_read_b128 v[172:175], v150 offset:1024
	ds_read_b128 v[176:179], v150 offset:2048
	ds_read_b128 v[180:183], v150 offset:3072
	ds_read_b128 v[184:187], v151
	ds_read_b128 v[188:191], v151 offset:1024
	ds_read_b128 v[192:195], v151 offset:2048
	ds_read_b128 v[196:199], v151 offset:3072
	ds_read_b128 v[200:203], v151 offset:4096
	ds_read_b128 v[204:207], v151 offset:5120
	ds_read_b128 v[208:211], v151 offset:6144
	ds_read_b128 v[212:215], v151 offset:7168
	s_waitcnt vmcnt(8)
	s_waitcnt lgkmcnt(0)
	s_barrier
	s_setprio 1
	s_waitcnt lgkmcnt(0)
	v_mfma_f32_16x16x32_bf16 v[124:127], v[152:155], v[184:187], v[124:127]
	v_mfma_f32_16x16x32_bf16 v[120:123], v[160:163], v[184:187], v[120:123]
	v_mfma_f32_16x16x32_bf16 v[108:111], v[152:155], v[192:195], v[108:111]
	v_mfma_f32_16x16x32_bf16 v[104:107], v[160:163], v[192:195], v[104:107]
	v_mfma_f32_16x16x32_bf16 v[92:95], v[152:155], v[200:203], v[92:95]
	v_mfma_f32_16x16x32_bf16 v[88:91], v[160:163], v[200:203], v[88:91]
	v_mfma_f32_16x16x32_bf16 v[76:79], v[152:155], v[208:211], v[76:79]
	v_mfma_f32_16x16x32_bf16 v[72:75], v[160:163], v[208:211], v[72:75]
	v_mfma_f32_16x16x32_bf16 v[124:127], v[156:159], v[188:191], v[124:127]
	v_mfma_f32_16x16x32_bf16 v[120:123], v[164:167], v[188:191], v[120:123]
	v_mfma_f32_16x16x32_bf16 v[108:111], v[156:159], v[196:199], v[108:111]
	v_mfma_f32_16x16x32_bf16 v[104:107], v[164:167], v[196:199], v[104:107]
	v_mfma_f32_16x16x32_bf16 v[92:95], v[156:159], v[204:207], v[92:95]
	v_mfma_f32_16x16x32_bf16 v[88:91], v[164:167], v[204:207], v[88:91]
	v_mfma_f32_16x16x32_bf16 v[76:79], v[156:159], v[212:215], v[76:79]
	v_mfma_f32_16x16x32_bf16 v[72:75], v[164:167], v[212:215], v[72:75]
	s_setprio 0
	s_setprio 1
	v_mfma_f32_16x16x32_bf16 v[116:119], v[168:171], v[184:187], v[116:119]
	v_mfma_f32_16x16x32_bf16 v[112:115], v[176:179], v[184:187], v[112:115]
	v_mfma_f32_16x16x32_bf16 v[100:103], v[168:171], v[192:195], v[100:103]
	v_mfma_f32_16x16x32_bf16 v[96:99], v[176:179], v[192:195], v[96:99]
	v_mfma_f32_16x16x32_bf16 v[84:87], v[168:171], v[200:203], v[84:87]
	v_mfma_f32_16x16x32_bf16 v[80:83], v[176:179], v[200:203], v[80:83]
	v_mfma_f32_16x16x32_bf16 v[68:71], v[168:171], v[208:211], v[68:71]
	v_mfma_f32_16x16x32_bf16 v[64:67], v[176:179], v[208:211], v[64:67]
	v_mfma_f32_16x16x32_bf16 v[116:119], v[172:175], v[188:191], v[116:119]
	v_mfma_f32_16x16x32_bf16 v[112:115], v[180:183], v[188:191], v[112:115]
	v_mfma_f32_16x16x32_bf16 v[100:103], v[172:175], v[196:199], v[100:103]
	v_mfma_f32_16x16x32_bf16 v[96:99], v[180:183], v[196:199], v[96:99]
	v_mfma_f32_16x16x32_bf16 v[84:87], v[172:175], v[204:207], v[84:87]
	v_mfma_f32_16x16x32_bf16 v[80:83], v[180:183], v[204:207], v[80:83]
	v_mfma_f32_16x16x32_bf16 v[68:71], v[172:175], v[212:215], v[68:71]
	v_mfma_f32_16x16x32_bf16 v[64:67], v[180:183], v[212:215], v[64:67]
	s_setprio 0
	s_barrier
	s_add_i32 s55, s46, s34
	s_add_u32 s100, s24, 0x80
	s_addc_u32 s101, s25, 0
	s_mov_b32 m0, s55
	s_nop 0
	global_load_lds_dwordx4 v132, s[22:23]
	s_add_i32 m0, s55, 0x2000
	s_add_u32 s56, s22, 0x80000
	s_addc_u32 s57, s23, 0
	s_add_i32 s55, s47, s34
	global_load_lds_dwordx4 v128, s[22:23]
	s_mov_b32 m0, s55
	s_nop 0
	global_load_lds_dwordx4 v132, s[56:57]
	s_add_i32 m0, s55, 0x2000
	s_nop 0
	global_load_lds_dwordx4 v128, s[56:57]
	s_mov_b32 m0, s19
	s_nop 0
	global_load_lds_dwordx4 v134, s[24:25]
	s_mov_b32 m0, s37
	s_nop 0
	global_load_lds_dwordx4 v130, s[24:25]
	ds_read_b128 v[184:187], v151 offset:16384
	ds_read_b128 v[188:191], v151 offset:17408
	ds_read_b128 v[192:195], v151 offset:18432
	ds_read_b128 v[196:199], v151 offset:19456
	ds_read_b128 v[200:203], v151 offset:20480
	ds_read_b128 v[204:207], v151 offset:21504
	ds_read_b128 v[208:211], v151 offset:22528
	ds_read_b128 v[212:215], v151 offset:23552
	s_waitcnt vmcnt(8)
	s_waitcnt lgkmcnt(0)
	s_barrier
	s_setprio 1
	s_waitcnt lgkmcnt(0)
	v_mfma_f32_16x16x32_bf16 v[60:63], v[152:155], v[184:187], v[60:63]
	v_mfma_f32_16x16x32_bf16 v[56:59], v[160:163], v[184:187], v[56:59]
	v_mfma_f32_16x16x32_bf16 v[44:47], v[152:155], v[192:195], v[44:47]
	v_mfma_f32_16x16x32_bf16 v[40:43], v[160:163], v[192:195], v[40:43]
	v_mfma_f32_16x16x32_bf16 v[28:31], v[152:155], v[200:203], v[28:31]
	v_mfma_f32_16x16x32_bf16 v[24:27], v[160:163], v[200:203], v[24:27]
	v_mfma_f32_16x16x32_bf16 v[12:15], v[152:155], v[208:211], v[12:15]
	v_mfma_f32_16x16x32_bf16 v[8:11], v[160:163], v[208:211], v[8:11]
	v_mfma_f32_16x16x32_bf16 v[60:63], v[156:159], v[188:191], v[60:63]
	v_mfma_f32_16x16x32_bf16 v[56:59], v[164:167], v[188:191], v[56:59]
	v_mfma_f32_16x16x32_bf16 v[44:47], v[156:159], v[196:199], v[44:47]
	v_mfma_f32_16x16x32_bf16 v[40:43], v[164:167], v[196:199], v[40:43]
	v_mfma_f32_16x16x32_bf16 v[28:31], v[156:159], v[204:207], v[28:31]
	v_mfma_f32_16x16x32_bf16 v[24:27], v[164:167], v[204:207], v[24:27]
	v_mfma_f32_16x16x32_bf16 v[12:15], v[156:159], v[212:215], v[12:15]
	v_mfma_f32_16x16x32_bf16 v[8:11], v[164:167], v[212:215], v[8:11]
	s_setprio 0
	s_setprio 1
	v_mfma_f32_16x16x32_bf16 v[52:55], v[168:171], v[184:187], v[52:55]
	v_mfma_f32_16x16x32_bf16 v[48:51], v[176:179], v[184:187], v[48:51]
	v_mfma_f32_16x16x32_bf16 v[36:39], v[168:171], v[192:195], v[36:39]
	v_mfma_f32_16x16x32_bf16 v[32:35], v[176:179], v[192:195], v[32:35]
	v_mfma_f32_16x16x32_bf16 v[20:23], v[168:171], v[200:203], v[20:23]
	v_mfma_f32_16x16x32_bf16 v[16:19], v[176:179], v[200:203], v[16:19]
	v_mfma_f32_16x16x32_bf16 v[4:7], v[168:171], v[208:211], v[4:7]
	v_mfma_f32_16x16x32_bf16 v[0:3], v[176:179], v[208:211], v[0:3]
	v_mfma_f32_16x16x32_bf16 v[52:55], v[172:175], v[188:191], v[52:55]
	v_mfma_f32_16x16x32_bf16 v[48:51], v[180:183], v[188:191], v[48:51]
	v_mfma_f32_16x16x32_bf16 v[36:39], v[172:175], v[196:199], v[36:39]
	v_mfma_f32_16x16x32_bf16 v[32:35], v[180:183], v[196:199], v[32:35]
	v_mfma_f32_16x16x32_bf16 v[20:23], v[172:175], v[204:207], v[20:23]
	v_mfma_f32_16x16x32_bf16 v[16:19], v[180:183], v[204:207], v[16:19]
	v_mfma_f32_16x16x32_bf16 v[4:7], v[172:175], v[212:215], v[4:7]
	v_mfma_f32_16x16x32_bf16 v[0:3], v[180:183], v[212:215], v[0:3]
	s_setprio 0
	s_barrier
; #define PG8_STAGE(bufoff, gbase, voff) do { _Pragma("unroll") for (int _i = 0; _i < 2; ++_i) \
;         __builtin_amdgcn_global_load_lds((const unsigned*)((const char*)(gbase) + (voff)[_i]), (LAS unsigned*)(lds + (bufoff) + ldsw + _i * 8192), 16, 0, 0); } while (0)
; #define PG8_LDA(dst, b, h) do { _Pragma("unroll") for (int m = 0; m < 4; ++m) _Pragma("unroll") for (int k = 0; k < 2; ++k) dst[m][k] = *(const LAS bf16x8*)(lds + PG8_SA(b, h) + aoff + m * 2048 + k * 1024); } while (0)
; #define PG8_LDB(dst, b, h) do { _Pragma("unroll") for (int n = 0; n < 2; ++n) _Pragma("unroll") for (int k = 0; k < 2; ++k) dst[n][k] = *(const LAS bf16x8*)(lds + PG8_SB(b, h) + boff + n * 2048 + k * 1024); } while (0)
; #define PG8_MMA(ai, bj, At, Bt) do { __builtin_amdgcn_s_setprio(1); _Pragma("unroll") for (int m = 0; m < 4; ++m) _Pragma("unroll") for (int n = 0; n < 2; ++n) _Pragma("unroll") for (int k = 0; k < 2; ++k) \
;         acc[ai][bj][m][n] = __builtin_amdgcn_mfma_f32_16x16x32_bf16(Bt[n][k], At[m][k], acc[ai][bj][m][n], 0, 0, 0); __builtin_amdgcn_s_setprio(0); } while (0)
; #define PG8_WAIT_V(n) asm volatile("s_waitcnt vmcnt(" #n ")" ::: "memory")
; #define PG8_WAIT_L(n) asm volatile("s_waitcnt lgkmcnt(" #n ")" ::: "memory")
; #define PG8_BAR __builtin_amdgcn_s_barrier()
; #define PG8_SCHED __builtin_amdgcn_sched_barrier(0)
; template <class Epi>
; __device__ __forceinline__ void gemm_phase(ldsp lds, const Gemm g, const StaticOrder& S, const Epi& E, int wave0) {
;     ...
;             PG8_LDB(B0, 1, 0); PG8_LDB(B1, 1, 1); PG8_SCHED; PG8_LDA(At, 1, 0); PG8_STAGE(PG8_SA(0, 1), a2 + hstep, voffA);
;             PG8_WAIT_V(8); PG8_WAIT_L(0); PG8_BAR; PG8_MMA(0, 0, At, B0); PG8_MMA(0, 1, At, B1); PG8_BAR; PG8_SCHED;
;             PG8_LDA(At, 1, 1); PG8_STAGE(PG8_SB(1, 0), b3, voffB); PG8_STAGE(PG8_SB(1, 1), b3 + hstep, voffB); PG8_STAGE(PG8_SA(1, 0), a3, voffA);
;             PG8_WAIT_V(8); PG8_WAIT_L(0); PG8_BAR; PG8_MMA(1, 0, At, B0); PG8_MMA(1, 1, At, B1); PG8_BAR; PG8_SCHED;
;         }
;         if (wr == 0) PG8_BAR;
	s_add_i32 s55, 0, 0x18000
	s_add_i32 s56, 0, 0x1c000
	v_add_u32_e32 v164, s55, v148
	v_add_u32_e32 v180, s56, v148
	s_add_u32 s24, s24, 0x80000
	s_addc_u32 s25, s25, 0
	s_mov_b32 m0, s38
	s_nop 0
	global_load_lds_dwordx4 v134, s[24:25]
	s_mov_b32 m0, s39
	s_nop 0
	global_load_lds_dwordx4 v130, s[24:25]
	ds_read_b128 v[152:155], v164
	ds_read_b128 v[156:159], v164 offset:1024
	ds_read_b128 v[160:163], v164 offset:2048
	ds_read_b128 v[164:167], v164 offset:3072
	ds_read_b128 v[168:171], v180
	ds_read_b128 v[172:175], v180 offset:1024
	ds_read_b128 v[176:179], v180 offset:2048
	ds_read_b128 v[180:183], v180 offset:3072
	ds_read_b128 v[184:187], v151 offset:32768
	ds_read_b128 v[188:191], v151 offset:33792
	ds_read_b128 v[192:195], v151 offset:34816
	ds_read_b128 v[196:199], v151 offset:35840
	ds_read_b128 v[200:203], v151 offset:36864
	ds_read_b128 v[204:207], v151 offset:37888
	ds_read_b128 v[208:211], v151 offset:38912
	ds_read_b128 v[212:215], v151 offset:39936
	s_waitcnt vmcnt(8)
	s_waitcnt lgkmcnt(0)
	s_barrier
	s_setprio 1
	s_waitcnt lgkmcnt(0)
	v_mfma_f32_16x16x32_bf16 v[124:127], v[152:155], v[184:187], v[124:127]
	v_mfma_f32_16x16x32_bf16 v[120:123], v[160:163], v[184:187], v[120:123]
	v_mfma_f32_16x16x32_bf16 v[108:111], v[152:155], v[192:195], v[108:111]
	v_mfma_f32_16x16x32_bf16 v[104:107], v[160:163], v[192:195], v[104:107]
	v_mfma_f32_16x16x32_bf16 v[92:95], v[152:155], v[200:203], v[92:95]
	v_mfma_f32_16x16x32_bf16 v[88:91], v[160:163], v[200:203], v[88:91]
	v_mfma_f32_16x16x32_bf16 v[76:79], v[152:155], v[208:211], v[76:79]
	v_mfma_f32_16x16x32_bf16 v[72:75], v[160:163], v[208:211], v[72:75]
	v_mfma_f32_16x16x32_bf16 v[124:127], v[156:159], v[188:191], v[124:127]
	v_mfma_f32_16x16x32_bf16 v[120:123], v[164:167], v[188:191], v[120:123]
	v_mfma_f32_16x16x32_bf16 v[108:111], v[156:159], v[196:199], v[108:111]
	v_mfma_f32_16x16x32_bf16 v[104:107], v[164:167], v[196:199], v[104:107]
	v_mfma_f32_16x16x32_bf16 v[92:95], v[156:159], v[204:207], v[92:95]
	v_mfma_f32_16x16x32_bf16 v[88:91], v[164:167], v[204:207], v[88:91]
	v_mfma_f32_16x16x32_bf16 v[76:79], v[156:159], v[212:215], v[76:79]
	v_mfma_f32_16x16x32_bf16 v[72:75], v[164:167], v[212:215], v[72:75]
	s_setprio 0
	s_setprio 1
	v_mfma_f32_16x16x32_bf16 v[116:119], v[168:171], v[184:187], v[116:119]
	v_mfma_f32_16x16x32_bf16 v[112:115], v[176:179], v[184:187], v[112:115]
	v_mfma_f32_16x16x32_bf16 v[100:103], v[168:171], v[192:195], v[100:103]
	v_mfma_f32_16x16x32_bf16 v[96:99], v[176:179], v[192:195], v[96:99]
	v_mfma_f32_16x16x32_bf16 v[84:87], v[168:171], v[200:203], v[84:87]
	v_mfma_f32_16x16x32_bf16 v[80:83], v[176:179], v[200:203], v[80:83]
	v_mfma_f32_16x16x32_bf16 v[68:71], v[168:171], v[208:211], v[68:71]
	v_mfma_f32_16x16x32_bf16 v[64:67], v[176:179], v[208:211], v[64:67]
	v_mfma_f32_16x16x32_bf16 v[116:119], v[172:175], v[188:191], v[116:119]
	v_mfma_f32_16x16x32_bf16 v[112:115], v[180:183], v[188:191], v[112:115]
	v_mfma_f32_16x16x32_bf16 v[100:103], v[172:175], v[196:199], v[100:103]
	v_mfma_f32_16x16x32_bf16 v[96:99], v[180:183], v[196:199], v[96:99]
	v_mfma_f32_16x16x32_bf16 v[84:87], v[172:175], v[204:207], v[84:87]
	v_mfma_f32_16x16x32_bf16 v[80:83], v[180:183], v[204:207], v[80:83]
	v_mfma_f32_16x16x32_bf16 v[68:71], v[172:175], v[212:215], v[68:71]
	v_mfma_f32_16x16x32_bf16 v[64:67], v[180:183], v[212:215], v[64:67]
	s_setprio 0
	s_barrier
	s_add_i32 s24, s55, s34
	s_add_u32 s22, s22, 0x80
	s_addc_u32 s23, s23, 0
	s_mov_b32 m0, s24
	s_nop 0
	global_load_lds_dwordx4 v132, s[22:23]
	s_add_i32 m0, s24, 0x2000
	s_add_i32 s24, s56, s34
	global_load_lds_dwordx4 v128, s[22:23]
	s_add_u32 s22, s22, 0x80000
	s_addc_u32 s23, s23, 0
	s_mov_b32 m0, s24
	s_nop 0
	global_load_lds_dwordx4 v132, s[22:23]
	s_add_i32 m0, s24, 0x2000
	s_nop 0
	global_load_lds_dwordx4 v128, s[22:23]
	s_mov_b32 m0, s42
	s_nop 0
	global_load_lds_dwordx4 v134, s[100:101]
	s_mov_b32 m0, s43
	s_nop 0
	global_load_lds_dwordx4 v130, s[100:101]
	ds_read_b128 v[184:187], v151 offset:49152
	ds_read_b128 v[188:191], v151 offset:50176
	ds_read_b128 v[192:195], v151 offset:51200
	ds_read_b128 v[196:199], v151 offset:52224
	ds_read_b128 v[200:203], v151 offset:53248
	ds_read_b128 v[204:207], v151 offset:54272
	ds_read_b128 v[208:211], v151 offset:55296
	ds_read_b128 v[212:215], v151 offset:56320
	s_waitcnt vmcnt(8)
	s_waitcnt lgkmcnt(0)
	s_barrier
	s_setprio 1
	s_waitcnt lgkmcnt(0)
	v_mfma_f32_16x16x32_bf16 v[60:63], v[152:155], v[184:187], v[60:63]
	v_mfma_f32_16x16x32_bf16 v[56:59], v[160:163], v[184:187], v[56:59]
	v_mfma_f32_16x16x32_bf16 v[44:47], v[152:155], v[192:195], v[44:47]
	v_mfma_f32_16x16x32_bf16 v[40:43], v[160:163], v[192:195], v[40:43]
	v_mfma_f32_16x16x32_bf16 v[28:31], v[152:155], v[200:203], v[28:31]
	v_mfma_f32_16x16x32_bf16 v[24:27], v[160:163], v[200:203], v[24:27]
	v_mfma_f32_16x16x32_bf16 v[12:15], v[152:155], v[208:211], v[12:15]
	v_mfma_f32_16x16x32_bf16 v[8:11], v[160:163], v[208:211], v[8:11]
	v_mfma_f32_16x16x32_bf16 v[60:63], v[156:159], v[188:191], v[60:63]
	v_mfma_f32_16x16x32_bf16 v[56:59], v[164:167], v[188:191], v[56:59]
	v_mfma_f32_16x16x32_bf16 v[44:47], v[156:159], v[196:199], v[44:47]
	v_mfma_f32_16x16x32_bf16 v[40:43], v[164:167], v[196:199], v[40:43]
	v_mfma_f32_16x16x32_bf16 v[28:31], v[156:159], v[204:207], v[28:31]
	v_mfma_f32_16x16x32_bf16 v[24:27], v[164:167], v[204:207], v[24:27]
	v_mfma_f32_16x16x32_bf16 v[12:15], v[156:159], v[212:215], v[12:15]
	v_mfma_f32_16x16x32_bf16 v[8:11], v[164:167], v[212:215], v[8:11]
	s_setprio 0
	s_setprio 1
	v_mfma_f32_16x16x32_bf16 v[52:55], v[168:171], v[184:187], v[52:55]
	v_mfma_f32_16x16x32_bf16 v[48:51], v[176:179], v[184:187], v[48:51]
	v_mfma_f32_16x16x32_bf16 v[36:39], v[168:171], v[192:195], v[36:39]
	v_mfma_f32_16x16x32_bf16 v[32:35], v[176:179], v[192:195], v[32:35]
	v_mfma_f32_16x16x32_bf16 v[20:23], v[168:171], v[200:203], v[20:23]
	v_mfma_f32_16x16x32_bf16 v[16:19], v[176:179], v[200:203], v[16:19]
	v_mfma_f32_16x16x32_bf16 v[4:7], v[168:171], v[208:211], v[4:7]
	v_mfma_f32_16x16x32_bf16 v[0:3], v[176:179], v[208:211], v[0:3]
	v_mfma_f32_16x16x32_bf16 v[52:55], v[172:175], v[188:191], v[52:55]
	v_mfma_f32_16x16x32_bf16 v[48:51], v[180:183], v[188:191], v[48:51]
	v_mfma_f32_16x16x32_bf16 v[36:39], v[172:175], v[196:199], v[36:39]
	v_mfma_f32_16x16x32_bf16 v[32:35], v[180:183], v[196:199], v[32:35]
	v_mfma_f32_16x16x32_bf16 v[20:23], v[172:175], v[204:207], v[20:23]
	v_mfma_f32_16x16x32_bf16 v[16:19], v[180:183], v[204:207], v[16:19]
	v_mfma_f32_16x16x32_bf16 v[4:7], v[172:175], v[212:215], v[4:7]
	v_mfma_f32_16x16x32_bf16 v[0:3], v[180:183], v[212:215], v[0:3]
	s_setprio 0
	s_barrier
	s_add_i32 s54, s54, 2
	s_add_u32 s52, s52, 0x100
	s_addc_u32 s53, s53, 0
	s_add_u32 s20, s20, 0x100
	s_addc_u32 s21, s21, 0
	s_cmp_gt_u32 s54, 29
	s_cbranch_scc0 .LBB0_150
	s_and_b64 vcc, exec, s[8:9]
	s_cbranch_vccz .LBB0_153
	s_barrier

; #define PG8_STAGE(bufoff, gbase, voff) do { _Pragma("unroll") for (int _i = 0; _i < 2; ++_i) \
;         __builtin_amdgcn_global_load_lds((const unsigned*)((const char*)(gbase) + (voff)[_i]), (LAS unsigned*)(lds + (bufoff) + ldsw + _i * 8192), 16, 0, 0); } while (0)
; #define PG8_LDA(dst, b, h) do { _Pragma("unroll") for (int m = 0; m < 4; ++m) _Pragma("unroll") for (int k = 0; k < 2; ++k) dst[m][k] = *(const LAS bf16x8*)(lds + PG8_SA(b, h) + aoff + m * 2048 + k * 1024); } while (0)
; #define PG8_LDB(dst, b, h) do { _Pragma("unroll") for (int n = 0; n < 2; ++n) _Pragma("unroll") for (int k = 0; k < 2; ++k) dst[n][k] = *(const LAS bf16x8*)(lds + PG8_SB(b, h) + boff + n * 2048 + k * 1024); } while (0)
; #define PG8_MMA(ai, bj, At, Bt) do { __builtin_amdgcn_s_setprio(1); _Pragma("unroll") for (int m = 0; m < 4; ++m) _Pragma("unroll") for (int n = 0; n < 2; ++n) _Pragma("unroll") for (int k = 0; k < 2; ++k) \
;         acc[ai][bj][m][n] = __builtin_amdgcn_mfma_f32_16x16x32_bf16(Bt[n][k], At[m][k], acc[ai][bj][m][n], 0, 0, 0); __builtin_amdgcn_s_setprio(0); } while (0)
; #define PG8_WAIT_V(n) asm volatile("s_waitcnt vmcnt(" #n ")" ::: "memory")
; #define PG8_WAIT_L(n) asm volatile("s_waitcnt lgkmcnt(" #n ")" ::: "memory")
; #define PG8_BAR __builtin_amdgcn_s_barrier()
; #define PG8_SCHED __builtin_amdgcn_sched_barrier(0)
; template <class Epi>
; __device__ __forceinline__ void gemm_phase(ldsp lds, const Gemm g, const StaticOrder& S, const Epi& E, int wave0) {
;     ...
;         for (int t = 0; t < nt; t += 2) {
;             const bool last = (t == nt - 2);
;             const char* a1 = cA + (size_t)(t + 1) * kstep;
;             const char* a2 = last ? nA : cA + (size_t)(t + 2) * kstep; const char* b2 = last ? nB : cB + (size_t)(t + 2) * kstep;
;             const char* a3 = a2 + kstep; const char* b3 = b2 + kstep;
;             PG8_LDB(B0, 0, 0); PG8_LDB(B1, 0, 1); PG8_SCHED; PG8_LDA(At, 0, 0); PG8_STAGE(PG8_SA(1, 1), a1 + hstep, voffA);
;             PG8_WAIT_V(8); PG8_WAIT_L(0); PG8_BAR; PG8_MMA(0, 0, At, B0); PG8_MMA(0, 1, At, B1); PG8_BAR; PG8_SCHED;
;             PG8_LDA(At, 0, 1); PG8_STAGE(PG8_SB(0, 0), b2, voffB); PG8_STAGE(PG8_SB(0, 1), b2 + hstep, voffB); PG8_STAGE(PG8_SA(0, 0), a2, voffA);
;             PG8_WAIT_V(8); PG8_WAIT_L(0); PG8_BAR; PG8_MMA(1, 0, At, B0); PG8_MMA(1, 1, At, B1); PG8_BAR; PG8_SCHED;
.LBB0_222:
	s_add_u32 s36, s34, 0x100
	s_addc_u32 s37, s35, 0
	s_cmpk_eq_i32 s69, 0x54
	s_cselect_b32 s41, s5, s37
	s_cselect_b32 s40, s4, s36
	s_cselect_b32 s39, s31, s68
	s_cselect_b32 s38, s30, s67
	s_add_i32 m0, s49, 0xc000
	s_nop 0
	global_load_lds_dwordx4 v138, s[34:35]
	s_add_i32 m0, s49, 0xe000
	s_nop 0
	global_load_lds_dwordx4 v136, s[34:35]
	ds_read_b128 v[152:155], v149
	ds_read_b128 v[156:159], v149 offset:1024
	ds_read_b128 v[160:163], v149 offset:2048
	ds_read_b128 v[164:167], v149 offset:3072
	ds_read_b128 v[168:171], v150
	ds_read_b128 v[172:175], v150 offset:1024
	ds_read_b128 v[176:179], v150 offset:2048
	ds_read_b128 v[180:183], v150 offset:3072
	ds_read_b128 v[184:187], v151
	ds_read_b128 v[188:191], v151 offset:1024
	ds_read_b128 v[192:195], v151 offset:2048
	ds_read_b128 v[196:199], v151 offset:3072
	ds_read_b128 v[200:203], v151 offset:4096
	ds_read_b128 v[204:207], v151 offset:5120
	ds_read_b128 v[208:211], v151 offset:6144
	ds_read_b128 v[212:215], v151 offset:7168
	s_waitcnt vmcnt(8)
	s_waitcnt lgkmcnt(0)
	s_barrier
	s_setprio 1
	s_waitcnt lgkmcnt(0)
	v_mfma_f32_16x16x32_bf16 v[124:127], v[152:155], v[184:187], v[124:127]
	v_mfma_f32_16x16x32_bf16 v[120:123], v[160:163], v[184:187], v[120:123]
	v_mfma_f32_16x16x32_bf16 v[112:115], v[152:155], v[192:195], v[112:115]
	v_mfma_f32_16x16x32_bf16 v[104:107], v[160:163], v[192:195], v[104:107]
	v_mfma_f32_16x16x32_bf16 v[96:99], v[152:155], v[200:203], v[96:99]
	v_mfma_f32_16x16x32_bf16 v[88:91], v[160:163], v[200:203], v[88:91]
	v_mfma_f32_16x16x32_bf16 v[80:83], v[152:155], v[208:211], v[80:83]
	v_mfma_f32_16x16x32_bf16 v[72:75], v[160:163], v[208:211], v[72:75]
	v_mfma_f32_16x16x32_bf16 v[124:127], v[156:159], v[188:191], v[124:127]
	v_mfma_f32_16x16x32_bf16 v[120:123], v[164:167], v[188:191], v[120:123]
	v_mfma_f32_16x16x32_bf16 v[112:115], v[156:159], v[196:199], v[112:115]
	v_mfma_f32_16x16x32_bf16 v[104:107], v[164:167], v[196:199], v[104:107]
	v_mfma_f32_16x16x32_bf16 v[96:99], v[156:159], v[204:207], v[96:99]
	v_mfma_f32_16x16x32_bf16 v[88:91], v[164:167], v[204:207], v[88:91]
	v_mfma_f32_16x16x32_bf16 v[80:83], v[156:159], v[212:215], v[80:83]
	v_mfma_f32_16x16x32_bf16 v[72:75], v[164:167], v[212:215], v[72:75]
	s_setprio 0
	s_setprio 1
	v_mfma_f32_16x16x32_bf16 v[116:119], v[168:171], v[184:187], v[116:119]
	v_mfma_f32_16x16x32_bf16 v[108:111], v[176:179], v[184:187], v[108:111]
	v_mfma_f32_16x16x32_bf16 v[100:103], v[168:171], v[192:195], v[100:103]
	v_mfma_f32_16x16x32_bf16 v[92:95], v[176:179], v[192:195], v[92:95]
	v_mfma_f32_16x16x32_bf16 v[84:87], v[168:171], v[200:203], v[84:87]
	v_mfma_f32_16x16x32_bf16 v[76:79], v[176:179], v[200:203], v[76:79]
	v_mfma_f32_16x16x32_bf16 v[68:71], v[168:171], v[208:211], v[68:71]
	v_mfma_f32_16x16x32_bf16 v[64:67], v[176:179], v[208:211], v[64:67]
	v_mfma_f32_16x16x32_bf16 v[116:119], v[172:175], v[188:191], v[116:119]
	v_mfma_f32_16x16x32_bf16 v[108:111], v[180:183], v[188:191], v[108:111]
	v_mfma_f32_16x16x32_bf16 v[100:103], v[172:175], v[196:199], v[100:103]
	v_mfma_f32_16x16x32_bf16 v[92:95], v[180:183], v[196:199], v[92:95]
	v_mfma_f32_16x16x32_bf16 v[84:87], v[172:175], v[204:207], v[84:87]
	v_mfma_f32_16x16x32_bf16 v[76:79], v[180:183], v[204:207], v[76:79]
	v_mfma_f32_16x16x32_bf16 v[68:71], v[172:175], v[212:215], v[68:71]
	v_mfma_f32_16x16x32_bf16 v[64:67], v[180:183], v[212:215], v[64:67]
	s_setprio 0
	s_barrier
	s_add_i32 s34, s61, s48
	s_mov_b32 m0, s34
	s_nop 0
	global_load_lds_dwordx4 v130, s[38:39]
	s_add_i32 m0, s34, 0x2000
	s_add_u32 s34, s38, 0x160000
	s_addc_u32 s35, s39, 0
	s_add_i32 s70, s62, s48
	global_load_lds_dwordx4 v134, s[38:39]
	s_mov_b32 m0, s70
	s_nop 0
	global_load_lds_dwordx4 v130, s[34:35]
	s_add_i32 m0, s70, 0x2000
	s_nop 0
	global_load_lds_dwordx4 v134, s[34:35]
	s_mov_b32 m0, s49
	s_nop 0
	global_load_lds_dwordx4 v128, s[40:41]
	s_mov_b32 m0, s50
	s_nop 0
	global_load_lds_dwordx4 v132, s[40:41]
	ds_read_b128 v[184:187], v151 offset:16384
	ds_read_b128 v[188:191], v151 offset:17408
	ds_read_b128 v[192:195], v151 offset:18432
	ds_read_b128 v[196:199], v151 offset:19456
	ds_read_b128 v[200:203], v151 offset:20480
	ds_read_b128 v[204:207], v151 offset:21504
	ds_read_b128 v[208:211], v151 offset:22528
	ds_read_b128 v[212:215], v151 offset:23552
	s_waitcnt vmcnt(8)
	s_waitcnt lgkmcnt(0)
	s_barrier
	s_setprio 1
	s_waitcnt lgkmcnt(0)
	v_mfma_f32_16x16x32_bf16 v[60:63], v[152:155], v[184:187], v[60:63]
	v_mfma_f32_16x16x32_bf16 v[56:59], v[160:163], v[184:187], v[56:59]
	v_mfma_f32_16x16x32_bf16 v[48:51], v[152:155], v[192:195], v[48:51]
	v_mfma_f32_16x16x32_bf16 v[40:43], v[160:163], v[192:195], v[40:43]
	v_mfma_f32_16x16x32_bf16 v[32:35], v[152:155], v[200:203], v[32:35]
	v_mfma_f32_16x16x32_bf16 v[24:27], v[160:163], v[200:203], v[24:27]
	v_mfma_f32_16x16x32_bf16 v[16:19], v[152:155], v[208:211], v[16:19]
	v_mfma_f32_16x16x32_bf16 v[8:11], v[160:163], v[208:211], v[8:11]
	v_mfma_f32_16x16x32_bf16 v[60:63], v[156:159], v[188:191], v[60:63]
	v_mfma_f32_16x16x32_bf16 v[56:59], v[164:167], v[188:191], v[56:59]
	v_mfma_f32_16x16x32_bf16 v[48:51], v[156:159], v[196:199], v[48:51]
	v_mfma_f32_16x16x32_bf16 v[40:43], v[164:167], v[196:199], v[40:43]
	v_mfma_f32_16x16x32_bf16 v[32:35], v[156:159], v[204:207], v[32:35]
	v_mfma_f32_16x16x32_bf16 v[24:27], v[164:167], v[204:207], v[24:27]
	v_mfma_f32_16x16x32_bf16 v[16:19], v[156:159], v[212:215], v[16:19]
	v_mfma_f32_16x16x32_bf16 v[8:11], v[164:167], v[212:215], v[8:11]
	s_setprio 0
	s_setprio 1
	v_mfma_f32_16x16x32_bf16 v[52:55], v[168:171], v[184:187], v[52:55]
	v_mfma_f32_16x16x32_bf16 v[44:47], v[176:179], v[184:187], v[44:47]
	v_mfma_f32_16x16x32_bf16 v[36:39], v[168:171], v[192:195], v[36:39]
	v_mfma_f32_16x16x32_bf16 v[28:31], v[176:179], v[192:195], v[28:31]
	v_mfma_f32_16x16x32_bf16 v[20:23], v[168:171], v[200:203], v[20:23]
	v_mfma_f32_16x16x32_bf16 v[12:15], v[176:179], v[200:203], v[12:15]
	v_mfma_f32_16x16x32_bf16 v[4:7], v[168:171], v[208:211], v[4:7]
	v_mfma_f32_16x16x32_bf16 v[0:3], v[176:179], v[208:211], v[0:3]
	v_mfma_f32_16x16x32_bf16 v[52:55], v[172:175], v[188:191], v[52:55]
	v_mfma_f32_16x16x32_bf16 v[44:47], v[180:183], v[188:191], v[44:47]
	v_mfma_f32_16x16x32_bf16 v[36:39], v[172:175], v[196:199], v[36:39]
	v_mfma_f32_16x16x32_bf16 v[28:31], v[180:183], v[196:199], v[28:31]
	v_mfma_f32_16x16x32_bf16 v[20:23], v[172:175], v[204:207], v[20:23]
	v_mfma_f32_16x16x32_bf16 v[12:15], v[180:183], v[204:207], v[12:15]
	v_mfma_f32_16x16x32_bf16 v[4:7], v[172:175], v[212:215], v[4:7]
	v_mfma_f32_16x16x32_bf16 v[0:3], v[180:183], v[212:215], v[0:3]
	s_setprio 0
	s_barrier
; #define PG8_STAGE(bufoff, gbase, voff) do { _Pragma("unroll") for (int _i = 0; _i < 2; ++_i) \
;         __builtin_amdgcn_global_load_lds((const unsigned*)((const char*)(gbase) + (voff)[_i]), (LAS unsigned*)(lds + (bufoff) + ldsw + _i * 8192), 16, 0, 0); } while (0)
; #define PG8_LDA(dst, b, h) do { _Pragma("unroll") for (int m = 0; m < 4; ++m) _Pragma("unroll") for (int k = 0; k < 2; ++k) dst[m][k] = *(const LAS bf16x8*)(lds + PG8_SA(b, h) + aoff + m * 2048 + k * 1024); } while (0)
; #define PG8_LDB(dst, b, h) do { _Pragma("unroll") for (int n = 0; n < 2; ++n) _Pragma("unroll") for (int k = 0; k < 2; ++k) dst[n][k] = *(const LAS bf16x8*)(lds + PG8_SB(b, h) + boff + n * 2048 + k * 1024); } while (0)
; #define PG8_MMA(ai, bj, At, Bt) do { __builtin_amdgcn_s_setprio(1); _Pragma("unroll") for (int m = 0; m < 4; ++m) _Pragma("unroll") for (int n = 0; n < 2; ++n) _Pragma("unroll") for (int k = 0; k < 2; ++k) \
;         acc[ai][bj][m][n] = __builtin_amdgcn_mfma_f32_16x16x32_bf16(Bt[n][k], At[m][k], acc[ai][bj][m][n], 0, 0, 0); __builtin_amdgcn_s_setprio(0); } while (0)
; #define PG8_WAIT_V(n) asm volatile("s_waitcnt vmcnt(" #n ")" ::: "memory")
; #define PG8_WAIT_L(n) asm volatile("s_waitcnt lgkmcnt(" #n ")" ::: "memory")
; #define PG8_BAR __builtin_amdgcn_s_barrier()
; #define PG8_SCHED __builtin_amdgcn_sched_barrier(0)
; template <class Epi>
; __device__ __forceinline__ void gemm_phase(ldsp lds, const Gemm g, const StaticOrder& S, const Epi& E, int wave0) {
;     ...
;             PG8_LDB(B0, 1, 0); PG8_LDB(B1, 1, 1); PG8_SCHED; PG8_LDA(At, 1, 0); PG8_STAGE(PG8_SA(0, 1), a2 + hstep, voffA);
;             PG8_WAIT_V(8); PG8_WAIT_L(0); PG8_BAR; PG8_MMA(0, 0, At, B0); PG8_MMA(0, 1, At, B1); PG8_BAR; PG8_SCHED;
;             PG8_LDA(At, 1, 1); PG8_STAGE(PG8_SB(1, 0), b3, voffB); PG8_STAGE(PG8_SB(1, 1), b3 + hstep, voffB); PG8_STAGE(PG8_SA(1, 0), a3, voffA);
;             PG8_WAIT_V(8); PG8_WAIT_L(0); PG8_BAR; PG8_MMA(1, 0, At, B0); PG8_MMA(1, 1, At, B1); PG8_BAR; PG8_SCHED;
;         }
;         if (wr == 0) PG8_BAR;
	s_add_i32 s70, 0, 0x18000
	s_add_i32 s71, 0, 0x1c000
	v_add_u32_e32 v164, s70, v148
	v_add_u32_e32 v180, s71, v148
	s_add_u32 s34, s40, 0x160000
	s_addc_u32 s35, s41, 0
	s_mov_b32 m0, s51
	s_nop 0
	global_load_lds_dwordx4 v128, s[34:35]
	s_mov_b32 m0, s52
	s_nop 0
	global_load_lds_dwordx4 v132, s[34:35]
	ds_read_b128 v[152:155], v164
	ds_read_b128 v[156:159], v164 offset:1024
	ds_read_b128 v[160:163], v164 offset:2048
	ds_read_b128 v[164:167], v164 offset:3072
	ds_read_b128 v[168:171], v180
	ds_read_b128 v[172:175], v180 offset:1024
	ds_read_b128 v[176:179], v180 offset:2048
	ds_read_b128 v[180:183], v180 offset:3072
	ds_read_b128 v[184:187], v151 offset:32768
	ds_read_b128 v[188:191], v151 offset:33792
	ds_read_b128 v[192:195], v151 offset:34816
	ds_read_b128 v[196:199], v151 offset:35840
	ds_read_b128 v[200:203], v151 offset:36864
	ds_read_b128 v[204:207], v151 offset:37888
	ds_read_b128 v[208:211], v151 offset:38912
	ds_read_b128 v[212:215], v151 offset:39936
	s_waitcnt vmcnt(8)
	s_waitcnt lgkmcnt(0)
	s_barrier
	s_setprio 1
	s_waitcnt lgkmcnt(0)
	v_mfma_f32_16x16x32_bf16 v[124:127], v[152:155], v[184:187], v[124:127]
	v_mfma_f32_16x16x32_bf16 v[120:123], v[160:163], v[184:187], v[120:123]
	v_mfma_f32_16x16x32_bf16 v[112:115], v[152:155], v[192:195], v[112:115]
	v_mfma_f32_16x16x32_bf16 v[104:107], v[160:163], v[192:195], v[104:107]
	v_mfma_f32_16x16x32_bf16 v[96:99], v[152:155], v[200:203], v[96:99]
	v_mfma_f32_16x16x32_bf16 v[88:91], v[160:163], v[200:203], v[88:91]
	v_mfma_f32_16x16x32_bf16 v[80:83], v[152:155], v[208:211], v[80:83]
	v_mfma_f32_16x16x32_bf16 v[72:75], v[160:163], v[208:211], v[72:75]
	v_mfma_f32_16x16x32_bf16 v[124:127], v[156:159], v[188:191], v[124:127]
	v_mfma_f32_16x16x32_bf16 v[120:123], v[164:167], v[188:191], v[120:123]
	v_mfma_f32_16x16x32_bf16 v[112:115], v[156:159], v[196:199], v[112:115]
	v_mfma_f32_16x16x32_bf16 v[104:107], v[164:167], v[196:199], v[104:107]
	v_mfma_f32_16x16x32_bf16 v[96:99], v[156:159], v[204:207], v[96:99]
	v_mfma_f32_16x16x32_bf16 v[88:91], v[164:167], v[204:207], v[88:91]
	v_mfma_f32_16x16x32_bf16 v[80:83], v[156:159], v[212:215], v[80:83]
	v_mfma_f32_16x16x32_bf16 v[72:75], v[164:167], v[212:215], v[72:75]
	s_setprio 0
	s_setprio 1
	v_mfma_f32_16x16x32_bf16 v[116:119], v[168:171], v[184:187], v[116:119]
	v_mfma_f32_16x16x32_bf16 v[108:111], v[176:179], v[184:187], v[108:111]
	v_mfma_f32_16x16x32_bf16 v[100:103], v[168:171], v[192:195], v[100:103]
	v_mfma_f32_16x16x32_bf16 v[92:95], v[176:179], v[192:195], v[92:95]
	v_mfma_f32_16x16x32_bf16 v[84:87], v[168:171], v[200:203], v[84:87]
	v_mfma_f32_16x16x32_bf16 v[76:79], v[176:179], v[200:203], v[76:79]
	v_mfma_f32_16x16x32_bf16 v[68:71], v[168:171], v[208:211], v[68:71]
	v_mfma_f32_16x16x32_bf16 v[64:67], v[176:179], v[208:211], v[64:67]
	v_mfma_f32_16x16x32_bf16 v[116:119], v[172:175], v[188:191], v[116:119]
	v_mfma_f32_16x16x32_bf16 v[108:111], v[180:183], v[188:191], v[108:111]
	v_mfma_f32_16x16x32_bf16 v[100:103], v[172:175], v[196:199], v[100:103]
	v_mfma_f32_16x16x32_bf16 v[92:95], v[180:183], v[196:199], v[92:95]
	v_mfma_f32_16x16x32_bf16 v[84:87], v[172:175], v[204:207], v[84:87]
	v_mfma_f32_16x16x32_bf16 v[76:79], v[180:183], v[204:207], v[76:79]
	v_mfma_f32_16x16x32_bf16 v[68:71], v[172:175], v[212:215], v[68:71]
	v_mfma_f32_16x16x32_bf16 v[64:67], v[180:183], v[212:215], v[64:67]
	s_setprio 0
	s_barrier
	s_add_i32 s34, s70, s48
	s_add_u32 s100, s38, 0x80
	s_addc_u32 s101, s39, 0
	s_add_u32 s98, s40, 0x80
	s_addc_u32 s99, s41, 0
	s_mov_b32 m0, s34
	s_nop 0
	global_load_lds_dwordx4 v130, s[100:101]
	s_add_i32 m0, s34, 0x2000
	s_add_u32 s34, s38, 0x160080
	s_addc_u32 s35, s39, 0
	s_add_i32 s38, s71, s48
	global_load_lds_dwordx4 v134, s[100:101]
	s_mov_b32 m0, s38
	s_nop 0
	global_load_lds_dwordx4 v130, s[34:35]
	s_add_i32 m0, s38, 0x2000
	s_nop 0
	global_load_lds_dwordx4 v134, s[34:35]
	s_mov_b32 m0, s56
	s_nop 0
	global_load_lds_dwordx4 v128, s[98:99]
	s_mov_b32 m0, s57
	s_nop 0
	global_load_lds_dwordx4 v132, s[98:99]
	ds_read_b128 v[184:187], v151 offset:49152
	ds_read_b128 v[188:191], v151 offset:50176
	ds_read_b128 v[192:195], v151 offset:51200
	ds_read_b128 v[196:199], v151 offset:52224
	ds_read_b128 v[200:203], v151 offset:53248
	ds_read_b128 v[204:207], v151 offset:54272
	ds_read_b128 v[208:211], v151 offset:55296
	ds_read_b128 v[212:215], v151 offset:56320
	s_waitcnt vmcnt(8)
	s_waitcnt lgkmcnt(0)
	s_barrier
	s_setprio 1
	s_waitcnt lgkmcnt(0)
	v_mfma_f32_16x16x32_bf16 v[60:63], v[152:155], v[184:187], v[60:63]
	v_mfma_f32_16x16x32_bf16 v[56:59], v[160:163], v[184:187], v[56:59]
	v_mfma_f32_16x16x32_bf16 v[48:51], v[152:155], v[192:195], v[48:51]
	v_mfma_f32_16x16x32_bf16 v[40:43], v[160:163], v[192:195], v[40:43]
	v_mfma_f32_16x16x32_bf16 v[32:35], v[152:155], v[200:203], v[32:35]
	v_mfma_f32_16x16x32_bf16 v[24:27], v[160:163], v[200:203], v[24:27]
	v_mfma_f32_16x16x32_bf16 v[16:19], v[152:155], v[208:211], v[16:19]
	v_mfma_f32_16x16x32_bf16 v[8:11], v[160:163], v[208:211], v[8:11]
	v_mfma_f32_16x16x32_bf16 v[60:63], v[156:159], v[188:191], v[60:63]
	v_mfma_f32_16x16x32_bf16 v[56:59], v[164:167], v[188:191], v[56:59]
	v_mfma_f32_16x16x32_bf16 v[48:51], v[156:159], v[196:199], v[48:51]
	v_mfma_f32_16x16x32_bf16 v[40:43], v[164:167], v[196:199], v[40:43]
	v_mfma_f32_16x16x32_bf16 v[32:35], v[156:159], v[204:207], v[32:35]
	v_mfma_f32_16x16x32_bf16 v[24:27], v[164:167], v[204:207], v[24:27]
	v_mfma_f32_16x16x32_bf16 v[16:19], v[156:159], v[212:215], v[16:19]
	v_mfma_f32_16x16x32_bf16 v[8:11], v[164:167], v[212:215], v[8:11]
	s_setprio 0
	s_setprio 1
	v_mfma_f32_16x16x32_bf16 v[52:55], v[168:171], v[184:187], v[52:55]
	v_mfma_f32_16x16x32_bf16 v[44:47], v[176:179], v[184:187], v[44:47]
	v_mfma_f32_16x16x32_bf16 v[36:39], v[168:171], v[192:195], v[36:39]
	v_mfma_f32_16x16x32_bf16 v[28:31], v[176:179], v[192:195], v[28:31]
	v_mfma_f32_16x16x32_bf16 v[20:23], v[168:171], v[200:203], v[20:23]
	v_mfma_f32_16x16x32_bf16 v[12:15], v[176:179], v[200:203], v[12:15]
	v_mfma_f32_16x16x32_bf16 v[4:7], v[168:171], v[208:211], v[4:7]
	v_mfma_f32_16x16x32_bf16 v[0:3], v[176:179], v[208:211], v[0:3]
	v_mfma_f32_16x16x32_bf16 v[52:55], v[172:175], v[188:191], v[52:55]
	v_mfma_f32_16x16x32_bf16 v[44:47], v[180:183], v[188:191], v[44:47]
	v_mfma_f32_16x16x32_bf16 v[36:39], v[172:175], v[196:199], v[36:39]
	v_mfma_f32_16x16x32_bf16 v[28:31], v[180:183], v[196:199], v[28:31]
	v_mfma_f32_16x16x32_bf16 v[20:23], v[172:175], v[204:207], v[20:23]
	v_mfma_f32_16x16x32_bf16 v[12:15], v[180:183], v[204:207], v[12:15]
	v_mfma_f32_16x16x32_bf16 v[4:7], v[172:175], v[212:215], v[4:7]
	v_mfma_f32_16x16x32_bf16 v[0:3], v[180:183], v[212:215], v[0:3]
	s_setprio 0
	s_barrier
	s_add_i32 s69, s69, 2
	s_add_u32 s67, s67, 0x100
	s_addc_u32 s68, s68, 0
	s_cmpk_gt_u32 s69, 0x55
	s_mov_b64 s[34:35], s[36:37]
	s_cbranch_scc0 .LBB0_222
	s_and_b64 vcc, exec, s[14:15]
	s_cbranch_vccz .LBB0_225
	s_barrier

; #define PG8_STAGE(bufoff, gbase, voff) do { _Pragma("unroll") for (int _i = 0; _i < 2; ++_i) \
;         __builtin_amdgcn_global_load_lds((const unsigned*)((const char*)(gbase) + (voff)[_i]), (LAS unsigned*)(lds + (bufoff) + ldsw + _i * 8192), 16, 0, 0); } while (0)
; #define PG8_LDA(dst, b, h) do { _Pragma("unroll") for (int m = 0; m < 4; ++m) _Pragma("unroll") for (int k = 0; k < 2; ++k) dst[m][k] = *(const LAS bf16x8*)(lds + PG8_SA(b, h) + aoff + m * 2048 + k * 1024); } while (0)
; #define PG8_LDB(dst, b, h) do { _Pragma("unroll") for (int n = 0; n < 2; ++n) _Pragma("unroll") for (int k = 0; k < 2; ++k) dst[n][k] = *(const LAS bf16x8*)(lds + PG8_SB(b, h) + boff + n * 2048 + k * 1024); } while (0)
; #define PG8_MMA(ai, bj, At, Bt) do { __builtin_amdgcn_s_setprio(1); _Pragma("unroll") for (int m = 0; m < 4; ++m) _Pragma("unroll") for (int n = 0; n < 2; ++n) _Pragma("unroll") for (int k = 0; k < 2; ++k) \
;         acc[ai][bj][m][n] = __builtin_amdgcn_mfma_f32_16x16x32_bf16(Bt[n][k], At[m][k], acc[ai][bj][m][n], 0, 0, 0); __builtin_amdgcn_s_setprio(0); } while (0)
; #define PG8_WAIT_V(n) asm volatile("s_waitcnt vmcnt(" #n ")" ::: "memory")
; #define PG8_WAIT_L(n) asm volatile("s_waitcnt lgkmcnt(" #n ")" ::: "memory")
; #define PG8_BAR __builtin_amdgcn_s_barrier()
; #define PG8_SCHED __builtin_amdgcn_sched_barrier(0)
; template <class Epi>
; __device__ __forceinline__ void gemm_phase(ldsp lds, const Gemm g, const StaticOrder& S, const Epi& E, int wave0) {
;     ...
;         for (int t = 0; t < nt; t += 2) {
;             const bool last = (t == nt - 2);
;             const char* a1 = cA + (size_t)(t + 1) * kstep;
;             const char* a2 = last ? nA : cA + (size_t)(t + 2) * kstep; const char* b2 = last ? nB : cB + (size_t)(t + 2) * kstep;
;             const char* a3 = a2 + kstep; const char* b3 = b2 + kstep;
;             PG8_LDB(B0, 0, 0); PG8_LDB(B1, 0, 1); PG8_SCHED; PG8_LDA(At, 0, 0); PG8_STAGE(PG8_SA(1, 1), a1 + hstep, voffA);
;             PG8_WAIT_V(8); PG8_WAIT_L(0); PG8_BAR; PG8_MMA(0, 0, At, B0); PG8_MMA(0, 1, At, B1); PG8_BAR; PG8_SCHED;
;             PG8_LDA(At, 0, 1); PG8_STAGE(PG8_SB(0, 0), b2, voffB); PG8_STAGE(PG8_SB(0, 1), b2 + hstep, voffB); PG8_STAGE(PG8_SA(0, 0), a2, voffA);
;             PG8_WAIT_V(8); PG8_WAIT_L(0); PG8_BAR; PG8_MMA(1, 0, At, B0); PG8_MMA(1, 1, At, B1); PG8_BAR; PG8_SCHED;
.LBB0_332:
	s_add_u32 s48, s46, 0xfff80080
	s_addc_u32 s49, s47, -1
	s_cmp_eq_u32 s89, 28
	s_cselect_b32 s51, s37, s49
	s_cselect_b32 s50, s45, s48
	s_cselect_b32 s49, s35, s88
	s_cselect_b32 s48, s52, s53
	s_add_i32 m0, s43, 0xc000
	s_nop 0
	global_load_lds_dwordx4 v154, s[46:47]
	s_add_i32 m0, s43, 0xe000
	s_nop 0
	global_load_lds_dwordx4 v152, s[46:47]
	ds_read_b128 v[128:131], v171
	ds_read_b128 v[132:135], v171 offset:1024
	ds_read_b128 v[136:139], v171 offset:2048
	ds_read_b128 v[140:143], v171 offset:3072
	ds_read_b128 v[160:163], v172
	ds_read_b128 v[164:167], v172 offset:1024
	ds_read_b128 v[176:179], v172 offset:2048
	ds_read_b128 v[180:183], v172 offset:3072
	ds_read_b128 v[184:187], v173
	ds_read_b128 v[188:191], v173 offset:1024
	ds_read_b128 v[192:195], v173 offset:2048
	ds_read_b128 v[196:199], v173 offset:3072
	ds_read_b128 v[200:203], v173 offset:4096
	ds_read_b128 v[204:207], v173 offset:5120
	ds_read_b128 v[208:211], v173 offset:6144
	ds_read_b128 v[212:215], v173 offset:7168
	s_waitcnt vmcnt(8)
	s_waitcnt lgkmcnt(0)
	s_barrier
	s_setprio 1
	s_waitcnt lgkmcnt(0)
	v_mfma_f32_16x16x32_bf16 v[124:127], v[128:131], v[184:187], v[124:127]
	v_mfma_f32_16x16x32_bf16 v[120:123], v[136:139], v[184:187], v[120:123]
	v_mfma_f32_16x16x32_bf16 v[108:111], v[128:131], v[192:195], v[108:111]
	v_mfma_f32_16x16x32_bf16 v[104:107], v[136:139], v[192:195], v[104:107]
	v_mfma_f32_16x16x32_bf16 v[92:95], v[128:131], v[200:203], v[92:95]
	v_mfma_f32_16x16x32_bf16 v[88:91], v[136:139], v[200:203], v[88:91]
	v_mfma_f32_16x16x32_bf16 v[76:79], v[128:131], v[208:211], v[76:79]
	v_mfma_f32_16x16x32_bf16 v[72:75], v[136:139], v[208:211], v[72:75]
	v_mfma_f32_16x16x32_bf16 v[124:127], v[132:135], v[188:191], v[124:127]
	v_mfma_f32_16x16x32_bf16 v[120:123], v[140:143], v[188:191], v[120:123]
	v_mfma_f32_16x16x32_bf16 v[108:111], v[132:135], v[196:199], v[108:111]
	v_mfma_f32_16x16x32_bf16 v[104:107], v[140:143], v[196:199], v[104:107]
	v_mfma_f32_16x16x32_bf16 v[92:95], v[132:135], v[204:207], v[92:95]
	v_mfma_f32_16x16x32_bf16 v[88:91], v[140:143], v[204:207], v[88:91]
	v_mfma_f32_16x16x32_bf16 v[76:79], v[132:135], v[212:215], v[76:79]
	v_mfma_f32_16x16x32_bf16 v[72:75], v[140:143], v[212:215], v[72:75]
	s_setprio 0
	s_setprio 1
	v_mfma_f32_16x16x32_bf16 v[116:119], v[160:163], v[184:187], v[116:119]
	v_mfma_f32_16x16x32_bf16 v[112:115], v[176:179], v[184:187], v[112:115]
	v_mfma_f32_16x16x32_bf16 v[100:103], v[160:163], v[192:195], v[100:103]
	v_mfma_f32_16x16x32_bf16 v[96:99], v[176:179], v[192:195], v[96:99]
	v_mfma_f32_16x16x32_bf16 v[84:87], v[160:163], v[200:203], v[84:87]
	v_mfma_f32_16x16x32_bf16 v[80:83], v[176:179], v[200:203], v[80:83]
	v_mfma_f32_16x16x32_bf16 v[68:71], v[160:163], v[208:211], v[68:71]
	v_mfma_f32_16x16x32_bf16 v[64:67], v[176:179], v[208:211], v[64:67]
	v_mfma_f32_16x16x32_bf16 v[116:119], v[164:167], v[188:191], v[116:119]
	v_mfma_f32_16x16x32_bf16 v[112:115], v[180:183], v[188:191], v[112:115]
	v_mfma_f32_16x16x32_bf16 v[100:103], v[164:167], v[196:199], v[100:103]
	v_mfma_f32_16x16x32_bf16 v[96:99], v[180:183], v[196:199], v[96:99]
	v_mfma_f32_16x16x32_bf16 v[84:87], v[164:167], v[204:207], v[84:87]
	v_mfma_f32_16x16x32_bf16 v[80:83], v[180:183], v[204:207], v[80:83]
	v_mfma_f32_16x16x32_bf16 v[68:71], v[164:167], v[212:215], v[68:71]
	v_mfma_f32_16x16x32_bf16 v[64:67], v[180:183], v[212:215], v[64:67]
	s_setprio 0
	s_barrier
	s_add_i32 s90, s79, s62
	s_add_u32 s100, s50, 0x80
	s_addc_u32 s101, s51, 0
	s_mov_b32 m0, s90
	s_nop 0
	global_load_lds_dwordx4 v146, s[48:49]
	s_add_i32 m0, s90, 0x2000
	s_add_u32 s90, s48, 0x80000
	s_addc_u32 s91, s49, 0
	s_add_i32 s92, s80, s62
	global_load_lds_dwordx4 v150, s[48:49]
	s_mov_b32 m0, s92
	s_nop 0
	global_load_lds_dwordx4 v146, s[90:91]
	s_add_i32 m0, s92, 0x2000
	s_nop 0
	global_load_lds_dwordx4 v150, s[90:91]
	s_mov_b32 m0, s43
	s_nop 0
	global_load_lds_dwordx4 v144, s[50:51]
	s_mov_b32 m0, s63
	s_nop 0
	global_load_lds_dwordx4 v148, s[50:51]
	ds_read_b128 v[184:187], v173 offset:16384
	ds_read_b128 v[188:191], v173 offset:17408
	ds_read_b128 v[192:195], v173 offset:18432
	ds_read_b128 v[196:199], v173 offset:19456
	ds_read_b128 v[200:203], v173 offset:20480
	ds_read_b128 v[204:207], v173 offset:21504
	ds_read_b128 v[208:211], v173 offset:22528
	ds_read_b128 v[212:215], v173 offset:23552
	s_waitcnt vmcnt(8)
	s_waitcnt lgkmcnt(0)
	s_barrier
	s_setprio 1
	s_waitcnt lgkmcnt(0)
	v_mfma_f32_16x16x32_bf16 v[60:63], v[128:131], v[184:187], v[60:63]
	v_mfma_f32_16x16x32_bf16 v[56:59], v[136:139], v[184:187], v[56:59]
	v_mfma_f32_16x16x32_bf16 v[44:47], v[128:131], v[192:195], v[44:47]
	v_mfma_f32_16x16x32_bf16 v[40:43], v[136:139], v[192:195], v[40:43]
	v_mfma_f32_16x16x32_bf16 v[28:31], v[128:131], v[200:203], v[28:31]
	v_mfma_f32_16x16x32_bf16 v[24:27], v[136:139], v[200:203], v[24:27]
	v_mfma_f32_16x16x32_bf16 v[12:15], v[128:131], v[208:211], v[12:15]
	v_mfma_f32_16x16x32_bf16 v[8:11], v[136:139], v[208:211], v[8:11]
	v_mfma_f32_16x16x32_bf16 v[60:63], v[132:135], v[188:191], v[60:63]
	v_mfma_f32_16x16x32_bf16 v[56:59], v[140:143], v[188:191], v[56:59]
	v_mfma_f32_16x16x32_bf16 v[44:47], v[132:135], v[196:199], v[44:47]
	v_mfma_f32_16x16x32_bf16 v[40:43], v[140:143], v[196:199], v[40:43]
	v_mfma_f32_16x16x32_bf16 v[28:31], v[132:135], v[204:207], v[28:31]
	v_mfma_f32_16x16x32_bf16 v[24:27], v[140:143], v[204:207], v[24:27]
	v_mfma_f32_16x16x32_bf16 v[12:15], v[132:135], v[212:215], v[12:15]
	v_mfma_f32_16x16x32_bf16 v[8:11], v[140:143], v[212:215], v[8:11]
	s_setprio 0
	s_setprio 1
	v_mfma_f32_16x16x32_bf16 v[52:55], v[160:163], v[184:187], v[52:55]
	v_mfma_f32_16x16x32_bf16 v[48:51], v[176:179], v[184:187], v[48:51]
	v_mfma_f32_16x16x32_bf16 v[36:39], v[160:163], v[192:195], v[36:39]
	v_mfma_f32_16x16x32_bf16 v[32:35], v[176:179], v[192:195], v[32:35]
	v_mfma_f32_16x16x32_bf16 v[20:23], v[160:163], v[200:203], v[20:23]
	v_mfma_f32_16x16x32_bf16 v[16:19], v[176:179], v[200:203], v[16:19]
	v_mfma_f32_16x16x32_bf16 v[4:7], v[160:163], v[208:211], v[4:7]
	v_mfma_f32_16x16x32_bf16 v[0:3], v[176:179], v[208:211], v[0:3]
	v_mfma_f32_16x16x32_bf16 v[52:55], v[164:167], v[188:191], v[52:55]
	v_mfma_f32_16x16x32_bf16 v[48:51], v[180:183], v[188:191], v[48:51]
	v_mfma_f32_16x16x32_bf16 v[36:39], v[164:167], v[196:199], v[36:39]
	v_mfma_f32_16x16x32_bf16 v[32:35], v[180:183], v[196:199], v[32:35]
	v_mfma_f32_16x16x32_bf16 v[20:23], v[164:167], v[204:207], v[20:23]
	v_mfma_f32_16x16x32_bf16 v[16:19], v[180:183], v[204:207], v[16:19]
	v_mfma_f32_16x16x32_bf16 v[4:7], v[164:167], v[212:215], v[4:7]
	v_mfma_f32_16x16x32_bf16 v[0:3], v[180:183], v[212:215], v[0:3]
	s_setprio 0
	s_barrier
; #define PG8_STAGE(bufoff, gbase, voff) do { _Pragma("unroll") for (int _i = 0; _i < 2; ++_i) \
;         __builtin_amdgcn_global_load_lds((const unsigned*)((const char*)(gbase) + (voff)[_i]), (LAS unsigned*)(lds + (bufoff) + ldsw + _i * 8192), 16, 0, 0); } while (0)
; #define PG8_LDA(dst, b, h) do { _Pragma("unroll") for (int m = 0; m < 4; ++m) _Pragma("unroll") for (int k = 0; k < 2; ++k) dst[m][k] = *(const LAS bf16x8*)(lds + PG8_SA(b, h) + aoff + m * 2048 + k * 1024); } while (0)
; #define PG8_LDB(dst, b, h) do { _Pragma("unroll") for (int n = 0; n < 2; ++n) _Pragma("unroll") for (int k = 0; k < 2; ++k) dst[n][k] = *(const LAS bf16x8*)(lds + PG8_SB(b, h) + boff + n * 2048 + k * 1024); } while (0)
; #define PG8_MMA(ai, bj, At, Bt) do { __builtin_amdgcn_s_setprio(1); _Pragma("unroll") for (int m = 0; m < 4; ++m) _Pragma("unroll") for (int n = 0; n < 2; ++n) _Pragma("unroll") for (int k = 0; k < 2; ++k) \
;         acc[ai][bj][m][n] = __builtin_amdgcn_mfma_f32_16x16x32_bf16(Bt[n][k], At[m][k], acc[ai][bj][m][n], 0, 0, 0); __builtin_amdgcn_s_setprio(0); } while (0)
; #define PG8_WAIT_V(n) asm volatile("s_waitcnt vmcnt(" #n ")" ::: "memory")
; #define PG8_WAIT_L(n) asm volatile("s_waitcnt lgkmcnt(" #n ")" ::: "memory")
; #define PG8_BAR __builtin_amdgcn_s_barrier()
; #define PG8_SCHED __builtin_amdgcn_sched_barrier(0)
; template <class Epi>
; __device__ __forceinline__ void gemm_phase(ldsp lds, const Gemm g, const StaticOrder& S, const Epi& E, int wave0) {
;     ...
;             PG8_LDB(B0, 1, 0); PG8_LDB(B1, 1, 1); PG8_SCHED; PG8_LDA(At, 1, 0); PG8_STAGE(PG8_SA(0, 1), a2 + hstep, voffA);
;             PG8_WAIT_V(8); PG8_WAIT_L(0); PG8_BAR; PG8_MMA(0, 0, At, B0); PG8_MMA(0, 1, At, B1); PG8_BAR; PG8_SCHED;
;             PG8_LDA(At, 1, 1); PG8_STAGE(PG8_SB(1, 0), b3, voffB); PG8_STAGE(PG8_SB(1, 1), b3 + hstep, voffB); PG8_STAGE(PG8_SA(1, 0), a3, voffA);
;             PG8_WAIT_V(8); PG8_WAIT_L(0); PG8_BAR; PG8_MMA(1, 0, At, B0); PG8_MMA(1, 1, At, B1); PG8_BAR; PG8_SCHED;
;         }
;         if (wr == 0) PG8_BAR;
	s_add_i32 s90, 0, 0x18000
	s_add_i32 s91, 0, 0x1c000
	v_add_u32_e32 v140, s90, v170
	v_add_u32_e32 v175, s91, v170
	s_add_u32 s50, s50, 0x80000
	s_addc_u32 s51, s51, 0
	s_mov_b32 m0, s64
	s_nop 0
	global_load_lds_dwordx4 v144, s[50:51]
	s_mov_b32 m0, s65
	s_nop 0
	global_load_lds_dwordx4 v148, s[50:51]
	ds_read_b128 v[128:131], v140
	ds_read_b128 v[132:135], v140 offset:1024
	ds_read_b128 v[136:139], v140 offset:2048
	ds_read_b128 v[140:143], v140 offset:3072
	ds_read_b128 v[160:163], v175
	ds_read_b128 v[164:167], v175 offset:1024
	ds_read_b128 v[176:179], v175 offset:2048
	ds_read_b128 v[180:183], v175 offset:3072
	ds_read_b128 v[184:187], v173 offset:32768
	ds_read_b128 v[188:191], v173 offset:33792
	ds_read_b128 v[192:195], v173 offset:34816
	ds_read_b128 v[196:199], v173 offset:35840
	ds_read_b128 v[200:203], v173 offset:36864
	ds_read_b128 v[204:207], v173 offset:37888
	ds_read_b128 v[208:211], v173 offset:38912
	ds_read_b128 v[212:215], v173 offset:39936
	s_waitcnt vmcnt(8)
	s_waitcnt lgkmcnt(0)
	s_barrier
	s_setprio 1
	s_waitcnt lgkmcnt(0)
	v_mfma_f32_16x16x32_bf16 v[124:127], v[128:131], v[184:187], v[124:127]
	v_mfma_f32_16x16x32_bf16 v[120:123], v[136:139], v[184:187], v[120:123]
	v_mfma_f32_16x16x32_bf16 v[108:111], v[128:131], v[192:195], v[108:111]
	v_mfma_f32_16x16x32_bf16 v[104:107], v[136:139], v[192:195], v[104:107]
	v_mfma_f32_16x16x32_bf16 v[92:95], v[128:131], v[200:203], v[92:95]
	v_mfma_f32_16x16x32_bf16 v[88:91], v[136:139], v[200:203], v[88:91]
	v_mfma_f32_16x16x32_bf16 v[76:79], v[128:131], v[208:211], v[76:79]
	v_mfma_f32_16x16x32_bf16 v[72:75], v[136:139], v[208:211], v[72:75]
	v_mfma_f32_16x16x32_bf16 v[124:127], v[132:135], v[188:191], v[124:127]
	v_mfma_f32_16x16x32_bf16 v[120:123], v[140:143], v[188:191], v[120:123]
	v_mfma_f32_16x16x32_bf16 v[108:111], v[132:135], v[196:199], v[108:111]
	v_mfma_f32_16x16x32_bf16 v[104:107], v[140:143], v[196:199], v[104:107]
	v_mfma_f32_16x16x32_bf16 v[92:95], v[132:135], v[204:207], v[92:95]
	v_mfma_f32_16x16x32_bf16 v[88:91], v[140:143], v[204:207], v[88:91]
	v_mfma_f32_16x16x32_bf16 v[76:79], v[132:135], v[212:215], v[76:79]
	v_mfma_f32_16x16x32_bf16 v[72:75], v[140:143], v[212:215], v[72:75]
	s_setprio 0
	s_setprio 1
	v_mfma_f32_16x16x32_bf16 v[116:119], v[160:163], v[184:187], v[116:119]
	v_mfma_f32_16x16x32_bf16 v[112:115], v[176:179], v[184:187], v[112:115]
	v_mfma_f32_16x16x32_bf16 v[100:103], v[160:163], v[192:195], v[100:103]
	v_mfma_f32_16x16x32_bf16 v[96:99], v[176:179], v[192:195], v[96:99]
	v_mfma_f32_16x16x32_bf16 v[84:87], v[160:163], v[200:203], v[84:87]
	v_mfma_f32_16x16x32_bf16 v[80:83], v[176:179], v[200:203], v[80:83]
	v_mfma_f32_16x16x32_bf16 v[68:71], v[160:163], v[208:211], v[68:71]
	v_mfma_f32_16x16x32_bf16 v[64:67], v[176:179], v[208:211], v[64:67]
	v_mfma_f32_16x16x32_bf16 v[116:119], v[164:167], v[188:191], v[116:119]
	v_mfma_f32_16x16x32_bf16 v[112:115], v[180:183], v[188:191], v[112:115]
	v_mfma_f32_16x16x32_bf16 v[100:103], v[164:167], v[196:199], v[100:103]
	v_mfma_f32_16x16x32_bf16 v[96:99], v[180:183], v[196:199], v[96:99]
	v_mfma_f32_16x16x32_bf16 v[84:87], v[164:167], v[204:207], v[84:87]
	v_mfma_f32_16x16x32_bf16 v[80:83], v[180:183], v[204:207], v[80:83]
	v_mfma_f32_16x16x32_bf16 v[68:71], v[164:167], v[212:215], v[68:71]
	v_mfma_f32_16x16x32_bf16 v[64:67], v[180:183], v[212:215], v[64:67]
	s_setprio 0
	s_barrier
	s_add_i32 s50, s90, s62
	s_add_u32 s48, s48, 0x80
	s_addc_u32 s49, s49, 0
	s_mov_b32 m0, s50
	s_nop 0
	global_load_lds_dwordx4 v146, s[48:49]
	s_add_i32 m0, s50, 0x2000
	s_add_i32 s50, s91, s62
	global_load_lds_dwordx4 v150, s[48:49]
	s_add_u32 s48, s48, 0x80000
	s_addc_u32 s49, s49, 0
	s_mov_b32 m0, s50
	s_nop 0
	global_load_lds_dwordx4 v146, s[48:49]
	s_add_i32 m0, s50, 0x2000
	s_nop 0
	global_load_lds_dwordx4 v150, s[48:49]
	s_mov_b32 m0, s70
	s_nop 0
	global_load_lds_dwordx4 v144, s[100:101]
	s_mov_b32 m0, s71
	s_nop 0
	global_load_lds_dwordx4 v148, s[100:101]
	ds_read_b128 v[184:187], v173 offset:49152
	ds_read_b128 v[188:191], v173 offset:50176
	ds_read_b128 v[192:195], v173 offset:51200
	ds_read_b128 v[196:199], v173 offset:52224
	ds_read_b128 v[200:203], v173 offset:53248
	ds_read_b128 v[204:207], v173 offset:54272
	ds_read_b128 v[208:211], v173 offset:55296
	ds_read_b128 v[212:215], v173 offset:56320
	s_waitcnt vmcnt(8)
	s_waitcnt lgkmcnt(0)
	s_barrier
	s_setprio 1
	s_waitcnt lgkmcnt(0)
	v_mfma_f32_16x16x32_bf16 v[60:63], v[128:131], v[184:187], v[60:63]
	v_mfma_f32_16x16x32_bf16 v[56:59], v[136:139], v[184:187], v[56:59]
	v_mfma_f32_16x16x32_bf16 v[44:47], v[128:131], v[192:195], v[44:47]
	v_mfma_f32_16x16x32_bf16 v[40:43], v[136:139], v[192:195], v[40:43]
	v_mfma_f32_16x16x32_bf16 v[28:31], v[128:131], v[200:203], v[28:31]
	v_mfma_f32_16x16x32_bf16 v[24:27], v[136:139], v[200:203], v[24:27]
	v_mfma_f32_16x16x32_bf16 v[12:15], v[128:131], v[208:211], v[12:15]
	v_mfma_f32_16x16x32_bf16 v[8:11], v[136:139], v[208:211], v[8:11]
	v_mfma_f32_16x16x32_bf16 v[60:63], v[132:135], v[188:191], v[60:63]
	v_mfma_f32_16x16x32_bf16 v[56:59], v[140:143], v[188:191], v[56:59]
	v_mfma_f32_16x16x32_bf16 v[44:47], v[132:135], v[196:199], v[44:47]
	v_mfma_f32_16x16x32_bf16 v[40:43], v[140:143], v[196:199], v[40:43]
	v_mfma_f32_16x16x32_bf16 v[28:31], v[132:135], v[204:207], v[28:31]
	v_mfma_f32_16x16x32_bf16 v[24:27], v[140:143], v[204:207], v[24:27]
	v_mfma_f32_16x16x32_bf16 v[12:15], v[132:135], v[212:215], v[12:15]
	v_mfma_f32_16x16x32_bf16 v[8:11], v[140:143], v[212:215], v[8:11]
	s_setprio 0
	s_setprio 1
	v_mfma_f32_16x16x32_bf16 v[52:55], v[160:163], v[184:187], v[52:55]
	v_mfma_f32_16x16x32_bf16 v[48:51], v[176:179], v[184:187], v[48:51]
	v_mfma_f32_16x16x32_bf16 v[36:39], v[160:163], v[192:195], v[36:39]
	v_mfma_f32_16x16x32_bf16 v[32:35], v[176:179], v[192:195], v[32:35]
	v_mfma_f32_16x16x32_bf16 v[20:23], v[160:163], v[200:203], v[20:23]
	v_mfma_f32_16x16x32_bf16 v[16:19], v[176:179], v[200:203], v[16:19]
	v_mfma_f32_16x16x32_bf16 v[4:7], v[160:163], v[208:211], v[4:7]
	v_mfma_f32_16x16x32_bf16 v[0:3], v[176:179], v[208:211], v[0:3]
	v_mfma_f32_16x16x32_bf16 v[52:55], v[164:167], v[188:191], v[52:55]
	v_mfma_f32_16x16x32_bf16 v[48:51], v[180:183], v[188:191], v[48:51]
	v_mfma_f32_16x16x32_bf16 v[36:39], v[164:167], v[196:199], v[36:39]
	v_mfma_f32_16x16x32_bf16 v[32:35], v[180:183], v[196:199], v[32:35]
	v_mfma_f32_16x16x32_bf16 v[20:23], v[164:167], v[204:207], v[20:23]
	v_mfma_f32_16x16x32_bf16 v[16:19], v[180:183], v[204:207], v[16:19]
	v_mfma_f32_16x16x32_bf16 v[4:7], v[164:167], v[212:215], v[4:7]
	v_mfma_f32_16x16x32_bf16 v[0:3], v[180:183], v[212:215], v[0:3]
	s_setprio 0
	s_barrier
	s_add_i32 s89, s89, 2
	s_add_u32 s53, s53, 0x100
	s_addc_u32 s88, s88, 0
	s_add_u32 s46, s46, 0x100
	s_addc_u32 s47, s47, 0
	s_cmp_gt_u32 s89, 29
	s_cbranch_scc0 .LBB0_332
	s_and_b64 vcc, exec, s[18:19]
	s_cbranch_vccz .LBB0_335
	s_barrier

; #define PG8_STAGE(bufoff, gbase, voff) do { _Pragma("unroll") for (int _i = 0; _i < 2; ++_i) \
;         __builtin_amdgcn_global_load_lds((const unsigned*)((const char*)(gbase) + (voff)[_i]), (LAS unsigned*)(lds + (bufoff) + ldsw + _i * 8192), 16, 0, 0); } while (0)
; #define PG8_LDA(dst, b, h) do { _Pragma("unroll") for (int m = 0; m < 4; ++m) _Pragma("unroll") for (int k = 0; k < 2; ++k) dst[m][k] = *(const LAS bf16x8*)(lds + PG8_SA(b, h) + aoff + m * 2048 + k * 1024); } while (0)
; #define PG8_LDB(dst, b, h) do { _Pragma("unroll") for (int n = 0; n < 2; ++n) _Pragma("unroll") for (int k = 0; k < 2; ++k) dst[n][k] = *(const LAS bf16x8*)(lds + PG8_SB(b, h) + boff + n * 2048 + k * 1024); } while (0)
; #define PG8_MMA(ai, bj, At, Bt) do { __builtin_amdgcn_s_setprio(1); _Pragma("unroll") for (int m = 0; m < 4; ++m) _Pragma("unroll") for (int n = 0; n < 2; ++n) _Pragma("unroll") for (int k = 0; k < 2; ++k) \
;         acc[ai][bj][m][n] = __builtin_amdgcn_mfma_f32_16x16x32_bf16(Bt[n][k], At[m][k], acc[ai][bj][m][n], 0, 0, 0); __builtin_amdgcn_s_setprio(0); } while (0)
; #define PG8_WAIT_V(n) asm volatile("s_waitcnt vmcnt(" #n ")" ::: "memory")
; #define PG8_WAIT_L(n) asm volatile("s_waitcnt lgkmcnt(" #n ")" ::: "memory")
; #define PG8_BAR __builtin_amdgcn_s_barrier()
; #define PG8_SCHED __builtin_amdgcn_sched_barrier(0)
; template <class Epi>
; __device__ __forceinline__ void gemm_phase(ldsp lds, const Gemm g, const StaticOrder& S, const Epi& E, int wave0) {
;     ...
;         for (int t = 0; t < nt; t += 2) {
;             const bool last = (t == nt - 2);
;             const char* a1 = cA + (size_t)(t + 1) * kstep;
;             const char* a2 = last ? nA : cA + (size_t)(t + 2) * kstep; const char* b2 = last ? nB : cB + (size_t)(t + 2) * kstep;
;             const char* a3 = a2 + kstep; const char* b3 = b2 + kstep;
;             PG8_LDB(B0, 0, 0); PG8_LDB(B1, 0, 1); PG8_SCHED; PG8_LDA(At, 0, 0); PG8_STAGE(PG8_SA(1, 1), a1 + hstep, voffA);
;             PG8_WAIT_V(8); PG8_WAIT_L(0); PG8_BAR; PG8_MMA(0, 0, At, B0); PG8_MMA(0, 1, At, B1); PG8_BAR; PG8_SCHED;
;             PG8_LDA(At, 0, 1); PG8_STAGE(PG8_SB(0, 0), b2, voffB); PG8_STAGE(PG8_SB(0, 1), b2 + hstep, voffB); PG8_STAGE(PG8_SA(0, 0), a2, voffA);
;             PG8_WAIT_V(8); PG8_WAIT_L(0); PG8_BAR; PG8_MMA(1, 0, At, B0); PG8_MMA(1, 1, At, B1); PG8_BAR; PG8_SCHED;
.LBB0_375:
	s_add_u32 s20, s18, 0xfff80080
	s_addc_u32 s21, s19, -1
	s_cmp_eq_u32 s56, 28
	s_cselect_b32 s23, s11, s21
	s_cselect_b32 s22, s17, s20
	s_cselect_b32 s21, s9, s55
	s_cselect_b32 s20, s53, s54
	s_add_i32 m0, s36, 0xc000
	s_nop 0
	global_load_lds_dwordx4 v138, s[18:19]
	s_add_i32 m0, s36, 0xe000
	s_nop 0
	global_load_lds_dwordx4 v136, s[18:19]
	ds_read_b128 v[144:147], v151
	ds_read_b128 v[154:157], v151 offset:1024
	ds_read_b128 v[158:161], v151 offset:2048
	ds_read_b128 v[162:165], v151 offset:3072
	ds_read_b128 v[166:169], v152
	ds_read_b128 v[170:173], v152 offset:1024
	ds_read_b128 v[174:177], v152 offset:2048
	ds_read_b128 v[178:181], v152 offset:3072
	ds_read_b128 v[182:185], v153
	ds_read_b128 v[186:189], v153 offset:1024
	ds_read_b128 v[190:193], v153 offset:2048
	ds_read_b128 v[194:197], v153 offset:3072
	ds_read_b128 v[198:201], v153 offset:4096
	ds_read_b128 v[202:205], v153 offset:5120
	ds_read_b128 v[206:209], v153 offset:6144
	ds_read_b128 v[210:213], v153 offset:7168
	s_waitcnt vmcnt(8)
	s_waitcnt lgkmcnt(0)
	s_barrier
	s_setprio 1
	s_waitcnt lgkmcnt(0)
	v_mfma_f32_16x16x32_bf16 v[124:127], v[144:147], v[182:185], v[124:127]
	v_mfma_f32_16x16x32_bf16 v[120:123], v[158:161], v[182:185], v[120:123]
	v_mfma_f32_16x16x32_bf16 v[112:115], v[144:147], v[190:193], v[112:115]
	v_mfma_f32_16x16x32_bf16 v[104:107], v[158:161], v[190:193], v[104:107]
	v_mfma_f32_16x16x32_bf16 v[100:103], v[144:147], v[198:201], v[100:103]
	v_mfma_f32_16x16x32_bf16 v[92:95], v[158:161], v[198:201], v[92:95]
	v_mfma_f32_16x16x32_bf16 v[84:87], v[144:147], v[206:209], v[84:87]
	v_mfma_f32_16x16x32_bf16 v[76:79], v[158:161], v[206:209], v[76:79]
	v_mfma_f32_16x16x32_bf16 v[124:127], v[154:157], v[186:189], v[124:127]
	v_mfma_f32_16x16x32_bf16 v[120:123], v[162:165], v[186:189], v[120:123]
	v_mfma_f32_16x16x32_bf16 v[112:115], v[154:157], v[194:197], v[112:115]
	v_mfma_f32_16x16x32_bf16 v[104:107], v[162:165], v[194:197], v[104:107]
	v_mfma_f32_16x16x32_bf16 v[100:103], v[154:157], v[202:205], v[100:103]
	v_mfma_f32_16x16x32_bf16 v[92:95], v[162:165], v[202:205], v[92:95]
	v_mfma_f32_16x16x32_bf16 v[84:87], v[154:157], v[210:213], v[84:87]
	v_mfma_f32_16x16x32_bf16 v[76:79], v[162:165], v[210:213], v[76:79]
	s_setprio 0
	s_setprio 1
	v_mfma_f32_16x16x32_bf16 v[116:119], v[166:169], v[182:185], v[116:119]
	v_mfma_f32_16x16x32_bf16 v[108:111], v[174:177], v[182:185], v[108:111]
	v_mfma_f32_16x16x32_bf16 v[96:99], v[166:169], v[190:193], v[96:99]
	v_mfma_f32_16x16x32_bf16 v[88:91], v[174:177], v[190:193], v[88:91]
	v_mfma_f32_16x16x32_bf16 v[80:83], v[166:169], v[198:201], v[80:83]
	v_mfma_f32_16x16x32_bf16 v[72:75], v[174:177], v[198:201], v[72:75]
	v_mfma_f32_16x16x32_bf16 v[68:71], v[166:169], v[206:209], v[68:71]
	v_mfma_f32_16x16x32_bf16 v[64:67], v[174:177], v[206:209], v[64:67]
	v_mfma_f32_16x16x32_bf16 v[116:119], v[170:173], v[186:189], v[116:119]
	v_mfma_f32_16x16x32_bf16 v[108:111], v[178:181], v[186:189], v[108:111]
	v_mfma_f32_16x16x32_bf16 v[96:99], v[170:173], v[194:197], v[96:99]
	v_mfma_f32_16x16x32_bf16 v[88:91], v[178:181], v[194:197], v[88:91]
	v_mfma_f32_16x16x32_bf16 v[80:83], v[170:173], v[202:205], v[80:83]
	v_mfma_f32_16x16x32_bf16 v[72:75], v[178:181], v[202:205], v[72:75]
	v_mfma_f32_16x16x32_bf16 v[68:71], v[170:173], v[210:213], v[68:71]
	v_mfma_f32_16x16x32_bf16 v[64:67], v[178:181], v[210:213], v[64:67]
	s_setprio 0
	s_barrier
	s_add_i32 s57, s50, s31
	s_add_u32 s100, s22, 0x80
	s_addc_u32 s101, s23, 0
	s_mov_b32 m0, s57
	s_nop 0
	global_load_lds_dwordx4 v132, s[20:21]
	s_add_i32 m0, s57, 0x2000
	s_add_u32 s60, s20, 0x80000
	s_addc_u32 s61, s21, 0
	s_add_i32 s57, s51, s31
	global_load_lds_dwordx4 v128, s[20:21]
	s_mov_b32 m0, s57
	s_nop 0
	global_load_lds_dwordx4 v132, s[60:61]
	s_add_i32 m0, s57, 0x2000
	s_nop 0
	global_load_lds_dwordx4 v128, s[60:61]
	s_mov_b32 m0, s36
	s_nop 0
	global_load_lds_dwordx4 v134, s[22:23]
	s_mov_b32 m0, s37
	s_nop 0
	global_load_lds_dwordx4 v130, s[22:23]
	ds_read_b128 v[182:185], v153 offset:16384
	ds_read_b128 v[186:189], v153 offset:17408
	ds_read_b128 v[190:193], v153 offset:18432
	ds_read_b128 v[194:197], v153 offset:19456
	ds_read_b128 v[198:201], v153 offset:20480
	ds_read_b128 v[202:205], v153 offset:21504
	ds_read_b128 v[206:209], v153 offset:22528
	ds_read_b128 v[210:213], v153 offset:23552
	s_waitcnt vmcnt(8)
	s_waitcnt lgkmcnt(0)
	s_barrier
	s_setprio 1
	s_waitcnt lgkmcnt(0)
	v_mfma_f32_16x16x32_bf16 v[60:63], v[144:147], v[182:185], v[60:63]
	v_mfma_f32_16x16x32_bf16 v[56:59], v[158:161], v[182:185], v[56:59]
	v_mfma_f32_16x16x32_bf16 v[52:55], v[144:147], v[190:193], v[52:55]
	v_mfma_f32_16x16x32_bf16 v[44:47], v[158:161], v[190:193], v[44:47]
	v_mfma_f32_16x16x32_bf16 v[36:39], v[144:147], v[198:201], v[36:39]
	v_mfma_f32_16x16x32_bf16 v[28:31], v[158:161], v[198:201], v[28:31]
	v_mfma_f32_16x16x32_bf16 v[20:23], v[144:147], v[206:209], v[20:23]
	v_mfma_f32_16x16x32_bf16 v[12:15], v[158:161], v[206:209], v[12:15]
	v_mfma_f32_16x16x32_bf16 v[60:63], v[154:157], v[186:189], v[60:63]
	v_mfma_f32_16x16x32_bf16 v[56:59], v[162:165], v[186:189], v[56:59]
	v_mfma_f32_16x16x32_bf16 v[52:55], v[154:157], v[194:197], v[52:55]
	v_mfma_f32_16x16x32_bf16 v[44:47], v[162:165], v[194:197], v[44:47]
	v_mfma_f32_16x16x32_bf16 v[36:39], v[154:157], v[202:205], v[36:39]
	v_mfma_f32_16x16x32_bf16 v[28:31], v[162:165], v[202:205], v[28:31]
	v_mfma_f32_16x16x32_bf16 v[20:23], v[154:157], v[210:213], v[20:23]
	v_mfma_f32_16x16x32_bf16 v[12:15], v[162:165], v[210:213], v[12:15]
	s_setprio 0
	s_setprio 1
	v_mfma_f32_16x16x32_bf16 v[48:51], v[166:169], v[182:185], v[48:51]
	v_mfma_f32_16x16x32_bf16 v[40:43], v[174:177], v[182:185], v[40:43]
	v_mfma_f32_16x16x32_bf16 v[32:35], v[166:169], v[190:193], v[32:35]
	v_mfma_f32_16x16x32_bf16 v[24:27], v[174:177], v[190:193], v[24:27]
	v_mfma_f32_16x16x32_bf16 v[16:19], v[166:169], v[198:201], v[16:19]
	v_mfma_f32_16x16x32_bf16 v[8:11], v[174:177], v[198:201], v[8:11]
	v_mfma_f32_16x16x32_bf16 v[4:7], v[166:169], v[206:209], v[4:7]
	v_mfma_f32_16x16x32_bf16 v[0:3], v[174:177], v[206:209], v[0:3]
	v_mfma_f32_16x16x32_bf16 v[48:51], v[170:173], v[186:189], v[48:51]
	v_mfma_f32_16x16x32_bf16 v[40:43], v[178:181], v[186:189], v[40:43]
	v_mfma_f32_16x16x32_bf16 v[32:35], v[170:173], v[194:197], v[32:35]
	v_mfma_f32_16x16x32_bf16 v[24:27], v[178:181], v[194:197], v[24:27]
	v_mfma_f32_16x16x32_bf16 v[16:19], v[170:173], v[202:205], v[16:19]
	v_mfma_f32_16x16x32_bf16 v[8:11], v[178:181], v[202:205], v[8:11]
	v_mfma_f32_16x16x32_bf16 v[4:7], v[170:173], v[210:213], v[4:7]
	v_mfma_f32_16x16x32_bf16 v[0:3], v[178:181], v[210:213], v[0:3]
	s_setprio 0
	s_barrier
; #define PG8_STAGE(bufoff, gbase, voff) do { _Pragma("unroll") for (int _i = 0; _i < 2; ++_i) \
;         __builtin_amdgcn_global_load_lds((const unsigned*)((const char*)(gbase) + (voff)[_i]), (LAS unsigned*)(lds + (bufoff) + ldsw + _i * 8192), 16, 0, 0); } while (0)
; #define PG8_LDA(dst, b, h) do { _Pragma("unroll") for (int m = 0; m < 4; ++m) _Pragma("unroll") for (int k = 0; k < 2; ++k) dst[m][k] = *(const LAS bf16x8*)(lds + PG8_SA(b, h) + aoff + m * 2048 + k * 1024); } while (0)
; #define PG8_LDB(dst, b, h) do { _Pragma("unroll") for (int n = 0; n < 2; ++n) _Pragma("unroll") for (int k = 0; k < 2; ++k) dst[n][k] = *(const LAS bf16x8*)(lds + PG8_SB(b, h) + boff + n * 2048 + k * 1024); } while (0)
; #define PG8_MMA(ai, bj, At, Bt) do { __builtin_amdgcn_s_setprio(1); _Pragma("unroll") for (int m = 0; m < 4; ++m) _Pragma("unroll") for (int n = 0; n < 2; ++n) _Pragma("unroll") for (int k = 0; k < 2; ++k) \
;         acc[ai][bj][m][n] = __builtin_amdgcn_mfma_f32_16x16x32_bf16(Bt[n][k], At[m][k], acc[ai][bj][m][n], 0, 0, 0); __builtin_amdgcn_s_setprio(0); } while (0)
; #define PG8_WAIT_V(n) asm volatile("s_waitcnt vmcnt(" #n ")" ::: "memory")
; #define PG8_WAIT_L(n) asm volatile("s_waitcnt lgkmcnt(" #n ")" ::: "memory")
; #define PG8_BAR __builtin_amdgcn_s_barrier()
; #define PG8_SCHED __builtin_amdgcn_sched_barrier(0)
; template <class Epi>
; __device__ __forceinline__ void gemm_phase(ldsp lds, const Gemm g, const StaticOrder& S, const Epi& E, int wave0) {
;     ...
;             PG8_LDB(B0, 1, 0); PG8_LDB(B1, 1, 1); PG8_SCHED; PG8_LDA(At, 1, 0); PG8_STAGE(PG8_SA(0, 1), a2 + hstep, voffA);
;             PG8_WAIT_V(8); PG8_WAIT_L(0); PG8_BAR; PG8_MMA(0, 0, At, B0); PG8_MMA(0, 1, At, B1); PG8_BAR; PG8_SCHED;
;             PG8_LDA(At, 1, 1); PG8_STAGE(PG8_SB(1, 0), b3, voffB); PG8_STAGE(PG8_SB(1, 1), b3 + hstep, voffB); PG8_STAGE(PG8_SA(1, 0), a3, voffA);
;             PG8_WAIT_V(8); PG8_WAIT_L(0); PG8_BAR; PG8_MMA(1, 0, At, B0); PG8_MMA(1, 1, At, B1); PG8_BAR; PG8_SCHED;
;         }
;         if (wr == 0) PG8_BAR;
	s_add_i32 s57, 0, 0x18000
	s_add_i32 s60, 0, 0x1c000
	v_add_u32_e32 v162, s57, v150
	v_add_u32_e32 v178, s60, v150
	s_add_u32 s22, s22, 0x80000
	s_addc_u32 s23, s23, 0
	s_mov_b32 m0, s38
	s_nop 0
	global_load_lds_dwordx4 v134, s[22:23]
	s_mov_b32 m0, s39
	s_nop 0
	global_load_lds_dwordx4 v130, s[22:23]
	ds_read_b128 v[144:147], v162
	ds_read_b128 v[154:157], v162 offset:1024
	ds_read_b128 v[158:161], v162 offset:2048
	ds_read_b128 v[162:165], v162 offset:3072
	ds_read_b128 v[166:169], v178
	ds_read_b128 v[170:173], v178 offset:1024
	ds_read_b128 v[174:177], v178 offset:2048
	ds_read_b128 v[178:181], v178 offset:3072
	ds_read_b128 v[182:185], v153 offset:32768
	ds_read_b128 v[186:189], v153 offset:33792
	ds_read_b128 v[190:193], v153 offset:34816
	ds_read_b128 v[194:197], v153 offset:35840
	ds_read_b128 v[198:201], v153 offset:36864
	ds_read_b128 v[202:205], v153 offset:37888
	ds_read_b128 v[206:209], v153 offset:38912
	ds_read_b128 v[210:213], v153 offset:39936
	s_waitcnt vmcnt(8)
	s_waitcnt lgkmcnt(0)
	s_barrier
	s_setprio 1
	s_waitcnt lgkmcnt(0)
	v_mfma_f32_16x16x32_bf16 v[124:127], v[144:147], v[182:185], v[124:127]
	v_mfma_f32_16x16x32_bf16 v[120:123], v[158:161], v[182:185], v[120:123]
	v_mfma_f32_16x16x32_bf16 v[112:115], v[144:147], v[190:193], v[112:115]
	v_mfma_f32_16x16x32_bf16 v[104:107], v[158:161], v[190:193], v[104:107]
	v_mfma_f32_16x16x32_bf16 v[100:103], v[144:147], v[198:201], v[100:103]
	v_mfma_f32_16x16x32_bf16 v[92:95], v[158:161], v[198:201], v[92:95]
	v_mfma_f32_16x16x32_bf16 v[84:87], v[144:147], v[206:209], v[84:87]
	v_mfma_f32_16x16x32_bf16 v[76:79], v[158:161], v[206:209], v[76:79]
	v_mfma_f32_16x16x32_bf16 v[124:127], v[154:157], v[186:189], v[124:127]
	v_mfma_f32_16x16x32_bf16 v[120:123], v[162:165], v[186:189], v[120:123]
	v_mfma_f32_16x16x32_bf16 v[112:115], v[154:157], v[194:197], v[112:115]
	v_mfma_f32_16x16x32_bf16 v[104:107], v[162:165], v[194:197], v[104:107]
	v_mfma_f32_16x16x32_bf16 v[100:103], v[154:157], v[202:205], v[100:103]
	v_mfma_f32_16x16x32_bf16 v[92:95], v[162:165], v[202:205], v[92:95]
	v_mfma_f32_16x16x32_bf16 v[84:87], v[154:157], v[210:213], v[84:87]
	v_mfma_f32_16x16x32_bf16 v[76:79], v[162:165], v[210:213], v[76:79]
	s_setprio 0
	s_setprio 1
	v_mfma_f32_16x16x32_bf16 v[116:119], v[166:169], v[182:185], v[116:119]
	v_mfma_f32_16x16x32_bf16 v[108:111], v[174:177], v[182:185], v[108:111]
	v_mfma_f32_16x16x32_bf16 v[96:99], v[166:169], v[190:193], v[96:99]
	v_mfma_f32_16x16x32_bf16 v[88:91], v[174:177], v[190:193], v[88:91]
	v_mfma_f32_16x16x32_bf16 v[80:83], v[166:169], v[198:201], v[80:83]
	v_mfma_f32_16x16x32_bf16 v[72:75], v[174:177], v[198:201], v[72:75]
	v_mfma_f32_16x16x32_bf16 v[68:71], v[166:169], v[206:209], v[68:71]
	v_mfma_f32_16x16x32_bf16 v[64:67], v[174:177], v[206:209], v[64:67]
	v_mfma_f32_16x16x32_bf16 v[116:119], v[170:173], v[186:189], v[116:119]
	v_mfma_f32_16x16x32_bf16 v[108:111], v[178:181], v[186:189], v[108:111]
	v_mfma_f32_16x16x32_bf16 v[96:99], v[170:173], v[194:197], v[96:99]
	v_mfma_f32_16x16x32_bf16 v[88:91], v[178:181], v[194:197], v[88:91]
	v_mfma_f32_16x16x32_bf16 v[80:83], v[170:173], v[202:205], v[80:83]
	v_mfma_f32_16x16x32_bf16 v[72:75], v[178:181], v[202:205], v[72:75]
	v_mfma_f32_16x16x32_bf16 v[68:71], v[170:173], v[210:213], v[68:71]
	v_mfma_f32_16x16x32_bf16 v[64:67], v[178:181], v[210:213], v[64:67]
	s_setprio 0
	s_barrier
	s_add_i32 s22, s57, s31
	s_add_u32 s20, s20, 0x80
	s_addc_u32 s21, s21, 0
	s_mov_b32 m0, s22
	s_nop 0
	global_load_lds_dwordx4 v132, s[20:21]
	s_add_i32 m0, s22, 0x2000
	s_add_i32 s22, s60, s31
	global_load_lds_dwordx4 v128, s[20:21]
	s_add_u32 s20, s20, 0x80000
	s_addc_u32 s21, s21, 0
	s_mov_b32 m0, s22
	s_nop 0
	global_load_lds_dwordx4 v132, s[20:21]
	s_add_i32 m0, s22, 0x2000
	s_nop 0
	global_load_lds_dwordx4 v128, s[20:21]
	s_mov_b32 m0, s46
	s_nop 0
	global_load_lds_dwordx4 v134, s[100:101]
	s_mov_b32 m0, s47
	s_nop 0
	global_load_lds_dwordx4 v130, s[100:101]
	ds_read_b128 v[182:185], v153 offset:49152
	ds_read_b128 v[186:189], v153 offset:50176
	ds_read_b128 v[190:193], v153 offset:51200
	ds_read_b128 v[194:197], v153 offset:52224
	ds_read_b128 v[198:201], v153 offset:53248
	ds_read_b128 v[202:205], v153 offset:54272
	ds_read_b128 v[206:209], v153 offset:55296
	ds_read_b128 v[210:213], v153 offset:56320
	s_waitcnt vmcnt(8)
	s_waitcnt lgkmcnt(0)
	s_barrier
	s_setprio 1
	s_waitcnt lgkmcnt(0)
	v_mfma_f32_16x16x32_bf16 v[60:63], v[144:147], v[182:185], v[60:63]
	v_mfma_f32_16x16x32_bf16 v[56:59], v[158:161], v[182:185], v[56:59]
	v_mfma_f32_16x16x32_bf16 v[52:55], v[144:147], v[190:193], v[52:55]
	v_mfma_f32_16x16x32_bf16 v[44:47], v[158:161], v[190:193], v[44:47]
	v_mfma_f32_16x16x32_bf16 v[36:39], v[144:147], v[198:201], v[36:39]
	v_mfma_f32_16x16x32_bf16 v[28:31], v[158:161], v[198:201], v[28:31]
	v_mfma_f32_16x16x32_bf16 v[20:23], v[144:147], v[206:209], v[20:23]
	v_mfma_f32_16x16x32_bf16 v[12:15], v[158:161], v[206:209], v[12:15]
	v_mfma_f32_16x16x32_bf16 v[60:63], v[154:157], v[186:189], v[60:63]
	v_mfma_f32_16x16x32_bf16 v[56:59], v[162:165], v[186:189], v[56:59]
	v_mfma_f32_16x16x32_bf16 v[52:55], v[154:157], v[194:197], v[52:55]
	v_mfma_f32_16x16x32_bf16 v[44:47], v[162:165], v[194:197], v[44:47]
	v_mfma_f32_16x16x32_bf16 v[36:39], v[154:157], v[202:205], v[36:39]
	v_mfma_f32_16x16x32_bf16 v[28:31], v[162:165], v[202:205], v[28:31]
	v_mfma_f32_16x16x32_bf16 v[20:23], v[154:157], v[210:213], v[20:23]
	v_mfma_f32_16x16x32_bf16 v[12:15], v[162:165], v[210:213], v[12:15]
	s_setprio 0
	s_setprio 1
	v_mfma_f32_16x16x32_bf16 v[48:51], v[166:169], v[182:185], v[48:51]
	v_mfma_f32_16x16x32_bf16 v[40:43], v[174:177], v[182:185], v[40:43]
	v_mfma_f32_16x16x32_bf16 v[32:35], v[166:169], v[190:193], v[32:35]
	v_mfma_f32_16x16x32_bf16 v[24:27], v[174:177], v[190:193], v[24:27]
	v_mfma_f32_16x16x32_bf16 v[16:19], v[166:169], v[198:201], v[16:19]
	v_mfma_f32_16x16x32_bf16 v[8:11], v[174:177], v[198:201], v[8:11]
	v_mfma_f32_16x16x32_bf16 v[4:7], v[166:169], v[206:209], v[4:7]
	v_mfma_f32_16x16x32_bf16 v[0:3], v[174:177], v[206:209], v[0:3]
	v_mfma_f32_16x16x32_bf16 v[48:51], v[170:173], v[186:189], v[48:51]
	v_mfma_f32_16x16x32_bf16 v[40:43], v[178:181], v[186:189], v[40:43]
	v_mfma_f32_16x16x32_bf16 v[32:35], v[170:173], v[194:197], v[32:35]
	v_mfma_f32_16x16x32_bf16 v[24:27], v[178:181], v[194:197], v[24:27]
	v_mfma_f32_16x16x32_bf16 v[16:19], v[170:173], v[202:205], v[16:19]
	v_mfma_f32_16x16x32_bf16 v[8:11], v[178:181], v[202:205], v[8:11]
	v_mfma_f32_16x16x32_bf16 v[4:7], v[170:173], v[210:213], v[4:7]
	v_mfma_f32_16x16x32_bf16 v[0:3], v[178:181], v[210:213], v[0:3]
	s_setprio 0
	s_barrier
	s_add_i32 s56, s56, 2
	s_add_u32 s54, s54, 0x100
	s_addc_u32 s55, s55, 0
	s_add_u32 s18, s18, 0x100
	s_addc_u32 s19, s19, 0
	s_cmp_gt_u32 s56, 29
	s_cbranch_scc0 .LBB0_375
	s_and_b64 vcc, exec, s[6:7]
	s_cbranch_vccz .LBB0_378
	s_barrier

; #define PG8_STAGE(bufoff, gbase, voff) do { _Pragma("unroll") for (int _i = 0; _i < 2; ++_i) \
;         __builtin_amdgcn_global_load_lds((const unsigned*)((const char*)(gbase) + (voff)[_i]), (LAS unsigned*)(lds + (bufoff) + ldsw + _i * 8192), 16, 0, 0); } while (0)
; #define PG8_LDA(dst, b, h) do { _Pragma("unroll") for (int m = 0; m < 4; ++m) _Pragma("unroll") for (int k = 0; k < 2; ++k) dst[m][k] = *(const LAS bf16x8*)(lds + PG8_SA(b, h) + aoff + m * 2048 + k * 1024); } while (0)
; #define PG8_LDB(dst, b, h) do { _Pragma("unroll") for (int n = 0; n < 2; ++n) _Pragma("unroll") for (int k = 0; k < 2; ++k) dst[n][k] = *(const LAS bf16x8*)(lds + PG8_SB(b, h) + boff + n * 2048 + k * 1024); } while (0)
; #define PG8_MMA(ai, bj, At, Bt) do { __builtin_amdgcn_s_setprio(1); _Pragma("unroll") for (int m = 0; m < 4; ++m) _Pragma("unroll") for (int n = 0; n < 2; ++n) _Pragma("unroll") for (int k = 0; k < 2; ++k) \
;         acc[ai][bj][m][n] = __builtin_amdgcn_mfma_f32_16x16x32_bf16(Bt[n][k], At[m][k], acc[ai][bj][m][n], 0, 0, 0); __builtin_amdgcn_s_setprio(0); } while (0)
; #define PG8_WAIT_V(n) asm volatile("s_waitcnt vmcnt(" #n ")" ::: "memory")
; #define PG8_WAIT_L(n) asm volatile("s_waitcnt lgkmcnt(" #n ")" ::: "memory")
; #define PG8_BAR __builtin_amdgcn_s_barrier()
; #define PG8_SCHED __builtin_amdgcn_sched_barrier(0)
; template <class Epi>
; __device__ __forceinline__ void gemm_phase(ldsp lds, const Gemm g, const StaticOrder& S, const Epi& E, int wave0) {
;     ...
;         for (int t = 0; t < nt; t += 2) {
;             const bool last = (t == nt - 2);
;             const char* a1 = cA + (size_t)(t + 1) * kstep;
;             const char* a2 = last ? nA : cA + (size_t)(t + 2) * kstep; const char* b2 = last ? nB : cB + (size_t)(t + 2) * kstep;
;             const char* a3 = a2 + kstep; const char* b3 = b2 + kstep;
;             PG8_LDB(B0, 0, 0); PG8_LDB(B1, 0, 1); PG8_SCHED; PG8_LDA(At, 0, 0); PG8_STAGE(PG8_SA(1, 1), a1 + hstep, voffA);
;             PG8_WAIT_V(8); PG8_WAIT_L(0); PG8_BAR; PG8_MMA(0, 0, At, B0); PG8_MMA(0, 1, At, B1); PG8_BAR; PG8_SCHED;
;             PG8_LDA(At, 0, 1); PG8_STAGE(PG8_SB(0, 0), b2, voffB); PG8_STAGE(PG8_SB(0, 1), b2 + hstep, voffB); PG8_STAGE(PG8_SA(0, 0), a2, voffA);
;             PG8_WAIT_V(8); PG8_WAIT_L(0); PG8_BAR; PG8_MMA(1, 0, At, B0); PG8_MMA(1, 1, At, B1); PG8_BAR; PG8_SCHED;
.LBB0_621:
	s_add_u32 s36, s34, 0xfff80080
	s_addc_u32 s37, s35, -1
	s_cmp_eq_u32 s76, 28
	s_cselect_b32 s39, s25, s37
	s_cselect_b32 s38, s72, s36
	s_cselect_b32 s37, s23, s75
	s_cselect_b32 s36, s73, s74
	s_add_i32 m0, s31, 0xc000
	s_nop 0
	global_load_lds_dwordx4 v138, s[34:35]
	s_add_i32 m0, s31, 0xe000
	s_nop 0
	global_load_lds_dwordx4 v136, s[34:35]
	ds_read_b128 v[152:155], v149
	ds_read_b128 v[156:159], v149 offset:1024
	ds_read_b128 v[160:163], v149 offset:2048
	ds_read_b128 v[164:167], v149 offset:3072
	ds_read_b128 v[168:171], v150
	ds_read_b128 v[172:175], v150 offset:1024
	ds_read_b128 v[176:179], v150 offset:2048
	ds_read_b128 v[180:183], v150 offset:3072
	ds_read_b128 v[184:187], v151
	ds_read_b128 v[188:191], v151 offset:1024
	ds_read_b128 v[192:195], v151 offset:2048
	ds_read_b128 v[196:199], v151 offset:3072
	ds_read_b128 v[200:203], v151 offset:4096
	ds_read_b128 v[204:207], v151 offset:5120
	ds_read_b128 v[208:211], v151 offset:6144
	ds_read_b128 v[212:215], v151 offset:7168
	s_waitcnt vmcnt(8)
	s_waitcnt lgkmcnt(0)
	s_barrier
	s_setprio 1
	s_waitcnt lgkmcnt(0)
	v_mfma_f32_16x16x32_bf16 v[124:127], v[152:155], v[184:187], v[124:127]
	v_mfma_f32_16x16x32_bf16 v[120:123], v[160:163], v[184:187], v[120:123]
	v_mfma_f32_16x16x32_bf16 v[108:111], v[152:155], v[192:195], v[108:111]
	v_mfma_f32_16x16x32_bf16 v[104:107], v[160:163], v[192:195], v[104:107]
	v_mfma_f32_16x16x32_bf16 v[92:95], v[152:155], v[200:203], v[92:95]
	v_mfma_f32_16x16x32_bf16 v[88:91], v[160:163], v[200:203], v[88:91]
	v_mfma_f32_16x16x32_bf16 v[76:79], v[152:155], v[208:211], v[76:79]
	v_mfma_f32_16x16x32_bf16 v[72:75], v[160:163], v[208:211], v[72:75]
	v_mfma_f32_16x16x32_bf16 v[124:127], v[156:159], v[188:191], v[124:127]
	v_mfma_f32_16x16x32_bf16 v[120:123], v[164:167], v[188:191], v[120:123]
	v_mfma_f32_16x16x32_bf16 v[108:111], v[156:159], v[196:199], v[108:111]
	v_mfma_f32_16x16x32_bf16 v[104:107], v[164:167], v[196:199], v[104:107]
	v_mfma_f32_16x16x32_bf16 v[92:95], v[156:159], v[204:207], v[92:95]
	v_mfma_f32_16x16x32_bf16 v[88:91], v[164:167], v[204:207], v[88:91]
	v_mfma_f32_16x16x32_bf16 v[76:79], v[156:159], v[212:215], v[76:79]
	v_mfma_f32_16x16x32_bf16 v[72:75], v[164:167], v[212:215], v[72:75]
	s_setprio 0
	s_setprio 1
	v_mfma_f32_16x16x32_bf16 v[116:119], v[168:171], v[184:187], v[116:119]
	v_mfma_f32_16x16x32_bf16 v[112:115], v[176:179], v[184:187], v[112:115]
	v_mfma_f32_16x16x32_bf16 v[100:103], v[168:171], v[192:195], v[100:103]
	v_mfma_f32_16x16x32_bf16 v[96:99], v[176:179], v[192:195], v[96:99]
	v_mfma_f32_16x16x32_bf16 v[84:87], v[168:171], v[200:203], v[84:87]
	v_mfma_f32_16x16x32_bf16 v[80:83], v[176:179], v[200:203], v[80:83]
	v_mfma_f32_16x16x32_bf16 v[68:71], v[168:171], v[208:211], v[68:71]
	v_mfma_f32_16x16x32_bf16 v[64:67], v[176:179], v[208:211], v[64:67]
	v_mfma_f32_16x16x32_bf16 v[116:119], v[172:175], v[188:191], v[116:119]
	v_mfma_f32_16x16x32_bf16 v[112:115], v[180:183], v[188:191], v[112:115]
	v_mfma_f32_16x16x32_bf16 v[100:103], v[172:175], v[196:199], v[100:103]
	v_mfma_f32_16x16x32_bf16 v[96:99], v[180:183], v[196:199], v[96:99]
	v_mfma_f32_16x16x32_bf16 v[84:87], v[172:175], v[204:207], v[84:87]
	v_mfma_f32_16x16x32_bf16 v[80:83], v[180:183], v[204:207], v[80:83]
	v_mfma_f32_16x16x32_bf16 v[68:71], v[172:175], v[212:215], v[68:71]
	v_mfma_f32_16x16x32_bf16 v[64:67], v[180:183], v[212:215], v[64:67]
	s_setprio 0
	s_barrier
	s_add_i32 s77, s62, s49
	s_add_u32 s100, s38, 0x80
	s_addc_u32 s101, s39, 0
	s_mov_b32 m0, s77
	s_nop 0
	global_load_lds_dwordx4 v130, s[36:37]
	s_add_i32 m0, s77, 0x2000
	s_add_u32 s78, s36, 0x80000
	s_addc_u32 s79, s37, 0
	s_add_i32 s77, s63, s49
	global_load_lds_dwordx4 v134, s[36:37]
	s_mov_b32 m0, s77
	s_nop 0
	global_load_lds_dwordx4 v130, s[78:79]
	s_add_i32 m0, s77, 0x2000
	s_nop 0
	global_load_lds_dwordx4 v134, s[78:79]
	s_mov_b32 m0, s31
	s_nop 0
	global_load_lds_dwordx4 v128, s[38:39]
	s_mov_b32 m0, s50
	s_nop 0
	global_load_lds_dwordx4 v132, s[38:39]
	ds_read_b128 v[184:187], v151 offset:16384
	ds_read_b128 v[188:191], v151 offset:17408
	ds_read_b128 v[192:195], v151 offset:18432
	ds_read_b128 v[196:199], v151 offset:19456
	ds_read_b128 v[200:203], v151 offset:20480
	ds_read_b128 v[204:207], v151 offset:21504
	ds_read_b128 v[208:211], v151 offset:22528
	ds_read_b128 v[212:215], v151 offset:23552
	s_waitcnt vmcnt(8)
	s_waitcnt lgkmcnt(0)
	s_barrier
	s_setprio 1
	s_waitcnt lgkmcnt(0)
	v_mfma_f32_16x16x32_bf16 v[60:63], v[152:155], v[184:187], v[60:63]
	v_mfma_f32_16x16x32_bf16 v[56:59], v[160:163], v[184:187], v[56:59]
	v_mfma_f32_16x16x32_bf16 v[44:47], v[152:155], v[192:195], v[44:47]
	v_mfma_f32_16x16x32_bf16 v[40:43], v[160:163], v[192:195], v[40:43]
	v_mfma_f32_16x16x32_bf16 v[28:31], v[152:155], v[200:203], v[28:31]
	v_mfma_f32_16x16x32_bf16 v[24:27], v[160:163], v[200:203], v[24:27]
	v_mfma_f32_16x16x32_bf16 v[12:15], v[152:155], v[208:211], v[12:15]
	v_mfma_f32_16x16x32_bf16 v[8:11], v[160:163], v[208:211], v[8:11]
	v_mfma_f32_16x16x32_bf16 v[60:63], v[156:159], v[188:191], v[60:63]
	v_mfma_f32_16x16x32_bf16 v[56:59], v[164:167], v[188:191], v[56:59]
	v_mfma_f32_16x16x32_bf16 v[44:47], v[156:159], v[196:199], v[44:47]
	v_mfma_f32_16x16x32_bf16 v[40:43], v[164:167], v[196:199], v[40:43]
	v_mfma_f32_16x16x32_bf16 v[28:31], v[156:159], v[204:207], v[28:31]
	v_mfma_f32_16x16x32_bf16 v[24:27], v[164:167], v[204:207], v[24:27]
	v_mfma_f32_16x16x32_bf16 v[12:15], v[156:159], v[212:215], v[12:15]
	v_mfma_f32_16x16x32_bf16 v[8:11], v[164:167], v[212:215], v[8:11]
	s_setprio 0
	s_setprio 1
	v_mfma_f32_16x16x32_bf16 v[52:55], v[168:171], v[184:187], v[52:55]
	v_mfma_f32_16x16x32_bf16 v[48:51], v[176:179], v[184:187], v[48:51]
	v_mfma_f32_16x16x32_bf16 v[36:39], v[168:171], v[192:195], v[36:39]
	v_mfma_f32_16x16x32_bf16 v[32:35], v[176:179], v[192:195], v[32:35]
	v_mfma_f32_16x16x32_bf16 v[20:23], v[168:171], v[200:203], v[20:23]
	v_mfma_f32_16x16x32_bf16 v[16:19], v[176:179], v[200:203], v[16:19]
	v_mfma_f32_16x16x32_bf16 v[4:7], v[168:171], v[208:211], v[4:7]
	v_mfma_f32_16x16x32_bf16 v[0:3], v[176:179], v[208:211], v[0:3]
	v_mfma_f32_16x16x32_bf16 v[52:55], v[172:175], v[188:191], v[52:55]
	v_mfma_f32_16x16x32_bf16 v[48:51], v[180:183], v[188:191], v[48:51]
	v_mfma_f32_16x16x32_bf16 v[36:39], v[172:175], v[196:199], v[36:39]
	v_mfma_f32_16x16x32_bf16 v[32:35], v[180:183], v[196:199], v[32:35]
	v_mfma_f32_16x16x32_bf16 v[20:23], v[172:175], v[204:207], v[20:23]
	v_mfma_f32_16x16x32_bf16 v[16:19], v[180:183], v[204:207], v[16:19]
	v_mfma_f32_16x16x32_bf16 v[4:7], v[172:175], v[212:215], v[4:7]
	v_mfma_f32_16x16x32_bf16 v[0:3], v[180:183], v[212:215], v[0:3]
	s_setprio 0
	s_barrier
; #define PG8_STAGE(bufoff, gbase, voff) do { _Pragma("unroll") for (int _i = 0; _i < 2; ++_i) \
;         __builtin_amdgcn_global_load_lds((const unsigned*)((const char*)(gbase) + (voff)[_i]), (LAS unsigned*)(lds + (bufoff) + ldsw + _i * 8192), 16, 0, 0); } while (0)
; #define PG8_LDA(dst, b, h) do { _Pragma("unroll") for (int m = 0; m < 4; ++m) _Pragma("unroll") for (int k = 0; k < 2; ++k) dst[m][k] = *(const LAS bf16x8*)(lds + PG8_SA(b, h) + aoff + m * 2048 + k * 1024); } while (0)
; #define PG8_LDB(dst, b, h) do { _Pragma("unroll") for (int n = 0; n < 2; ++n) _Pragma("unroll") for (int k = 0; k < 2; ++k) dst[n][k] = *(const LAS bf16x8*)(lds + PG8_SB(b, h) + boff + n * 2048 + k * 1024); } while (0)
; #define PG8_MMA(ai, bj, At, Bt) do { __builtin_amdgcn_s_setprio(1); _Pragma("unroll") for (int m = 0; m < 4; ++m) _Pragma("unroll") for (int n = 0; n < 2; ++n) _Pragma("unroll") for (int k = 0; k < 2; ++k) \
;         acc[ai][bj][m][n] = __builtin_amdgcn_mfma_f32_16x16x32_bf16(Bt[n][k], At[m][k], acc[ai][bj][m][n], 0, 0, 0); __builtin_amdgcn_s_setprio(0); } while (0)
; #define PG8_WAIT_V(n) asm volatile("s_waitcnt vmcnt(" #n ")" ::: "memory")
; #define PG8_WAIT_L(n) asm volatile("s_waitcnt lgkmcnt(" #n ")" ::: "memory")
; #define PG8_BAR __builtin_amdgcn_s_barrier()
; #define PG8_SCHED __builtin_amdgcn_sched_barrier(0)
; template <class Epi>
; __device__ __forceinline__ void gemm_phase(ldsp lds, const Gemm g, const StaticOrder& S, const Epi& E, int wave0) {
;     ...
;             PG8_LDB(B0, 1, 0); PG8_LDB(B1, 1, 1); PG8_SCHED; PG8_LDA(At, 1, 0); PG8_STAGE(PG8_SA(0, 1), a2 + hstep, voffA);
;             PG8_WAIT_V(8); PG8_WAIT_L(0); PG8_BAR; PG8_MMA(0, 0, At, B0); PG8_MMA(0, 1, At, B1); PG8_BAR; PG8_SCHED;
;             PG8_LDA(At, 1, 1); PG8_STAGE(PG8_SB(1, 0), b3, voffB); PG8_STAGE(PG8_SB(1, 1), b3 + hstep, voffB); PG8_STAGE(PG8_SA(1, 0), a3, voffA);
;             PG8_WAIT_V(8); PG8_WAIT_L(0); PG8_BAR; PG8_MMA(1, 0, At, B0); PG8_MMA(1, 1, At, B1); PG8_BAR; PG8_SCHED;
;         }
;         if (wr == 0) PG8_BAR;
	s_add_i32 s77, 0, 0x18000
	s_add_i32 s78, 0, 0x1c000
	v_add_u32_e32 v164, s77, v148
	v_add_u32_e32 v180, s78, v148
	s_add_u32 s38, s38, 0x80000
	s_addc_u32 s39, s39, 0
	s_mov_b32 m0, s51
	s_nop 0
	global_load_lds_dwordx4 v128, s[38:39]
	s_mov_b32 m0, s52
	s_nop 0
	global_load_lds_dwordx4 v132, s[38:39]
	ds_read_b128 v[152:155], v164
	ds_read_b128 v[156:159], v164 offset:1024
	ds_read_b128 v[160:163], v164 offset:2048
	ds_read_b128 v[164:167], v164 offset:3072
	ds_read_b128 v[168:171], v180
	ds_read_b128 v[172:175], v180 offset:1024
	ds_read_b128 v[176:179], v180 offset:2048
	ds_read_b128 v[180:183], v180 offset:3072
	ds_read_b128 v[184:187], v151 offset:32768
	ds_read_b128 v[188:191], v151 offset:33792
	ds_read_b128 v[192:195], v151 offset:34816
	ds_read_b128 v[196:199], v151 offset:35840
	ds_read_b128 v[200:203], v151 offset:36864
	ds_read_b128 v[204:207], v151 offset:37888
	ds_read_b128 v[208:211], v151 offset:38912
	ds_read_b128 v[212:215], v151 offset:39936
	s_waitcnt vmcnt(8)
	s_waitcnt lgkmcnt(0)
	s_barrier
	s_setprio 1
	s_waitcnt lgkmcnt(0)
	v_mfma_f32_16x16x32_bf16 v[124:127], v[152:155], v[184:187], v[124:127]
	v_mfma_f32_16x16x32_bf16 v[120:123], v[160:163], v[184:187], v[120:123]
	v_mfma_f32_16x16x32_bf16 v[108:111], v[152:155], v[192:195], v[108:111]
	v_mfma_f32_16x16x32_bf16 v[104:107], v[160:163], v[192:195], v[104:107]
	v_mfma_f32_16x16x32_bf16 v[92:95], v[152:155], v[200:203], v[92:95]
	v_mfma_f32_16x16x32_bf16 v[88:91], v[160:163], v[200:203], v[88:91]
	v_mfma_f32_16x16x32_bf16 v[76:79], v[152:155], v[208:211], v[76:79]
	v_mfma_f32_16x16x32_bf16 v[72:75], v[160:163], v[208:211], v[72:75]
	v_mfma_f32_16x16x32_bf16 v[124:127], v[156:159], v[188:191], v[124:127]
	v_mfma_f32_16x16x32_bf16 v[120:123], v[164:167], v[188:191], v[120:123]
	v_mfma_f32_16x16x32_bf16 v[108:111], v[156:159], v[196:199], v[108:111]
	v_mfma_f32_16x16x32_bf16 v[104:107], v[164:167], v[196:199], v[104:107]
	v_mfma_f32_16x16x32_bf16 v[92:95], v[156:159], v[204:207], v[92:95]
	v_mfma_f32_16x16x32_bf16 v[88:91], v[164:167], v[204:207], v[88:91]
	v_mfma_f32_16x16x32_bf16 v[76:79], v[156:159], v[212:215], v[76:79]
	v_mfma_f32_16x16x32_bf16 v[72:75], v[164:167], v[212:215], v[72:75]
	s_setprio 0
	s_setprio 1
	v_mfma_f32_16x16x32_bf16 v[116:119], v[168:171], v[184:187], v[116:119]
	v_mfma_f32_16x16x32_bf16 v[112:115], v[176:179], v[184:187], v[112:115]
	v_mfma_f32_16x16x32_bf16 v[100:103], v[168:171], v[192:195], v[100:103]
	v_mfma_f32_16x16x32_bf16 v[96:99], v[176:179], v[192:195], v[96:99]
	v_mfma_f32_16x16x32_bf16 v[84:87], v[168:171], v[200:203], v[84:87]
	v_mfma_f32_16x16x32_bf16 v[80:83], v[176:179], v[200:203], v[80:83]
	v_mfma_f32_16x16x32_bf16 v[68:71], v[168:171], v[208:211], v[68:71]
	v_mfma_f32_16x16x32_bf16 v[64:67], v[176:179], v[208:211], v[64:67]
	v_mfma_f32_16x16x32_bf16 v[116:119], v[172:175], v[188:191], v[116:119]
	v_mfma_f32_16x16x32_bf16 v[112:115], v[180:183], v[188:191], v[112:115]
	v_mfma_f32_16x16x32_bf16 v[100:103], v[172:175], v[196:199], v[100:103]
	v_mfma_f32_16x16x32_bf16 v[96:99], v[180:183], v[196:199], v[96:99]
	v_mfma_f32_16x16x32_bf16 v[84:87], v[172:175], v[204:207], v[84:87]
	v_mfma_f32_16x16x32_bf16 v[80:83], v[180:183], v[204:207], v[80:83]
	v_mfma_f32_16x16x32_bf16 v[68:71], v[172:175], v[212:215], v[68:71]
	v_mfma_f32_16x16x32_bf16 v[64:67], v[180:183], v[212:215], v[64:67]
	s_setprio 0
	s_barrier
	s_add_i32 s38, s77, s49
	s_add_u32 s36, s36, 0x80
	s_addc_u32 s37, s37, 0
	s_mov_b32 m0, s38
	s_nop 0
	global_load_lds_dwordx4 v130, s[36:37]
	s_add_i32 m0, s38, 0x2000
	s_add_i32 s38, s78, s49
	global_load_lds_dwordx4 v134, s[36:37]
	s_add_u32 s36, s36, 0x80000
	s_addc_u32 s37, s37, 0
	s_mov_b32 m0, s38
	s_nop 0
	global_load_lds_dwordx4 v130, s[36:37]
	s_add_i32 m0, s38, 0x2000
	s_nop 0
	global_load_lds_dwordx4 v134, s[36:37]
	s_mov_b32 m0, s59
	s_nop 0
	global_load_lds_dwordx4 v128, s[100:101]
	s_mov_b32 m0, s60
	s_nop 0
	global_load_lds_dwordx4 v132, s[100:101]
	ds_read_b128 v[184:187], v151 offset:49152
	ds_read_b128 v[188:191], v151 offset:50176
	ds_read_b128 v[192:195], v151 offset:51200
	ds_read_b128 v[196:199], v151 offset:52224
	ds_read_b128 v[200:203], v151 offset:53248
	ds_read_b128 v[204:207], v151 offset:54272
	ds_read_b128 v[208:211], v151 offset:55296
	ds_read_b128 v[212:215], v151 offset:56320
	s_waitcnt vmcnt(8)
	s_waitcnt lgkmcnt(0)
	s_barrier
	s_setprio 1
	s_waitcnt lgkmcnt(0)
	v_mfma_f32_16x16x32_bf16 v[60:63], v[152:155], v[184:187], v[60:63]
	v_mfma_f32_16x16x32_bf16 v[56:59], v[160:163], v[184:187], v[56:59]
	v_mfma_f32_16x16x32_bf16 v[44:47], v[152:155], v[192:195], v[44:47]
	v_mfma_f32_16x16x32_bf16 v[40:43], v[160:163], v[192:195], v[40:43]
	v_mfma_f32_16x16x32_bf16 v[28:31], v[152:155], v[200:203], v[28:31]
	v_mfma_f32_16x16x32_bf16 v[24:27], v[160:163], v[200:203], v[24:27]
	v_mfma_f32_16x16x32_bf16 v[12:15], v[152:155], v[208:211], v[12:15]
	v_mfma_f32_16x16x32_bf16 v[8:11], v[160:163], v[208:211], v[8:11]
	v_mfma_f32_16x16x32_bf16 v[60:63], v[156:159], v[188:191], v[60:63]
	v_mfma_f32_16x16x32_bf16 v[56:59], v[164:167], v[188:191], v[56:59]
	v_mfma_f32_16x16x32_bf16 v[44:47], v[156:159], v[196:199], v[44:47]
	v_mfma_f32_16x16x32_bf16 v[40:43], v[164:167], v[196:199], v[40:43]
	v_mfma_f32_16x16x32_bf16 v[28:31], v[156:159], v[204:207], v[28:31]
	v_mfma_f32_16x16x32_bf16 v[24:27], v[164:167], v[204:207], v[24:27]
	v_mfma_f32_16x16x32_bf16 v[12:15], v[156:159], v[212:215], v[12:15]
	v_mfma_f32_16x16x32_bf16 v[8:11], v[164:167], v[212:215], v[8:11]
	s_setprio 0
	s_setprio 1
	v_mfma_f32_16x16x32_bf16 v[52:55], v[168:171], v[184:187], v[52:55]
	v_mfma_f32_16x16x32_bf16 v[48:51], v[176:179], v[184:187], v[48:51]
	v_mfma_f32_16x16x32_bf16 v[36:39], v[168:171], v[192:195], v[36:39]
	v_mfma_f32_16x16x32_bf16 v[32:35], v[176:179], v[192:195], v[32:35]
	v_mfma_f32_16x16x32_bf16 v[20:23], v[168:171], v[200:203], v[20:23]
	v_mfma_f32_16x16x32_bf16 v[16:19], v[176:179], v[200:203], v[16:19]
	v_mfma_f32_16x16x32_bf16 v[4:7], v[168:171], v[208:211], v[4:7]
	v_mfma_f32_16x16x32_bf16 v[0:3], v[176:179], v[208:211], v[0:3]
	v_mfma_f32_16x16x32_bf16 v[52:55], v[172:175], v[188:191], v[52:55]
	v_mfma_f32_16x16x32_bf16 v[48:51], v[180:183], v[188:191], v[48:51]
	v_mfma_f32_16x16x32_bf16 v[36:39], v[172:175], v[196:199], v[36:39]
	v_mfma_f32_16x16x32_bf16 v[32:35], v[180:183], v[196:199], v[32:35]
	v_mfma_f32_16x16x32_bf16 v[20:23], v[172:175], v[204:207], v[20:23]
	v_mfma_f32_16x16x32_bf16 v[16:19], v[180:183], v[204:207], v[16:19]
	v_mfma_f32_16x16x32_bf16 v[4:7], v[172:175], v[212:215], v[4:7]
	v_mfma_f32_16x16x32_bf16 v[0:3], v[180:183], v[212:215], v[0:3]
	s_setprio 0
	s_barrier
	s_add_i32 s76, s76, 2
	s_add_u32 s74, s74, 0x100
	s_addc_u32 s75, s75, 0
	s_add_u32 s34, s34, 0x100
	s_addc_u32 s35, s35, 0
	s_cmp_gt_u32 s76, 29
	s_cbranch_scc0 .LBB0_621
	s_and_b64 vcc, exec, s[8:9]
	s_cbranch_vccz .LBB0_624
	s_barrier

; #define PG8_STAGE(bufoff, gbase, voff) do { _Pragma("unroll") for (int _i = 0; _i < 2; ++_i) \
;         __builtin_amdgcn_global_load_lds((const unsigned*)((const char*)(gbase) + (voff)[_i]), (LAS unsigned*)(lds + (bufoff) + ldsw + _i * 8192), 16, 0, 0); } while (0)
; #define PG8_LDA(dst, b, h) do { _Pragma("unroll") for (int m = 0; m < 4; ++m) _Pragma("unroll") for (int k = 0; k < 2; ++k) dst[m][k] = *(const LAS bf16x8*)(lds + PG8_SA(b, h) + aoff + m * 2048 + k * 1024); } while (0)
; #define PG8_LDB(dst, b, h) do { _Pragma("unroll") for (int n = 0; n < 2; ++n) _Pragma("unroll") for (int k = 0; k < 2; ++k) dst[n][k] = *(const LAS bf16x8*)(lds + PG8_SB(b, h) + boff + n * 2048 + k * 1024); } while (0)
; #define PG8_MMA(ai, bj, At, Bt) do { __builtin_amdgcn_s_setprio(1); _Pragma("unroll") for (int m = 0; m < 4; ++m) _Pragma("unroll") for (int n = 0; n < 2; ++n) _Pragma("unroll") for (int k = 0; k < 2; ++k) \
;         acc[ai][bj][m][n] = __builtin_amdgcn_mfma_f32_16x16x32_bf16(Bt[n][k], At[m][k], acc[ai][bj][m][n], 0, 0, 0); __builtin_amdgcn_s_setprio(0); } while (0)
; #define PG8_WAIT_V(n) asm volatile("s_waitcnt vmcnt(" #n ")" ::: "memory")
; #define PG8_WAIT_L(n) asm volatile("s_waitcnt lgkmcnt(" #n ")" ::: "memory")
; #define PG8_BAR __builtin_amdgcn_s_barrier()
; #define PG8_SCHED __builtin_amdgcn_sched_barrier(0)
; template <class Epi>
; __device__ __forceinline__ void gemm_phase(ldsp lds, const Gemm g, const StaticOrder& S, const Epi& E, int wave0) {
;     ...
;         for (int t = 0; t < nt; t += 2) {
;             const bool last = (t == nt - 2);
;             const char* a1 = cA + (size_t)(t + 1) * kstep;
;             const char* a2 = last ? nA : cA + (size_t)(t + 2) * kstep; const char* b2 = last ? nB : cB + (size_t)(t + 2) * kstep;
;             const char* a3 = a2 + kstep; const char* b3 = b2 + kstep;
;             PG8_LDB(B0, 0, 0); PG8_LDB(B1, 0, 1); PG8_SCHED; PG8_LDA(At, 0, 0); PG8_STAGE(PG8_SA(1, 1), a1 + hstep, voffA);
;             PG8_WAIT_V(8); PG8_WAIT_L(0); PG8_BAR; PG8_MMA(0, 0, At, B0); PG8_MMA(0, 1, At, B1); PG8_BAR; PG8_SCHED;
;             PG8_LDA(At, 0, 1); PG8_STAGE(PG8_SB(0, 0), b2, voffB); PG8_STAGE(PG8_SB(0, 1), b2 + hstep, voffB); PG8_STAGE(PG8_SA(0, 0), a2, voffA);
;             PG8_WAIT_V(8); PG8_WAIT_L(0); PG8_BAR; PG8_MMA(1, 0, At, B0); PG8_MMA(1, 1, At, B1); PG8_BAR; PG8_SCHED;
.LBB0_689:
	s_add_u32 s38, s36, 0xfff80080
	s_addc_u32 s39, s37, -1
	s_cmp_eq_u32 s73, 28
	s_cselect_b32 s41, s27, s39
	s_cselect_b32 s40, s69, s38
	s_cselect_b32 s39, s25, s72
	s_cselect_b32 s38, s70, s71
	s_add_i32 m0, s35, 0xc000
	s_nop 0
	global_load_lds_dwordx4 v138, s[36:37]
	s_add_i32 m0, s35, 0xe000
	s_nop 0
	global_load_lds_dwordx4 v136, s[36:37]
	ds_read_b128 v[152:155], v149
	ds_read_b128 v[156:159], v149 offset:1024
	ds_read_b128 v[160:163], v149 offset:2048
	ds_read_b128 v[164:167], v149 offset:3072
	ds_read_b128 v[168:171], v150
	ds_read_b128 v[172:175], v150 offset:1024
	ds_read_b128 v[176:179], v150 offset:2048
	ds_read_b128 v[180:183], v150 offset:3072
	ds_read_b128 v[184:187], v151
	ds_read_b128 v[188:191], v151 offset:1024
	ds_read_b128 v[192:195], v151 offset:2048
	ds_read_b128 v[196:199], v151 offset:3072
	ds_read_b128 v[200:203], v151 offset:4096
	ds_read_b128 v[204:207], v151 offset:5120
	ds_read_b128 v[208:211], v151 offset:6144
	ds_read_b128 v[212:215], v151 offset:7168
	s_waitcnt vmcnt(8)
	s_waitcnt lgkmcnt(0)
	s_barrier
	s_setprio 1
	s_waitcnt lgkmcnt(0)
	v_mfma_f32_16x16x32_bf16 v[124:127], v[152:155], v[184:187], v[124:127]
	v_mfma_f32_16x16x32_bf16 v[120:123], v[160:163], v[184:187], v[120:123]
	v_mfma_f32_16x16x32_bf16 v[112:115], v[152:155], v[192:195], v[112:115]
	v_mfma_f32_16x16x32_bf16 v[104:107], v[160:163], v[192:195], v[104:107]
	v_mfma_f32_16x16x32_bf16 v[96:99], v[152:155], v[200:203], v[96:99]
	v_mfma_f32_16x16x32_bf16 v[88:91], v[160:163], v[200:203], v[88:91]
	v_mfma_f32_16x16x32_bf16 v[80:83], v[152:155], v[208:211], v[80:83]
	v_mfma_f32_16x16x32_bf16 v[72:75], v[160:163], v[208:211], v[72:75]
	v_mfma_f32_16x16x32_bf16 v[124:127], v[156:159], v[188:191], v[124:127]
	v_mfma_f32_16x16x32_bf16 v[120:123], v[164:167], v[188:191], v[120:123]
	v_mfma_f32_16x16x32_bf16 v[112:115], v[156:159], v[196:199], v[112:115]
	v_mfma_f32_16x16x32_bf16 v[104:107], v[164:167], v[196:199], v[104:107]
	v_mfma_f32_16x16x32_bf16 v[96:99], v[156:159], v[204:207], v[96:99]
	v_mfma_f32_16x16x32_bf16 v[88:91], v[164:167], v[204:207], v[88:91]
	v_mfma_f32_16x16x32_bf16 v[80:83], v[156:159], v[212:215], v[80:83]
	v_mfma_f32_16x16x32_bf16 v[72:75], v[164:167], v[212:215], v[72:75]
	s_setprio 0
	s_setprio 1
	v_mfma_f32_16x16x32_bf16 v[116:119], v[168:171], v[184:187], v[116:119]
	v_mfma_f32_16x16x32_bf16 v[108:111], v[176:179], v[184:187], v[108:111]
	v_mfma_f32_16x16x32_bf16 v[100:103], v[168:171], v[192:195], v[100:103]
	v_mfma_f32_16x16x32_bf16 v[92:95], v[176:179], v[192:195], v[92:95]
	v_mfma_f32_16x16x32_bf16 v[84:87], v[168:171], v[200:203], v[84:87]
	v_mfma_f32_16x16x32_bf16 v[76:79], v[176:179], v[200:203], v[76:79]
	v_mfma_f32_16x16x32_bf16 v[68:71], v[168:171], v[208:211], v[68:71]
	v_mfma_f32_16x16x32_bf16 v[64:67], v[176:179], v[208:211], v[64:67]
	v_mfma_f32_16x16x32_bf16 v[116:119], v[172:175], v[188:191], v[116:119]
	v_mfma_f32_16x16x32_bf16 v[108:111], v[180:183], v[188:191], v[108:111]
	v_mfma_f32_16x16x32_bf16 v[100:103], v[172:175], v[196:199], v[100:103]
	v_mfma_f32_16x16x32_bf16 v[92:95], v[180:183], v[196:199], v[92:95]
	v_mfma_f32_16x16x32_bf16 v[84:87], v[172:175], v[204:207], v[84:87]
	v_mfma_f32_16x16x32_bf16 v[76:79], v[180:183], v[204:207], v[76:79]
	v_mfma_f32_16x16x32_bf16 v[68:71], v[172:175], v[212:215], v[68:71]
	v_mfma_f32_16x16x32_bf16 v[64:67], v[180:183], v[212:215], v[64:67]
	s_setprio 0
	s_barrier
	s_add_i32 s74, s60, s49
	s_add_u32 s100, s40, 0x80
	s_addc_u32 s101, s41, 0
	s_mov_b32 m0, s74
	s_nop 0
	global_load_lds_dwordx4 v130, s[38:39]
	s_add_i32 m0, s74, 0x2000
	s_add_u32 s74, s38, 0x80000
	s_addc_u32 s75, s39, 0
	s_add_i32 s76, s61, s49
	global_load_lds_dwordx4 v134, s[38:39]
	s_mov_b32 m0, s76
	s_nop 0
	global_load_lds_dwordx4 v130, s[74:75]
	s_add_i32 m0, s76, 0x2000
	s_nop 0
	global_load_lds_dwordx4 v134, s[74:75]
	s_mov_b32 m0, s35
	s_nop 0
	global_load_lds_dwordx4 v128, s[40:41]
	s_mov_b32 m0, s50
	s_nop 0
	global_load_lds_dwordx4 v132, s[40:41]
	ds_read_b128 v[184:187], v151 offset:16384
	ds_read_b128 v[188:191], v151 offset:17408
	ds_read_b128 v[192:195], v151 offset:18432
	ds_read_b128 v[196:199], v151 offset:19456
	ds_read_b128 v[200:203], v151 offset:20480
	ds_read_b128 v[204:207], v151 offset:21504
	ds_read_b128 v[208:211], v151 offset:22528
	ds_read_b128 v[212:215], v151 offset:23552
	s_waitcnt vmcnt(8)
	s_waitcnt lgkmcnt(0)
	s_barrier
	s_setprio 1
	s_waitcnt lgkmcnt(0)
	v_mfma_f32_16x16x32_bf16 v[60:63], v[152:155], v[184:187], v[60:63]
	v_mfma_f32_16x16x32_bf16 v[56:59], v[160:163], v[184:187], v[56:59]
	v_mfma_f32_16x16x32_bf16 v[48:51], v[152:155], v[192:195], v[48:51]
	v_mfma_f32_16x16x32_bf16 v[40:43], v[160:163], v[192:195], v[40:43]
	v_mfma_f32_16x16x32_bf16 v[32:35], v[152:155], v[200:203], v[32:35]
	v_mfma_f32_16x16x32_bf16 v[24:27], v[160:163], v[200:203], v[24:27]
	v_mfma_f32_16x16x32_bf16 v[16:19], v[152:155], v[208:211], v[16:19]
	v_mfma_f32_16x16x32_bf16 v[8:11], v[160:163], v[208:211], v[8:11]
	v_mfma_f32_16x16x32_bf16 v[60:63], v[156:159], v[188:191], v[60:63]
	v_mfma_f32_16x16x32_bf16 v[56:59], v[164:167], v[188:191], v[56:59]
	v_mfma_f32_16x16x32_bf16 v[48:51], v[156:159], v[196:199], v[48:51]
	v_mfma_f32_16x16x32_bf16 v[40:43], v[164:167], v[196:199], v[40:43]
	v_mfma_f32_16x16x32_bf16 v[32:35], v[156:159], v[204:207], v[32:35]
	v_mfma_f32_16x16x32_bf16 v[24:27], v[164:167], v[204:207], v[24:27]
	v_mfma_f32_16x16x32_bf16 v[16:19], v[156:159], v[212:215], v[16:19]
	v_mfma_f32_16x16x32_bf16 v[8:11], v[164:167], v[212:215], v[8:11]
	s_setprio 0
	s_setprio 1
	v_mfma_f32_16x16x32_bf16 v[52:55], v[168:171], v[184:187], v[52:55]
	v_mfma_f32_16x16x32_bf16 v[44:47], v[176:179], v[184:187], v[44:47]
	v_mfma_f32_16x16x32_bf16 v[36:39], v[168:171], v[192:195], v[36:39]
	v_mfma_f32_16x16x32_bf16 v[28:31], v[176:179], v[192:195], v[28:31]
	v_mfma_f32_16x16x32_bf16 v[20:23], v[168:171], v[200:203], v[20:23]
	v_mfma_f32_16x16x32_bf16 v[12:15], v[176:179], v[200:203], v[12:15]
	v_mfma_f32_16x16x32_bf16 v[4:7], v[168:171], v[208:211], v[4:7]
	v_mfma_f32_16x16x32_bf16 v[0:3], v[176:179], v[208:211], v[0:3]
	v_mfma_f32_16x16x32_bf16 v[52:55], v[172:175], v[188:191], v[52:55]
	v_mfma_f32_16x16x32_bf16 v[44:47], v[180:183], v[188:191], v[44:47]
	v_mfma_f32_16x16x32_bf16 v[36:39], v[172:175], v[196:199], v[36:39]
	v_mfma_f32_16x16x32_bf16 v[28:31], v[180:183], v[196:199], v[28:31]
	v_mfma_f32_16x16x32_bf16 v[20:23], v[172:175], v[204:207], v[20:23]
	v_mfma_f32_16x16x32_bf16 v[12:15], v[180:183], v[204:207], v[12:15]
	v_mfma_f32_16x16x32_bf16 v[4:7], v[172:175], v[212:215], v[4:7]
	v_mfma_f32_16x16x32_bf16 v[0:3], v[180:183], v[212:215], v[0:3]
	s_setprio 0
	s_barrier
; #define PG8_STAGE(bufoff, gbase, voff) do { _Pragma("unroll") for (int _i = 0; _i < 2; ++_i) \
;         __builtin_amdgcn_global_load_lds((const unsigned*)((const char*)(gbase) + (voff)[_i]), (LAS unsigned*)(lds + (bufoff) + ldsw + _i * 8192), 16, 0, 0); } while (0)
; #define PG8_LDA(dst, b, h) do { _Pragma("unroll") for (int m = 0; m < 4; ++m) _Pragma("unroll") for (int k = 0; k < 2; ++k) dst[m][k] = *(const LAS bf16x8*)(lds + PG8_SA(b, h) + aoff + m * 2048 + k * 1024); } while (0)
; #define PG8_LDB(dst, b, h) do { _Pragma("unroll") for (int n = 0; n < 2; ++n) _Pragma("unroll") for (int k = 0; k < 2; ++k) dst[n][k] = *(const LAS bf16x8*)(lds + PG8_SB(b, h) + boff + n * 2048 + k * 1024); } while (0)
; #define PG8_MMA(ai, bj, At, Bt) do { __builtin_amdgcn_s_setprio(1); _Pragma("unroll") for (int m = 0; m < 4; ++m) _Pragma("unroll") for (int n = 0; n < 2; ++n) _Pragma("unroll") for (int k = 0; k < 2; ++k) \
;         acc[ai][bj][m][n] = __builtin_amdgcn_mfma_f32_16x16x32_bf16(Bt[n][k], At[m][k], acc[ai][bj][m][n], 0, 0, 0); __builtin_amdgcn_s_setprio(0); } while (0)
; #define PG8_WAIT_V(n) asm volatile("s_waitcnt vmcnt(" #n ")" ::: "memory")
; #define PG8_WAIT_L(n) asm volatile("s_waitcnt lgkmcnt(" #n ")" ::: "memory")
; #define PG8_BAR __builtin_amdgcn_s_barrier()
; #define PG8_SCHED __builtin_amdgcn_sched_barrier(0)
; template <class Epi>
; __device__ __forceinline__ void gemm_phase(ldsp lds, const Gemm g, const StaticOrder& S, const Epi& E, int wave0) {
;     ...
;             PG8_LDB(B0, 1, 0); PG8_LDB(B1, 1, 1); PG8_SCHED; PG8_LDA(At, 1, 0); PG8_STAGE(PG8_SA(0, 1), a2 + hstep, voffA);
;             PG8_WAIT_V(8); PG8_WAIT_L(0); PG8_BAR; PG8_MMA(0, 0, At, B0); PG8_MMA(0, 1, At, B1); PG8_BAR; PG8_SCHED;
;             PG8_LDA(At, 1, 1); PG8_STAGE(PG8_SB(1, 0), b3, voffB); PG8_STAGE(PG8_SB(1, 1), b3 + hstep, voffB); PG8_STAGE(PG8_SA(1, 0), a3, voffA);
;             PG8_WAIT_V(8); PG8_WAIT_L(0); PG8_BAR; PG8_MMA(1, 0, At, B0); PG8_MMA(1, 1, At, B1); PG8_BAR; PG8_SCHED;
;         }
;         if (wr == 0) PG8_BAR;
	s_add_i32 s74, 0, 0x18000
	s_add_i32 s75, 0, 0x1c000
	v_add_u32_e32 v164, s74, v148
	v_add_u32_e32 v180, s75, v148
	s_add_u32 s40, s40, 0x80000
	s_addc_u32 s41, s41, 0
	s_mov_b32 m0, s51
	s_nop 0
	global_load_lds_dwordx4 v128, s[40:41]
	s_mov_b32 m0, s52
	s_nop 0
	global_load_lds_dwordx4 v132, s[40:41]
	ds_read_b128 v[152:155], v164
	ds_read_b128 v[156:159], v164 offset:1024
	ds_read_b128 v[160:163], v164 offset:2048
	ds_read_b128 v[164:167], v164 offset:3072
	ds_read_b128 v[168:171], v180
	ds_read_b128 v[172:175], v180 offset:1024
	ds_read_b128 v[176:179], v180 offset:2048
	ds_read_b128 v[180:183], v180 offset:3072
	ds_read_b128 v[184:187], v151 offset:32768
	ds_read_b128 v[188:191], v151 offset:33792
	ds_read_b128 v[192:195], v151 offset:34816
	ds_read_b128 v[196:199], v151 offset:35840
	ds_read_b128 v[200:203], v151 offset:36864
	ds_read_b128 v[204:207], v151 offset:37888
	ds_read_b128 v[208:211], v151 offset:38912
	ds_read_b128 v[212:215], v151 offset:39936
	s_waitcnt vmcnt(8)
	s_waitcnt lgkmcnt(0)
	s_barrier
	s_setprio 1
	s_waitcnt lgkmcnt(0)
	v_mfma_f32_16x16x32_bf16 v[124:127], v[152:155], v[184:187], v[124:127]
	v_mfma_f32_16x16x32_bf16 v[120:123], v[160:163], v[184:187], v[120:123]
	v_mfma_f32_16x16x32_bf16 v[112:115], v[152:155], v[192:195], v[112:115]
	v_mfma_f32_16x16x32_bf16 v[104:107], v[160:163], v[192:195], v[104:107]
	v_mfma_f32_16x16x32_bf16 v[96:99], v[152:155], v[200:203], v[96:99]
	v_mfma_f32_16x16x32_bf16 v[88:91], v[160:163], v[200:203], v[88:91]
	v_mfma_f32_16x16x32_bf16 v[80:83], v[152:155], v[208:211], v[80:83]
	v_mfma_f32_16x16x32_bf16 v[72:75], v[160:163], v[208:211], v[72:75]
	v_mfma_f32_16x16x32_bf16 v[124:127], v[156:159], v[188:191], v[124:127]
	v_mfma_f32_16x16x32_bf16 v[120:123], v[164:167], v[188:191], v[120:123]
	v_mfma_f32_16x16x32_bf16 v[112:115], v[156:159], v[196:199], v[112:115]
	v_mfma_f32_16x16x32_bf16 v[104:107], v[164:167], v[196:199], v[104:107]
	v_mfma_f32_16x16x32_bf16 v[96:99], v[156:159], v[204:207], v[96:99]
	v_mfma_f32_16x16x32_bf16 v[88:91], v[164:167], v[204:207], v[88:91]
	v_mfma_f32_16x16x32_bf16 v[80:83], v[156:159], v[212:215], v[80:83]
	v_mfma_f32_16x16x32_bf16 v[72:75], v[164:167], v[212:215], v[72:75]
	s_setprio 0
	s_setprio 1
	v_mfma_f32_16x16x32_bf16 v[116:119], v[168:171], v[184:187], v[116:119]
	v_mfma_f32_16x16x32_bf16 v[108:111], v[176:179], v[184:187], v[108:111]
	v_mfma_f32_16x16x32_bf16 v[100:103], v[168:171], v[192:195], v[100:103]
	v_mfma_f32_16x16x32_bf16 v[92:95], v[176:179], v[192:195], v[92:95]
	v_mfma_f32_16x16x32_bf16 v[84:87], v[168:171], v[200:203], v[84:87]
	v_mfma_f32_16x16x32_bf16 v[76:79], v[176:179], v[200:203], v[76:79]
	v_mfma_f32_16x16x32_bf16 v[68:71], v[168:171], v[208:211], v[68:71]
	v_mfma_f32_16x16x32_bf16 v[64:67], v[176:179], v[208:211], v[64:67]
	v_mfma_f32_16x16x32_bf16 v[116:119], v[172:175], v[188:191], v[116:119]
	v_mfma_f32_16x16x32_bf16 v[108:111], v[180:183], v[188:191], v[108:111]
	v_mfma_f32_16x16x32_bf16 v[100:103], v[172:175], v[196:199], v[100:103]
	v_mfma_f32_16x16x32_bf16 v[92:95], v[180:183], v[196:199], v[92:95]
	v_mfma_f32_16x16x32_bf16 v[84:87], v[172:175], v[204:207], v[84:87]
	v_mfma_f32_16x16x32_bf16 v[76:79], v[180:183], v[204:207], v[76:79]
	v_mfma_f32_16x16x32_bf16 v[68:71], v[172:175], v[212:215], v[68:71]
	v_mfma_f32_16x16x32_bf16 v[64:67], v[180:183], v[212:215], v[64:67]
	s_setprio 0
	s_barrier
	s_add_i32 s40, s74, s49
	s_add_u32 s38, s38, 0x80
	s_addc_u32 s39, s39, 0
	s_mov_b32 m0, s40
	s_nop 0
	global_load_lds_dwordx4 v130, s[38:39]
	s_add_i32 m0, s40, 0x2000
	s_add_i32 s40, s75, s49
	global_load_lds_dwordx4 v134, s[38:39]
	s_add_u32 s38, s38, 0x80000
	s_addc_u32 s39, s39, 0
	s_mov_b32 m0, s40
	s_nop 0
	global_load_lds_dwordx4 v130, s[38:39]
	s_add_i32 m0, s40, 0x2000
	s_nop 0
	global_load_lds_dwordx4 v134, s[38:39]
	s_mov_b32 m0, s57
	s_nop 0
	global_load_lds_dwordx4 v128, s[100:101]
	s_mov_b32 m0, s58
	s_nop 0
	global_load_lds_dwordx4 v132, s[100:101]
	ds_read_b128 v[184:187], v151 offset:49152
	ds_read_b128 v[188:191], v151 offset:50176
	ds_read_b128 v[192:195], v151 offset:51200
	ds_read_b128 v[196:199], v151 offset:52224
	ds_read_b128 v[200:203], v151 offset:53248
	ds_read_b128 v[204:207], v151 offset:54272
	ds_read_b128 v[208:211], v151 offset:55296
	ds_read_b128 v[212:215], v151 offset:56320
	s_waitcnt vmcnt(8)
	s_waitcnt lgkmcnt(0)
	s_barrier
	s_setprio 1
	s_waitcnt lgkmcnt(0)
	v_mfma_f32_16x16x32_bf16 v[60:63], v[152:155], v[184:187], v[60:63]
	v_mfma_f32_16x16x32_bf16 v[56:59], v[160:163], v[184:187], v[56:59]
	v_mfma_f32_16x16x32_bf16 v[48:51], v[152:155], v[192:195], v[48:51]
	v_mfma_f32_16x16x32_bf16 v[40:43], v[160:163], v[192:195], v[40:43]
	v_mfma_f32_16x16x32_bf16 v[32:35], v[152:155], v[200:203], v[32:35]
	v_mfma_f32_16x16x32_bf16 v[24:27], v[160:163], v[200:203], v[24:27]
	v_mfma_f32_16x16x32_bf16 v[16:19], v[152:155], v[208:211], v[16:19]
	v_mfma_f32_16x16x32_bf16 v[8:11], v[160:163], v[208:211], v[8:11]
	v_mfma_f32_16x16x32_bf16 v[60:63], v[156:159], v[188:191], v[60:63]
	v_mfma_f32_16x16x32_bf16 v[56:59], v[164:167], v[188:191], v[56:59]
	v_mfma_f32_16x16x32_bf16 v[48:51], v[156:159], v[196:199], v[48:51]
	v_mfma_f32_16x16x32_bf16 v[40:43], v[164:167], v[196:199], v[40:43]
	v_mfma_f32_16x16x32_bf16 v[32:35], v[156:159], v[204:207], v[32:35]
	v_mfma_f32_16x16x32_bf16 v[24:27], v[164:167], v[204:207], v[24:27]
	v_mfma_f32_16x16x32_bf16 v[16:19], v[156:159], v[212:215], v[16:19]
	v_mfma_f32_16x16x32_bf16 v[8:11], v[164:167], v[212:215], v[8:11]
	s_setprio 0
	s_setprio 1
	v_mfma_f32_16x16x32_bf16 v[52:55], v[168:171], v[184:187], v[52:55]
	v_mfma_f32_16x16x32_bf16 v[44:47], v[176:179], v[184:187], v[44:47]
	v_mfma_f32_16x16x32_bf16 v[36:39], v[168:171], v[192:195], v[36:39]
	v_mfma_f32_16x16x32_bf16 v[28:31], v[176:179], v[192:195], v[28:31]
	v_mfma_f32_16x16x32_bf16 v[20:23], v[168:171], v[200:203], v[20:23]
	v_mfma_f32_16x16x32_bf16 v[12:15], v[176:179], v[200:203], v[12:15]
	v_mfma_f32_16x16x32_bf16 v[4:7], v[168:171], v[208:211], v[4:7]
	v_mfma_f32_16x16x32_bf16 v[0:3], v[176:179], v[208:211], v[0:3]
	v_mfma_f32_16x16x32_bf16 v[52:55], v[172:175], v[188:191], v[52:55]
	v_mfma_f32_16x16x32_bf16 v[44:47], v[180:183], v[188:191], v[44:47]
	v_mfma_f32_16x16x32_bf16 v[36:39], v[172:175], v[196:199], v[36:39]
	v_mfma_f32_16x16x32_bf16 v[28:31], v[180:183], v[196:199], v[28:31]
	v_mfma_f32_16x16x32_bf16 v[20:23], v[172:175], v[204:207], v[20:23]
	v_mfma_f32_16x16x32_bf16 v[12:15], v[180:183], v[204:207], v[12:15]
	v_mfma_f32_16x16x32_bf16 v[4:7], v[172:175], v[212:215], v[4:7]
	v_mfma_f32_16x16x32_bf16 v[0:3], v[180:183], v[212:215], v[0:3]
	s_setprio 0
	s_barrier
	s_add_i32 s73, s73, 2
	s_add_u32 s71, s71, 0x100
	s_addc_u32 s72, s72, 0
	s_add_u32 s36, s36, 0x100
	s_addc_u32 s37, s37, 0
	s_cmp_gt_u32 s73, 29
	s_cbranch_scc0 .LBB0_689
	s_and_b64 vcc, exec, s[10:11]
	s_cbranch_vccz .LBB0_692
	s_barrier

; #define PG8_STAGE(bufoff, gbase, voff) do { _Pragma("unroll") for (int _i = 0; _i < 2; ++_i) \
;         __builtin_amdgcn_global_load_lds((const unsigned*)((const char*)(gbase) + (voff)[_i]), (LAS unsigned*)(lds + (bufoff) + ldsw + _i * 8192), 16, 0, 0); } while (0)
; #define PG8_LDA(dst, b, h) do { _Pragma("unroll") for (int m = 0; m < 4; ++m) _Pragma("unroll") for (int k = 0; k < 2; ++k) dst[m][k] = *(const LAS bf16x8*)(lds + PG8_SA(b, h) + aoff + m * 2048 + k * 1024); } while (0)
; #define PG8_LDB(dst, b, h) do { _Pragma("unroll") for (int n = 0; n < 2; ++n) _Pragma("unroll") for (int k = 0; k < 2; ++k) dst[n][k] = *(const LAS bf16x8*)(lds + PG8_SB(b, h) + boff + n * 2048 + k * 1024); } while (0)
; #define PG8_MMA(ai, bj, At, Bt) do { __builtin_amdgcn_s_setprio(1); _Pragma("unroll") for (int m = 0; m < 4; ++m) _Pragma("unroll") for (int n = 0; n < 2; ++n) _Pragma("unroll") for (int k = 0; k < 2; ++k) \
;         acc[ai][bj][m][n] = __builtin_amdgcn_mfma_f32_16x16x32_bf16(Bt[n][k], At[m][k], acc[ai][bj][m][n], 0, 0, 0); __builtin_amdgcn_s_setprio(0); } while (0)
; #define PG8_WAIT_V(n) asm volatile("s_waitcnt vmcnt(" #n ")" ::: "memory")
; #define PG8_WAIT_L(n) asm volatile("s_waitcnt lgkmcnt(" #n ")" ::: "memory")
; #define PG8_BAR __builtin_amdgcn_s_barrier()
; #define PG8_SCHED __builtin_amdgcn_sched_barrier(0)
; template <class Epi>
; __device__ __forceinline__ void gemm_phase(ldsp lds, const Gemm g, const StaticOrder& S, const Epi& E, int wave0) {
;     ...
;         for (int t = 0; t < nt; t += 2) {
;             const bool last = (t == nt - 2);
;             const char* a1 = cA + (size_t)(t + 1) * kstep;
;             const char* a2 = last ? nA : cA + (size_t)(t + 2) * kstep; const char* b2 = last ? nB : cB + (size_t)(t + 2) * kstep;
;             const char* a3 = a2 + kstep; const char* b3 = b2 + kstep;
;             PG8_LDB(B0, 0, 0); PG8_LDB(B1, 0, 1); PG8_SCHED; PG8_LDA(At, 0, 0); PG8_STAGE(PG8_SA(1, 1), a1 + hstep, voffA);
;             PG8_WAIT_V(8); PG8_WAIT_L(0); PG8_BAR; PG8_MMA(0, 0, At, B0); PG8_MMA(0, 1, At, B1); PG8_BAR; PG8_SCHED;
;             PG8_LDA(At, 0, 1); PG8_STAGE(PG8_SB(0, 0), b2, voffB); PG8_STAGE(PG8_SB(0, 1), b2 + hstep, voffB); PG8_STAGE(PG8_SA(0, 0), a2, voffA);
;             PG8_WAIT_V(8); PG8_WAIT_L(0); PG8_BAR; PG8_MMA(1, 0, At, B0); PG8_MMA(1, 1, At, B1); PG8_BAR; PG8_SCHED;
.LBB0_713:
	s_add_u32 s40, s38, 0xfffc0080
	s_addc_u32 s41, s39, -1
	s_cmp_eq_u32 s66, 12
	s_cselect_b32 s43, s29, s41
	s_cselect_b32 s42, s62, s40
	s_cselect_b32 s41, s27, s65
	s_cselect_b32 s40, s63, s64
	s_add_i32 m0, s37, 0xc000
	s_nop 0
	global_load_lds_dwordx4 v138, s[38:39]
	s_add_i32 m0, s37, 0xe000
	s_nop 0
	global_load_lds_dwordx4 v136, s[38:39]
	ds_read_b128 v[152:155], v149
	ds_read_b128 v[156:159], v149 offset:1024
	ds_read_b128 v[160:163], v149 offset:2048
	ds_read_b128 v[164:167], v149 offset:3072
	ds_read_b128 v[168:171], v150
	ds_read_b128 v[172:175], v150 offset:1024
	ds_read_b128 v[176:179], v150 offset:2048
	ds_read_b128 v[180:183], v150 offset:3072
	ds_read_b128 v[184:187], v151
	ds_read_b128 v[188:191], v151 offset:1024
	ds_read_b128 v[192:195], v151 offset:2048
	ds_read_b128 v[196:199], v151 offset:3072
	ds_read_b128 v[200:203], v151 offset:4096
	ds_read_b128 v[204:207], v151 offset:5120
	ds_read_b128 v[208:211], v151 offset:6144
	ds_read_b128 v[212:215], v151 offset:7168
	s_waitcnt vmcnt(8)
	s_waitcnt lgkmcnt(0)
	s_barrier
	s_setprio 1
	s_waitcnt lgkmcnt(0)
	v_mfma_f32_16x16x32_bf16 v[124:127], v[152:155], v[184:187], v[124:127]
	v_mfma_f32_16x16x32_bf16 v[120:123], v[160:163], v[184:187], v[120:123]
	v_mfma_f32_16x16x32_bf16 v[108:111], v[152:155], v[192:195], v[108:111]
	v_mfma_f32_16x16x32_bf16 v[104:107], v[160:163], v[192:195], v[104:107]
	v_mfma_f32_16x16x32_bf16 v[92:95], v[152:155], v[200:203], v[92:95]
	v_mfma_f32_16x16x32_bf16 v[88:91], v[160:163], v[200:203], v[88:91]
	v_mfma_f32_16x16x32_bf16 v[76:79], v[152:155], v[208:211], v[76:79]
	v_mfma_f32_16x16x32_bf16 v[72:75], v[160:163], v[208:211], v[72:75]
	v_mfma_f32_16x16x32_bf16 v[124:127], v[156:159], v[188:191], v[124:127]
	v_mfma_f32_16x16x32_bf16 v[120:123], v[164:167], v[188:191], v[120:123]
	v_mfma_f32_16x16x32_bf16 v[108:111], v[156:159], v[196:199], v[108:111]
	v_mfma_f32_16x16x32_bf16 v[104:107], v[164:167], v[196:199], v[104:107]
	v_mfma_f32_16x16x32_bf16 v[92:95], v[156:159], v[204:207], v[92:95]
	v_mfma_f32_16x16x32_bf16 v[88:91], v[164:167], v[204:207], v[88:91]
	v_mfma_f32_16x16x32_bf16 v[76:79], v[156:159], v[212:215], v[76:79]
	v_mfma_f32_16x16x32_bf16 v[72:75], v[164:167], v[212:215], v[72:75]
	s_setprio 0
	s_setprio 1
	v_mfma_f32_16x16x32_bf16 v[116:119], v[168:171], v[184:187], v[116:119]
	v_mfma_f32_16x16x32_bf16 v[112:115], v[176:179], v[184:187], v[112:115]
	v_mfma_f32_16x16x32_bf16 v[100:103], v[168:171], v[192:195], v[100:103]
	v_mfma_f32_16x16x32_bf16 v[96:99], v[176:179], v[192:195], v[96:99]
	v_mfma_f32_16x16x32_bf16 v[84:87], v[168:171], v[200:203], v[84:87]
	v_mfma_f32_16x16x32_bf16 v[80:83], v[176:179], v[200:203], v[80:83]
	v_mfma_f32_16x16x32_bf16 v[68:71], v[168:171], v[208:211], v[68:71]
	v_mfma_f32_16x16x32_bf16 v[64:67], v[176:179], v[208:211], v[64:67]
	v_mfma_f32_16x16x32_bf16 v[116:119], v[172:175], v[188:191], v[116:119]
	v_mfma_f32_16x16x32_bf16 v[112:115], v[180:183], v[188:191], v[112:115]
	v_mfma_f32_16x16x32_bf16 v[100:103], v[172:175], v[196:199], v[100:103]
	v_mfma_f32_16x16x32_bf16 v[96:99], v[180:183], v[196:199], v[96:99]
	v_mfma_f32_16x16x32_bf16 v[84:87], v[172:175], v[204:207], v[84:87]
	v_mfma_f32_16x16x32_bf16 v[80:83], v[180:183], v[204:207], v[80:83]
	v_mfma_f32_16x16x32_bf16 v[68:71], v[172:175], v[212:215], v[68:71]
	v_mfma_f32_16x16x32_bf16 v[64:67], v[180:183], v[212:215], v[64:67]
	s_setprio 0
	s_barrier
	s_add_i32 s67, s59, s49
	s_add_u32 s100, s42, 0x80
	s_addc_u32 s101, s43, 0
	s_mov_b32 m0, s67
	s_nop 0
	global_load_lds_dwordx4 v130, s[40:41]
	s_add_i32 m0, s67, 0x2000
	s_add_u32 s68, s40, 0x40000
	s_addc_u32 s69, s41, 0
	s_add_i32 s67, s60, s49
	global_load_lds_dwordx4 v134, s[40:41]
	s_mov_b32 m0, s67
	s_nop 0
	global_load_lds_dwordx4 v130, s[68:69]
	s_add_i32 m0, s67, 0x2000
	s_nop 0
	global_load_lds_dwordx4 v134, s[68:69]
	s_mov_b32 m0, s37
	s_nop 0
	global_load_lds_dwordx4 v128, s[42:43]
	s_mov_b32 m0, s50
	s_nop 0
	global_load_lds_dwordx4 v132, s[42:43]
	ds_read_b128 v[184:187], v151 offset:16384
	ds_read_b128 v[188:191], v151 offset:17408
	ds_read_b128 v[192:195], v151 offset:18432
	ds_read_b128 v[196:199], v151 offset:19456
	ds_read_b128 v[200:203], v151 offset:20480
	ds_read_b128 v[204:207], v151 offset:21504
	ds_read_b128 v[208:211], v151 offset:22528
	ds_read_b128 v[212:215], v151 offset:23552
	s_waitcnt vmcnt(8)
	s_waitcnt lgkmcnt(0)
	s_barrier
	s_setprio 1
	s_waitcnt lgkmcnt(0)
	v_mfma_f32_16x16x32_bf16 v[60:63], v[152:155], v[184:187], v[60:63]
	v_mfma_f32_16x16x32_bf16 v[56:59], v[160:163], v[184:187], v[56:59]
	v_mfma_f32_16x16x32_bf16 v[44:47], v[152:155], v[192:195], v[44:47]
	v_mfma_f32_16x16x32_bf16 v[40:43], v[160:163], v[192:195], v[40:43]
	v_mfma_f32_16x16x32_bf16 v[28:31], v[152:155], v[200:203], v[28:31]
	v_mfma_f32_16x16x32_bf16 v[24:27], v[160:163], v[200:203], v[24:27]
	v_mfma_f32_16x16x32_bf16 v[12:15], v[152:155], v[208:211], v[12:15]
	v_mfma_f32_16x16x32_bf16 v[8:11], v[160:163], v[208:211], v[8:11]
	v_mfma_f32_16x16x32_bf16 v[60:63], v[156:159], v[188:191], v[60:63]
	v_mfma_f32_16x16x32_bf16 v[56:59], v[164:167], v[188:191], v[56:59]
	v_mfma_f32_16x16x32_bf16 v[44:47], v[156:159], v[196:199], v[44:47]
	v_mfma_f32_16x16x32_bf16 v[40:43], v[164:167], v[196:199], v[40:43]
	v_mfma_f32_16x16x32_bf16 v[28:31], v[156:159], v[204:207], v[28:31]
	v_mfma_f32_16x16x32_bf16 v[24:27], v[164:167], v[204:207], v[24:27]
	v_mfma_f32_16x16x32_bf16 v[12:15], v[156:159], v[212:215], v[12:15]
	v_mfma_f32_16x16x32_bf16 v[8:11], v[164:167], v[212:215], v[8:11]
	s_setprio 0
	s_setprio 1
	v_mfma_f32_16x16x32_bf16 v[52:55], v[168:171], v[184:187], v[52:55]
	v_mfma_f32_16x16x32_bf16 v[48:51], v[176:179], v[184:187], v[48:51]
	v_mfma_f32_16x16x32_bf16 v[36:39], v[168:171], v[192:195], v[36:39]
	v_mfma_f32_16x16x32_bf16 v[32:35], v[176:179], v[192:195], v[32:35]
	v_mfma_f32_16x16x32_bf16 v[20:23], v[168:171], v[200:203], v[20:23]
	v_mfma_f32_16x16x32_bf16 v[16:19], v[176:179], v[200:203], v[16:19]
	v_mfma_f32_16x16x32_bf16 v[4:7], v[168:171], v[208:211], v[4:7]
	v_mfma_f32_16x16x32_bf16 v[0:3], v[176:179], v[208:211], v[0:3]
	v_mfma_f32_16x16x32_bf16 v[52:55], v[172:175], v[188:191], v[52:55]
	v_mfma_f32_16x16x32_bf16 v[48:51], v[180:183], v[188:191], v[48:51]
	v_mfma_f32_16x16x32_bf16 v[36:39], v[172:175], v[196:199], v[36:39]
	v_mfma_f32_16x16x32_bf16 v[32:35], v[180:183], v[196:199], v[32:35]
	v_mfma_f32_16x16x32_bf16 v[20:23], v[172:175], v[204:207], v[20:23]
	v_mfma_f32_16x16x32_bf16 v[16:19], v[180:183], v[204:207], v[16:19]
	v_mfma_f32_16x16x32_bf16 v[4:7], v[172:175], v[212:215], v[4:7]
	v_mfma_f32_16x16x32_bf16 v[0:3], v[180:183], v[212:215], v[0:3]
	s_setprio 0
	s_barrier
; #define PG8_STAGE(bufoff, gbase, voff) do { _Pragma("unroll") for (int _i = 0; _i < 2; ++_i) \
;         __builtin_amdgcn_global_load_lds((const unsigned*)((const char*)(gbase) + (voff)[_i]), (LAS unsigned*)(lds + (bufoff) + ldsw + _i * 8192), 16, 0, 0); } while (0)
; #define PG8_LDA(dst, b, h) do { _Pragma("unroll") for (int m = 0; m < 4; ++m) _Pragma("unroll") for (int k = 0; k < 2; ++k) dst[m][k] = *(const LAS bf16x8*)(lds + PG8_SA(b, h) + aoff + m * 2048 + k * 1024); } while (0)
; #define PG8_LDB(dst, b, h) do { _Pragma("unroll") for (int n = 0; n < 2; ++n) _Pragma("unroll") for (int k = 0; k < 2; ++k) dst[n][k] = *(const LAS bf16x8*)(lds + PG8_SB(b, h) + boff + n * 2048 + k * 1024); } while (0)
; #define PG8_MMA(ai, bj, At, Bt) do { __builtin_amdgcn_s_setprio(1); _Pragma("unroll") for (int m = 0; m < 4; ++m) _Pragma("unroll") for (int n = 0; n < 2; ++n) _Pragma("unroll") for (int k = 0; k < 2; ++k) \
;         acc[ai][bj][m][n] = __builtin_amdgcn_mfma_f32_16x16x32_bf16(Bt[n][k], At[m][k], acc[ai][bj][m][n], 0, 0, 0); __builtin_amdgcn_s_setprio(0); } while (0)
; #define PG8_WAIT_V(n) asm volatile("s_waitcnt vmcnt(" #n ")" ::: "memory")
; #define PG8_WAIT_L(n) asm volatile("s_waitcnt lgkmcnt(" #n ")" ::: "memory")
; #define PG8_BAR __builtin_amdgcn_s_barrier()
; #define PG8_SCHED __builtin_amdgcn_sched_barrier(0)
; template <class Epi>
; __device__ __forceinline__ void gemm_phase(ldsp lds, const Gemm g, const StaticOrder& S, const Epi& E, int wave0) {
;     ...
;             PG8_LDB(B0, 1, 0); PG8_LDB(B1, 1, 1); PG8_SCHED; PG8_LDA(At, 1, 0); PG8_STAGE(PG8_SA(0, 1), a2 + hstep, voffA);
;             PG8_WAIT_V(8); PG8_WAIT_L(0); PG8_BAR; PG8_MMA(0, 0, At, B0); PG8_MMA(0, 1, At, B1); PG8_BAR; PG8_SCHED;
;             PG8_LDA(At, 1, 1); PG8_STAGE(PG8_SB(1, 0), b3, voffB); PG8_STAGE(PG8_SB(1, 1), b3 + hstep, voffB); PG8_STAGE(PG8_SA(1, 0), a3, voffA);
;             PG8_WAIT_V(8); PG8_WAIT_L(0); PG8_BAR; PG8_MMA(1, 0, At, B0); PG8_MMA(1, 1, At, B1); PG8_BAR; PG8_SCHED;
;         }
;         if (wr == 0) PG8_BAR;
	s_add_i32 s67, 0, 0x18000
	s_add_i32 s68, 0, 0x1c000
	v_add_u32_e32 v164, s67, v148
	v_add_u32_e32 v180, s68, v148
	s_add_u32 s42, s42, 0x40000
	s_addc_u32 s43, s43, 0
	s_mov_b32 m0, s51
	s_nop 0
	global_load_lds_dwordx4 v128, s[42:43]
	s_mov_b32 m0, s52
	s_nop 0
	global_load_lds_dwordx4 v132, s[42:43]
	ds_read_b128 v[152:155], v164
	ds_read_b128 v[156:159], v164 offset:1024
	ds_read_b128 v[160:163], v164 offset:2048
	ds_read_b128 v[164:167], v164 offset:3072
	ds_read_b128 v[168:171], v180
	ds_read_b128 v[172:175], v180 offset:1024
	ds_read_b128 v[176:179], v180 offset:2048
	ds_read_b128 v[180:183], v180 offset:3072
	ds_read_b128 v[184:187], v151 offset:32768
	ds_read_b128 v[188:191], v151 offset:33792
	ds_read_b128 v[192:195], v151 offset:34816
	ds_read_b128 v[196:199], v151 offset:35840
	ds_read_b128 v[200:203], v151 offset:36864
	ds_read_b128 v[204:207], v151 offset:37888
	ds_read_b128 v[208:211], v151 offset:38912
	ds_read_b128 v[212:215], v151 offset:39936
	s_waitcnt vmcnt(8)
	s_waitcnt lgkmcnt(0)
	s_barrier
	s_setprio 1
	s_waitcnt lgkmcnt(0)
	v_mfma_f32_16x16x32_bf16 v[124:127], v[152:155], v[184:187], v[124:127]
	v_mfma_f32_16x16x32_bf16 v[120:123], v[160:163], v[184:187], v[120:123]
	v_mfma_f32_16x16x32_bf16 v[108:111], v[152:155], v[192:195], v[108:111]
	v_mfma_f32_16x16x32_bf16 v[104:107], v[160:163], v[192:195], v[104:107]
	v_mfma_f32_16x16x32_bf16 v[92:95], v[152:155], v[200:203], v[92:95]
	v_mfma_f32_16x16x32_bf16 v[88:91], v[160:163], v[200:203], v[88:91]
	v_mfma_f32_16x16x32_bf16 v[76:79], v[152:155], v[208:211], v[76:79]
	v_mfma_f32_16x16x32_bf16 v[72:75], v[160:163], v[208:211], v[72:75]
	v_mfma_f32_16x16x32_bf16 v[124:127], v[156:159], v[188:191], v[124:127]
	v_mfma_f32_16x16x32_bf16 v[120:123], v[164:167], v[188:191], v[120:123]
	v_mfma_f32_16x16x32_bf16 v[108:111], v[156:159], v[196:199], v[108:111]
	v_mfma_f32_16x16x32_bf16 v[104:107], v[164:167], v[196:199], v[104:107]
	v_mfma_f32_16x16x32_bf16 v[92:95], v[156:159], v[204:207], v[92:95]
	v_mfma_f32_16x16x32_bf16 v[88:91], v[164:167], v[204:207], v[88:91]
	v_mfma_f32_16x16x32_bf16 v[76:79], v[156:159], v[212:215], v[76:79]
	v_mfma_f32_16x16x32_bf16 v[72:75], v[164:167], v[212:215], v[72:75]
	s_setprio 0
	s_setprio 1
	v_mfma_f32_16x16x32_bf16 v[116:119], v[168:171], v[184:187], v[116:119]
	v_mfma_f32_16x16x32_bf16 v[112:115], v[176:179], v[184:187], v[112:115]
	v_mfma_f32_16x16x32_bf16 v[100:103], v[168:171], v[192:195], v[100:103]
	v_mfma_f32_16x16x32_bf16 v[96:99], v[176:179], v[192:195], v[96:99]
	v_mfma_f32_16x16x32_bf16 v[84:87], v[168:171], v[200:203], v[84:87]
	v_mfma_f32_16x16x32_bf16 v[80:83], v[176:179], v[200:203], v[80:83]
	v_mfma_f32_16x16x32_bf16 v[68:71], v[168:171], v[208:211], v[68:71]
	v_mfma_f32_16x16x32_bf16 v[64:67], v[176:179], v[208:211], v[64:67]
	v_mfma_f32_16x16x32_bf16 v[116:119], v[172:175], v[188:191], v[116:119]
	v_mfma_f32_16x16x32_bf16 v[112:115], v[180:183], v[188:191], v[112:115]
	v_mfma_f32_16x16x32_bf16 v[100:103], v[172:175], v[196:199], v[100:103]
	v_mfma_f32_16x16x32_bf16 v[96:99], v[180:183], v[196:199], v[96:99]
	v_mfma_f32_16x16x32_bf16 v[84:87], v[172:175], v[204:207], v[84:87]
	v_mfma_f32_16x16x32_bf16 v[80:83], v[180:183], v[204:207], v[80:83]
	v_mfma_f32_16x16x32_bf16 v[68:71], v[172:175], v[212:215], v[68:71]
	v_mfma_f32_16x16x32_bf16 v[64:67], v[180:183], v[212:215], v[64:67]
	s_setprio 0
	s_barrier
	s_add_i32 s42, s67, s49
	s_add_u32 s40, s40, 0x80
	s_addc_u32 s41, s41, 0
	s_mov_b32 m0, s42
	s_nop 0
	global_load_lds_dwordx4 v130, s[40:41]
	s_add_i32 m0, s42, 0x2000
	s_add_i32 s42, s68, s49
	global_load_lds_dwordx4 v134, s[40:41]
	s_add_u32 s40, s40, 0x40000
	s_addc_u32 s41, s41, 0
	s_mov_b32 m0, s42
	s_nop 0
	global_load_lds_dwordx4 v130, s[40:41]
	s_add_i32 m0, s42, 0x2000
	s_nop 0
	global_load_lds_dwordx4 v134, s[40:41]
	s_mov_b32 m0, s56
	s_nop 0
	global_load_lds_dwordx4 v128, s[100:101]
	s_mov_b32 m0, s57
	s_nop 0
	global_load_lds_dwordx4 v132, s[100:101]
	ds_read_b128 v[184:187], v151 offset:49152
	ds_read_b128 v[188:191], v151 offset:50176
	ds_read_b128 v[192:195], v151 offset:51200
	ds_read_b128 v[196:199], v151 offset:52224
	ds_read_b128 v[200:203], v151 offset:53248
	ds_read_b128 v[204:207], v151 offset:54272
	ds_read_b128 v[208:211], v151 offset:55296
	ds_read_b128 v[212:215], v151 offset:56320
	s_waitcnt vmcnt(8)
	s_waitcnt lgkmcnt(0)
	s_barrier
	s_setprio 1
	s_waitcnt lgkmcnt(0)
	v_mfma_f32_16x16x32_bf16 v[60:63], v[152:155], v[184:187], v[60:63]
	v_mfma_f32_16x16x32_bf16 v[56:59], v[160:163], v[184:187], v[56:59]
	v_mfma_f32_16x16x32_bf16 v[44:47], v[152:155], v[192:195], v[44:47]
	v_mfma_f32_16x16x32_bf16 v[40:43], v[160:163], v[192:195], v[40:43]
	v_mfma_f32_16x16x32_bf16 v[28:31], v[152:155], v[200:203], v[28:31]
	v_mfma_f32_16x16x32_bf16 v[24:27], v[160:163], v[200:203], v[24:27]
	v_mfma_f32_16x16x32_bf16 v[12:15], v[152:155], v[208:211], v[12:15]
	v_mfma_f32_16x16x32_bf16 v[8:11], v[160:163], v[208:211], v[8:11]
	v_mfma_f32_16x16x32_bf16 v[60:63], v[156:159], v[188:191], v[60:63]
	v_mfma_f32_16x16x32_bf16 v[56:59], v[164:167], v[188:191], v[56:59]
	v_mfma_f32_16x16x32_bf16 v[44:47], v[156:159], v[196:199], v[44:47]
	v_mfma_f32_16x16x32_bf16 v[40:43], v[164:167], v[196:199], v[40:43]
	v_mfma_f32_16x16x32_bf16 v[28:31], v[156:159], v[204:207], v[28:31]
	v_mfma_f32_16x16x32_bf16 v[24:27], v[164:167], v[204:207], v[24:27]
	v_mfma_f32_16x16x32_bf16 v[12:15], v[156:159], v[212:215], v[12:15]
	v_mfma_f32_16x16x32_bf16 v[8:11], v[164:167], v[212:215], v[8:11]
	s_setprio 0
	s_setprio 1
	v_mfma_f32_16x16x32_bf16 v[52:55], v[168:171], v[184:187], v[52:55]
	v_mfma_f32_16x16x32_bf16 v[48:51], v[176:179], v[184:187], v[48:51]
	v_mfma_f32_16x16x32_bf16 v[36:39], v[168:171], v[192:195], v[36:39]
	v_mfma_f32_16x16x32_bf16 v[32:35], v[176:179], v[192:195], v[32:35]
	v_mfma_f32_16x16x32_bf16 v[20:23], v[168:171], v[200:203], v[20:23]
	v_mfma_f32_16x16x32_bf16 v[16:19], v[176:179], v[200:203], v[16:19]
	v_mfma_f32_16x16x32_bf16 v[4:7], v[168:171], v[208:211], v[4:7]
	v_mfma_f32_16x16x32_bf16 v[0:3], v[176:179], v[208:211], v[0:3]
	v_mfma_f32_16x16x32_bf16 v[52:55], v[172:175], v[188:191], v[52:55]
	v_mfma_f32_16x16x32_bf16 v[48:51], v[180:183], v[188:191], v[48:51]
	v_mfma_f32_16x16x32_bf16 v[36:39], v[172:175], v[196:199], v[36:39]
	v_mfma_f32_16x16x32_bf16 v[32:35], v[180:183], v[196:199], v[32:35]
	v_mfma_f32_16x16x32_bf16 v[20:23], v[172:175], v[204:207], v[20:23]
	v_mfma_f32_16x16x32_bf16 v[16:19], v[180:183], v[204:207], v[16:19]
	v_mfma_f32_16x16x32_bf16 v[4:7], v[172:175], v[212:215], v[4:7]
	v_mfma_f32_16x16x32_bf16 v[0:3], v[180:183], v[212:215], v[0:3]
	s_setprio 0
	s_barrier
	s_add_i32 s66, s66, 2
	s_add_u32 s64, s64, 0x100
	s_addc_u32 s65, s65, 0
	s_add_u32 s38, s38, 0x100
	s_addc_u32 s39, s39, 0
	s_cmp_gt_u32 s66, 13
	s_cbranch_scc0 .LBB0_713
	s_and_b64 vcc, exec, s[10:11]
	s_cbranch_vccz .LBB0_716
	s_barrier

; #define PG8_STAGE(bufoff, gbase, voff) do { _Pragma("unroll") for (int _i = 0; _i < 2; ++_i) \
;         __builtin_amdgcn_global_load_lds((const unsigned*)((const char*)(gbase) + (voff)[_i]), (LAS unsigned*)(lds + (bufoff) + ldsw + _i * 8192), 16, 0, 0); } while (0)
; #define PG8_LDA(dst, b, h) do { _Pragma("unroll") for (int m = 0; m < 4; ++m) _Pragma("unroll") for (int k = 0; k < 2; ++k) dst[m][k] = *(const LAS bf16x8*)(lds + PG8_SA(b, h) + aoff + m * 2048 + k * 1024); } while (0)
; #define PG8_LDB(dst, b, h) do { _Pragma("unroll") for (int n = 0; n < 2; ++n) _Pragma("unroll") for (int k = 0; k < 2; ++k) dst[n][k] = *(const LAS bf16x8*)(lds + PG8_SB(b, h) + boff + n * 2048 + k * 1024); } while (0)
; #define PG8_MMA(ai, bj, At, Bt) do { __builtin_amdgcn_s_setprio(1); _Pragma("unroll") for (int m = 0; m < 4; ++m) _Pragma("unroll") for (int n = 0; n < 2; ++n) _Pragma("unroll") for (int k = 0; k < 2; ++k) \
;         acc[ai][bj][m][n] = __builtin_amdgcn_mfma_f32_16x16x32_bf16(Bt[n][k], At[m][k], acc[ai][bj][m][n], 0, 0, 0); __builtin_amdgcn_s_setprio(0); } while (0)
; #define PG8_WAIT_V(n) asm volatile("s_waitcnt vmcnt(" #n ")" ::: "memory")
; #define PG8_WAIT_L(n) asm volatile("s_waitcnt lgkmcnt(" #n ")" ::: "memory")
; #define PG8_BAR __builtin_amdgcn_s_barrier()
; #define PG8_SCHED __builtin_amdgcn_sched_barrier(0)
; template <class Epi>
; __device__ __forceinline__ void gemm_phase(ldsp lds, const Gemm g, const StaticOrder& S, const Epi& E, int wave0) {
;     ...
;         for (int t = 0; t < nt; t += 2) {
;             const bool last = (t == nt - 2);
;             const char* a1 = cA + (size_t)(t + 1) * kstep;
;             const char* a2 = last ? nA : cA + (size_t)(t + 2) * kstep; const char* b2 = last ? nB : cB + (size_t)(t + 2) * kstep;
;             const char* a3 = a2 + kstep; const char* b3 = b2 + kstep;
;             PG8_LDB(B0, 0, 0); PG8_LDB(B1, 0, 1); PG8_SCHED; PG8_LDA(At, 0, 0); PG8_STAGE(PG8_SA(1, 1), a1 + hstep, voffA);
;             PG8_WAIT_V(8); PG8_WAIT_L(0); PG8_BAR; PG8_MMA(0, 0, At, B0); PG8_MMA(0, 1, At, B1); PG8_BAR; PG8_SCHED;
;             PG8_LDA(At, 0, 1); PG8_STAGE(PG8_SB(0, 0), b2, voffB); PG8_STAGE(PG8_SB(0, 1), b2 + hstep, voffB); PG8_STAGE(PG8_SA(0, 0), a2, voffA);
;             PG8_WAIT_V(8); PG8_WAIT_L(0); PG8_BAR; PG8_MMA(1, 0, At, B0); PG8_MMA(1, 1, At, B1); PG8_BAR; PG8_SCHED;
.LBB0_781:
	s_add_u32 s42, s40, 0xfff80080
	s_addc_u32 s43, s41, -1
	s_cmp_eq_u32 s69, 28
	s_cselect_b32 s45, s31, s43
	s_cselect_b32 s44, s65, s42
	s_cselect_b32 s43, s29, s68
	s_cselect_b32 s42, s66, s67
	s_add_i32 m0, s39, 0xc000
	s_nop 0
	global_load_lds_dwordx4 v138, s[40:41]
	s_add_i32 m0, s39, 0xe000
	s_nop 0
	global_load_lds_dwordx4 v136, s[40:41]
	ds_read_b128 v[152:155], v149
	ds_read_b128 v[156:159], v149 offset:1024
	ds_read_b128 v[160:163], v149 offset:2048
	ds_read_b128 v[164:167], v149 offset:3072
	ds_read_b128 v[168:171], v150
	ds_read_b128 v[172:175], v150 offset:1024
	ds_read_b128 v[176:179], v150 offset:2048
	ds_read_b128 v[180:183], v150 offset:3072
	ds_read_b128 v[184:187], v151
	ds_read_b128 v[188:191], v151 offset:1024
	ds_read_b128 v[192:195], v151 offset:2048
	ds_read_b128 v[196:199], v151 offset:3072
	ds_read_b128 v[200:203], v151 offset:4096
	ds_read_b128 v[204:207], v151 offset:5120
	ds_read_b128 v[208:211], v151 offset:6144
	ds_read_b128 v[212:215], v151 offset:7168
	s_waitcnt vmcnt(8)
	s_waitcnt lgkmcnt(0)
	s_barrier
	s_setprio 1
	s_waitcnt lgkmcnt(0)
	v_mfma_f32_16x16x32_bf16 v[124:127], v[152:155], v[184:187], v[124:127]
	v_mfma_f32_16x16x32_bf16 v[120:123], v[160:163], v[184:187], v[120:123]
	v_mfma_f32_16x16x32_bf16 v[108:111], v[152:155], v[192:195], v[108:111]
	v_mfma_f32_16x16x32_bf16 v[104:107], v[160:163], v[192:195], v[104:107]
	v_mfma_f32_16x16x32_bf16 v[92:95], v[152:155], v[200:203], v[92:95]
	v_mfma_f32_16x16x32_bf16 v[88:91], v[160:163], v[200:203], v[88:91]
	v_mfma_f32_16x16x32_bf16 v[76:79], v[152:155], v[208:211], v[76:79]
	v_mfma_f32_16x16x32_bf16 v[72:75], v[160:163], v[208:211], v[72:75]
	v_mfma_f32_16x16x32_bf16 v[124:127], v[156:159], v[188:191], v[124:127]
	v_mfma_f32_16x16x32_bf16 v[120:123], v[164:167], v[188:191], v[120:123]
	v_mfma_f32_16x16x32_bf16 v[108:111], v[156:159], v[196:199], v[108:111]
	v_mfma_f32_16x16x32_bf16 v[104:107], v[164:167], v[196:199], v[104:107]
	v_mfma_f32_16x16x32_bf16 v[92:95], v[156:159], v[204:207], v[92:95]
	v_mfma_f32_16x16x32_bf16 v[88:91], v[164:167], v[204:207], v[88:91]
	v_mfma_f32_16x16x32_bf16 v[76:79], v[156:159], v[212:215], v[76:79]
	v_mfma_f32_16x16x32_bf16 v[72:75], v[164:167], v[212:215], v[72:75]
	s_setprio 0
	s_setprio 1
	v_mfma_f32_16x16x32_bf16 v[116:119], v[168:171], v[184:187], v[116:119]
	v_mfma_f32_16x16x32_bf16 v[112:115], v[176:179], v[184:187], v[112:115]
	v_mfma_f32_16x16x32_bf16 v[100:103], v[168:171], v[192:195], v[100:103]
	v_mfma_f32_16x16x32_bf16 v[96:99], v[176:179], v[192:195], v[96:99]
	v_mfma_f32_16x16x32_bf16 v[84:87], v[168:171], v[200:203], v[84:87]
	v_mfma_f32_16x16x32_bf16 v[80:83], v[176:179], v[200:203], v[80:83]
	v_mfma_f32_16x16x32_bf16 v[68:71], v[168:171], v[208:211], v[68:71]
	v_mfma_f32_16x16x32_bf16 v[64:67], v[176:179], v[208:211], v[64:67]
	v_mfma_f32_16x16x32_bf16 v[116:119], v[172:175], v[188:191], v[116:119]
	v_mfma_f32_16x16x32_bf16 v[112:115], v[180:183], v[188:191], v[112:115]
	v_mfma_f32_16x16x32_bf16 v[100:103], v[172:175], v[196:199], v[100:103]
	v_mfma_f32_16x16x32_bf16 v[96:99], v[180:183], v[196:199], v[96:99]
	v_mfma_f32_16x16x32_bf16 v[84:87], v[172:175], v[204:207], v[84:87]
	v_mfma_f32_16x16x32_bf16 v[80:83], v[180:183], v[204:207], v[80:83]
	v_mfma_f32_16x16x32_bf16 v[68:71], v[172:175], v[212:215], v[68:71]
	v_mfma_f32_16x16x32_bf16 v[64:67], v[180:183], v[212:215], v[64:67]
	s_setprio 0
	s_barrier
	s_add_i32 s70, s62, s52
	s_add_u32 s100, s44, 0x80
	s_addc_u32 s101, s45, 0
	s_mov_b32 m0, s70
	s_nop 0
	global_load_lds_dwordx4 v130, s[42:43]
	s_add_i32 m0, s70, 0x2000
	s_add_u32 s70, s42, 0x80000
	s_addc_u32 s71, s43, 0
	s_add_i32 s72, s63, s52
	global_load_lds_dwordx4 v134, s[42:43]
	s_mov_b32 m0, s72
	s_nop 0
	global_load_lds_dwordx4 v130, s[70:71]
	s_add_i32 m0, s72, 0x2000
	s_nop 0
	global_load_lds_dwordx4 v134, s[70:71]
	s_mov_b32 m0, s39
	s_nop 0
	global_load_lds_dwordx4 v128, s[44:45]
	s_mov_b32 m0, s53
	s_nop 0
	global_load_lds_dwordx4 v132, s[44:45]
	ds_read_b128 v[184:187], v151 offset:16384
	ds_read_b128 v[188:191], v151 offset:17408
	ds_read_b128 v[192:195], v151 offset:18432
	ds_read_b128 v[196:199], v151 offset:19456
	ds_read_b128 v[200:203], v151 offset:20480
	ds_read_b128 v[204:207], v151 offset:21504
	ds_read_b128 v[208:211], v151 offset:22528
	ds_read_b128 v[212:215], v151 offset:23552
	s_waitcnt vmcnt(8)
	s_waitcnt lgkmcnt(0)
	s_barrier
	s_setprio 1
	s_waitcnt lgkmcnt(0)
	v_mfma_f32_16x16x32_bf16 v[60:63], v[152:155], v[184:187], v[60:63]
	v_mfma_f32_16x16x32_bf16 v[56:59], v[160:163], v[184:187], v[56:59]
	v_mfma_f32_16x16x32_bf16 v[44:47], v[152:155], v[192:195], v[44:47]
	v_mfma_f32_16x16x32_bf16 v[40:43], v[160:163], v[192:195], v[40:43]
	v_mfma_f32_16x16x32_bf16 v[28:31], v[152:155], v[200:203], v[28:31]
	v_mfma_f32_16x16x32_bf16 v[24:27], v[160:163], v[200:203], v[24:27]
	v_mfma_f32_16x16x32_bf16 v[12:15], v[152:155], v[208:211], v[12:15]
	v_mfma_f32_16x16x32_bf16 v[8:11], v[160:163], v[208:211], v[8:11]
	v_mfma_f32_16x16x32_bf16 v[60:63], v[156:159], v[188:191], v[60:63]
	v_mfma_f32_16x16x32_bf16 v[56:59], v[164:167], v[188:191], v[56:59]
	v_mfma_f32_16x16x32_bf16 v[44:47], v[156:159], v[196:199], v[44:47]
	v_mfma_f32_16x16x32_bf16 v[40:43], v[164:167], v[196:199], v[40:43]
	v_mfma_f32_16x16x32_bf16 v[28:31], v[156:159], v[204:207], v[28:31]
	v_mfma_f32_16x16x32_bf16 v[24:27], v[164:167], v[204:207], v[24:27]
	v_mfma_f32_16x16x32_bf16 v[12:15], v[156:159], v[212:215], v[12:15]
	v_mfma_f32_16x16x32_bf16 v[8:11], v[164:167], v[212:215], v[8:11]
	s_setprio 0
	s_setprio 1
	v_mfma_f32_16x16x32_bf16 v[52:55], v[168:171], v[184:187], v[52:55]
	v_mfma_f32_16x16x32_bf16 v[48:51], v[176:179], v[184:187], v[48:51]
	v_mfma_f32_16x16x32_bf16 v[36:39], v[168:171], v[192:195], v[36:39]
	v_mfma_f32_16x16x32_bf16 v[32:35], v[176:179], v[192:195], v[32:35]
	v_mfma_f32_16x16x32_bf16 v[20:23], v[168:171], v[200:203], v[20:23]
	v_mfma_f32_16x16x32_bf16 v[16:19], v[176:179], v[200:203], v[16:19]
	v_mfma_f32_16x16x32_bf16 v[4:7], v[168:171], v[208:211], v[4:7]
	v_mfma_f32_16x16x32_bf16 v[0:3], v[176:179], v[208:211], v[0:3]
	v_mfma_f32_16x16x32_bf16 v[52:55], v[172:175], v[188:191], v[52:55]
	v_mfma_f32_16x16x32_bf16 v[48:51], v[180:183], v[188:191], v[48:51]
	v_mfma_f32_16x16x32_bf16 v[36:39], v[172:175], v[196:199], v[36:39]
	v_mfma_f32_16x16x32_bf16 v[32:35], v[180:183], v[196:199], v[32:35]
	v_mfma_f32_16x16x32_bf16 v[20:23], v[172:175], v[204:207], v[20:23]
	v_mfma_f32_16x16x32_bf16 v[16:19], v[180:183], v[204:207], v[16:19]
	v_mfma_f32_16x16x32_bf16 v[4:7], v[172:175], v[212:215], v[4:7]
	v_mfma_f32_16x16x32_bf16 v[0:3], v[180:183], v[212:215], v[0:3]
	s_setprio 0
	s_barrier
; #define PG8_STAGE(bufoff, gbase, voff) do { _Pragma("unroll") for (int _i = 0; _i < 2; ++_i) \
;         __builtin_amdgcn_global_load_lds((const unsigned*)((const char*)(gbase) + (voff)[_i]), (LAS unsigned*)(lds + (bufoff) + ldsw + _i * 8192), 16, 0, 0); } while (0)
; #define PG8_LDA(dst, b, h) do { _Pragma("unroll") for (int m = 0; m < 4; ++m) _Pragma("unroll") for (int k = 0; k < 2; ++k) dst[m][k] = *(const LAS bf16x8*)(lds + PG8_SA(b, h) + aoff + m * 2048 + k * 1024); } while (0)
; #define PG8_LDB(dst, b, h) do { _Pragma("unroll") for (int n = 0; n < 2; ++n) _Pragma("unroll") for (int k = 0; k < 2; ++k) dst[n][k] = *(const LAS bf16x8*)(lds + PG8_SB(b, h) + boff + n * 2048 + k * 1024); } while (0)
; #define PG8_MMA(ai, bj, At, Bt) do { __builtin_amdgcn_s_setprio(1); _Pragma("unroll") for (int m = 0; m < 4; ++m) _Pragma("unroll") for (int n = 0; n < 2; ++n) _Pragma("unroll") for (int k = 0; k < 2; ++k) \
;         acc[ai][bj][m][n] = __builtin_amdgcn_mfma_f32_16x16x32_bf16(Bt[n][k], At[m][k], acc[ai][bj][m][n], 0, 0, 0); __builtin_amdgcn_s_setprio(0); } while (0)
; #define PG8_WAIT_V(n) asm volatile("s_waitcnt vmcnt(" #n ")" ::: "memory")
; #define PG8_WAIT_L(n) asm volatile("s_waitcnt lgkmcnt(" #n ")" ::: "memory")
; #define PG8_BAR __builtin_amdgcn_s_barrier()
; #define PG8_SCHED __builtin_amdgcn_sched_barrier(0)
; template <class Epi>
; __device__ __forceinline__ void gemm_phase(ldsp lds, const Gemm g, const StaticOrder& S, const Epi& E, int wave0) {
;     ...
;             PG8_LDB(B0, 1, 0); PG8_LDB(B1, 1, 1); PG8_SCHED; PG8_LDA(At, 1, 0); PG8_STAGE(PG8_SA(0, 1), a2 + hstep, voffA);
;             PG8_WAIT_V(8); PG8_WAIT_L(0); PG8_BAR; PG8_MMA(0, 0, At, B0); PG8_MMA(0, 1, At, B1); PG8_BAR; PG8_SCHED;
;             PG8_LDA(At, 1, 1); PG8_STAGE(PG8_SB(1, 0), b3, voffB); PG8_STAGE(PG8_SB(1, 1), b3 + hstep, voffB); PG8_STAGE(PG8_SA(1, 0), a3, voffA);
;             PG8_WAIT_V(8); PG8_WAIT_L(0); PG8_BAR; PG8_MMA(1, 0, At, B0); PG8_MMA(1, 1, At, B1); PG8_BAR; PG8_SCHED;
;         }
;         if (wr == 0) PG8_BAR;
	s_add_i32 s70, 0, 0x18000
	s_add_i32 s71, 0, 0x1c000
	v_add_u32_e32 v164, s70, v148
	v_add_u32_e32 v180, s71, v148
	s_add_u32 s44, s44, 0x80000
	s_addc_u32 s45, s45, 0
	s_mov_b32 m0, s54
	s_nop 0
	global_load_lds_dwordx4 v128, s[44:45]
	s_mov_b32 m0, s55
	s_nop 0
	global_load_lds_dwordx4 v132, s[44:45]
	ds_read_b128 v[152:155], v164
	ds_read_b128 v[156:159], v164 offset:1024
	ds_read_b128 v[160:163], v164 offset:2048
	ds_read_b128 v[164:167], v164 offset:3072
	ds_read_b128 v[168:171], v180
	ds_read_b128 v[172:175], v180 offset:1024
	ds_read_b128 v[176:179], v180 offset:2048
	ds_read_b128 v[180:183], v180 offset:3072
	ds_read_b128 v[184:187], v151 offset:32768
	ds_read_b128 v[188:191], v151 offset:33792
	ds_read_b128 v[192:195], v151 offset:34816
	ds_read_b128 v[196:199], v151 offset:35840
	ds_read_b128 v[200:203], v151 offset:36864
	ds_read_b128 v[204:207], v151 offset:37888
	ds_read_b128 v[208:211], v151 offset:38912
	ds_read_b128 v[212:215], v151 offset:39936
	s_waitcnt vmcnt(8)
	s_waitcnt lgkmcnt(0)
	s_barrier
	s_setprio 1
	s_waitcnt lgkmcnt(0)
	v_mfma_f32_16x16x32_bf16 v[124:127], v[152:155], v[184:187], v[124:127]
	v_mfma_f32_16x16x32_bf16 v[120:123], v[160:163], v[184:187], v[120:123]
	v_mfma_f32_16x16x32_bf16 v[108:111], v[152:155], v[192:195], v[108:111]
	v_mfma_f32_16x16x32_bf16 v[104:107], v[160:163], v[192:195], v[104:107]
	v_mfma_f32_16x16x32_bf16 v[92:95], v[152:155], v[200:203], v[92:95]
	v_mfma_f32_16x16x32_bf16 v[88:91], v[160:163], v[200:203], v[88:91]
	v_mfma_f32_16x16x32_bf16 v[76:79], v[152:155], v[208:211], v[76:79]
	v_mfma_f32_16x16x32_bf16 v[72:75], v[160:163], v[208:211], v[72:75]
	v_mfma_f32_16x16x32_bf16 v[124:127], v[156:159], v[188:191], v[124:127]
	v_mfma_f32_16x16x32_bf16 v[120:123], v[164:167], v[188:191], v[120:123]
	v_mfma_f32_16x16x32_bf16 v[108:111], v[156:159], v[196:199], v[108:111]
	v_mfma_f32_16x16x32_bf16 v[104:107], v[164:167], v[196:199], v[104:107]
	v_mfma_f32_16x16x32_bf16 v[92:95], v[156:159], v[204:207], v[92:95]
	v_mfma_f32_16x16x32_bf16 v[88:91], v[164:167], v[204:207], v[88:91]
	v_mfma_f32_16x16x32_bf16 v[76:79], v[156:159], v[212:215], v[76:79]
	v_mfma_f32_16x16x32_bf16 v[72:75], v[164:167], v[212:215], v[72:75]
	s_setprio 0
	s_setprio 1
	v_mfma_f32_16x16x32_bf16 v[116:119], v[168:171], v[184:187], v[116:119]
	v_mfma_f32_16x16x32_bf16 v[112:115], v[176:179], v[184:187], v[112:115]
	v_mfma_f32_16x16x32_bf16 v[100:103], v[168:171], v[192:195], v[100:103]
	v_mfma_f32_16x16x32_bf16 v[96:99], v[176:179], v[192:195], v[96:99]
	v_mfma_f32_16x16x32_bf16 v[84:87], v[168:171], v[200:203], v[84:87]
	v_mfma_f32_16x16x32_bf16 v[80:83], v[176:179], v[200:203], v[80:83]
	v_mfma_f32_16x16x32_bf16 v[68:71], v[168:171], v[208:211], v[68:71]
	v_mfma_f32_16x16x32_bf16 v[64:67], v[176:179], v[208:211], v[64:67]
	v_mfma_f32_16x16x32_bf16 v[116:119], v[172:175], v[188:191], v[116:119]
	v_mfma_f32_16x16x32_bf16 v[112:115], v[180:183], v[188:191], v[112:115]
	v_mfma_f32_16x16x32_bf16 v[100:103], v[172:175], v[196:199], v[100:103]
	v_mfma_f32_16x16x32_bf16 v[96:99], v[180:183], v[196:199], v[96:99]
	v_mfma_f32_16x16x32_bf16 v[84:87], v[172:175], v[204:207], v[84:87]
	v_mfma_f32_16x16x32_bf16 v[80:83], v[180:183], v[204:207], v[80:83]
	v_mfma_f32_16x16x32_bf16 v[68:71], v[172:175], v[212:215], v[68:71]
	v_mfma_f32_16x16x32_bf16 v[64:67], v[180:183], v[212:215], v[64:67]
	s_setprio 0
	s_barrier
	s_add_i32 s44, s70, s52
	s_add_u32 s42, s42, 0x80
	s_addc_u32 s43, s43, 0
	s_mov_b32 m0, s44
	s_nop 0
	global_load_lds_dwordx4 v130, s[42:43]
	s_add_i32 m0, s44, 0x2000
	s_add_i32 s44, s71, s52
	global_load_lds_dwordx4 v134, s[42:43]
	s_add_u32 s42, s42, 0x80000
	s_addc_u32 s43, s43, 0
	s_mov_b32 m0, s44
	s_nop 0
	global_load_lds_dwordx4 v130, s[42:43]
	s_add_i32 m0, s44, 0x2000
	s_nop 0
	global_load_lds_dwordx4 v134, s[42:43]
	s_mov_b32 m0, s59
	s_nop 0
	global_load_lds_dwordx4 v128, s[100:101]
	s_mov_b32 m0, s60
	s_nop 0
	global_load_lds_dwordx4 v132, s[100:101]
	ds_read_b128 v[184:187], v151 offset:49152
	ds_read_b128 v[188:191], v151 offset:50176
	ds_read_b128 v[192:195], v151 offset:51200
	ds_read_b128 v[196:199], v151 offset:52224
	ds_read_b128 v[200:203], v151 offset:53248
	ds_read_b128 v[204:207], v151 offset:54272
	ds_read_b128 v[208:211], v151 offset:55296
	ds_read_b128 v[212:215], v151 offset:56320
	s_waitcnt vmcnt(8)
	s_waitcnt lgkmcnt(0)
	s_barrier
	s_setprio 1
	s_waitcnt lgkmcnt(0)
	v_mfma_f32_16x16x32_bf16 v[60:63], v[152:155], v[184:187], v[60:63]
	v_mfma_f32_16x16x32_bf16 v[56:59], v[160:163], v[184:187], v[56:59]
	v_mfma_f32_16x16x32_bf16 v[44:47], v[152:155], v[192:195], v[44:47]
	v_mfma_f32_16x16x32_bf16 v[40:43], v[160:163], v[192:195], v[40:43]
	v_mfma_f32_16x16x32_bf16 v[28:31], v[152:155], v[200:203], v[28:31]
	v_mfma_f32_16x16x32_bf16 v[24:27], v[160:163], v[200:203], v[24:27]
	v_mfma_f32_16x16x32_bf16 v[12:15], v[152:155], v[208:211], v[12:15]
	v_mfma_f32_16x16x32_bf16 v[8:11], v[160:163], v[208:211], v[8:11]
	v_mfma_f32_16x16x32_bf16 v[60:63], v[156:159], v[188:191], v[60:63]
	v_mfma_f32_16x16x32_bf16 v[56:59], v[164:167], v[188:191], v[56:59]
	v_mfma_f32_16x16x32_bf16 v[44:47], v[156:159], v[196:199], v[44:47]
	v_mfma_f32_16x16x32_bf16 v[40:43], v[164:167], v[196:199], v[40:43]
	v_mfma_f32_16x16x32_bf16 v[28:31], v[156:159], v[204:207], v[28:31]
	v_mfma_f32_16x16x32_bf16 v[24:27], v[164:167], v[204:207], v[24:27]
	v_mfma_f32_16x16x32_bf16 v[12:15], v[156:159], v[212:215], v[12:15]
	v_mfma_f32_16x16x32_bf16 v[8:11], v[164:167], v[212:215], v[8:11]
	s_setprio 0
	s_setprio 1
	v_mfma_f32_16x16x32_bf16 v[52:55], v[168:171], v[184:187], v[52:55]
	v_mfma_f32_16x16x32_bf16 v[48:51], v[176:179], v[184:187], v[48:51]
	v_mfma_f32_16x16x32_bf16 v[36:39], v[168:171], v[192:195], v[36:39]
	v_mfma_f32_16x16x32_bf16 v[32:35], v[176:179], v[192:195], v[32:35]
	v_mfma_f32_16x16x32_bf16 v[20:23], v[168:171], v[200:203], v[20:23]
	v_mfma_f32_16x16x32_bf16 v[16:19], v[176:179], v[200:203], v[16:19]
	v_mfma_f32_16x16x32_bf16 v[4:7], v[168:171], v[208:211], v[4:7]
	v_mfma_f32_16x16x32_bf16 v[0:3], v[176:179], v[208:211], v[0:3]
	v_mfma_f32_16x16x32_bf16 v[52:55], v[172:175], v[188:191], v[52:55]
	v_mfma_f32_16x16x32_bf16 v[48:51], v[180:183], v[188:191], v[48:51]
	v_mfma_f32_16x16x32_bf16 v[36:39], v[172:175], v[196:199], v[36:39]
	v_mfma_f32_16x16x32_bf16 v[32:35], v[180:183], v[196:199], v[32:35]
	v_mfma_f32_16x16x32_bf16 v[20:23], v[172:175], v[204:207], v[20:23]
	v_mfma_f32_16x16x32_bf16 v[16:19], v[180:183], v[204:207], v[16:19]
	v_mfma_f32_16x16x32_bf16 v[4:7], v[172:175], v[212:215], v[4:7]
	v_mfma_f32_16x16x32_bf16 v[0:3], v[180:183], v[212:215], v[0:3]
	s_setprio 0
	s_barrier
	s_add_i32 s69, s69, 2
	s_add_u32 s67, s67, 0x100
	s_addc_u32 s68, s68, 0
	s_add_u32 s40, s40, 0x100
	s_addc_u32 s41, s41, 0
	s_cmp_gt_u32 s69, 29
	s_cbranch_scc0 .LBB0_781
	s_and_b64 vcc, exec, s[10:11]
	s_cbranch_vccz .LBB0_784
	s_barrier

; #define PG8_STAGE(bufoff, gbase, voff) do { _Pragma("unroll") for (int _i = 0; _i < 2; ++_i) \
;         __builtin_amdgcn_global_load_lds((const unsigned*)((const char*)(gbase) + (voff)[_i]), (LAS unsigned*)(lds + (bufoff) + ldsw + _i * 8192), 16, 0, 0); } while (0)
; #define PG8_LDA(dst, b, h) do { _Pragma("unroll") for (int m = 0; m < 4; ++m) _Pragma("unroll") for (int k = 0; k < 2; ++k) dst[m][k] = *(const LAS bf16x8*)(lds + PG8_SA(b, h) + aoff + m * 2048 + k * 1024); } while (0)
; #define PG8_LDB(dst, b, h) do { _Pragma("unroll") for (int n = 0; n < 2; ++n) _Pragma("unroll") for (int k = 0; k < 2; ++k) dst[n][k] = *(const LAS bf16x8*)(lds + PG8_SB(b, h) + boff + n * 2048 + k * 1024); } while (0)
; #define PG8_MMA(ai, bj, At, Bt) do { __builtin_amdgcn_s_setprio(1); _Pragma("unroll") for (int m = 0; m < 4; ++m) _Pragma("unroll") for (int n = 0; n < 2; ++n) _Pragma("unroll") for (int k = 0; k < 2; ++k) \
;         acc[ai][bj][m][n] = __builtin_amdgcn_mfma_f32_16x16x32_bf16(Bt[n][k], At[m][k], acc[ai][bj][m][n], 0, 0, 0); __builtin_amdgcn_s_setprio(0); } while (0)
; #define PG8_WAIT_V(n) asm volatile("s_waitcnt vmcnt(" #n ")" ::: "memory")
; #define PG8_WAIT_L(n) asm volatile("s_waitcnt lgkmcnt(" #n ")" ::: "memory")
; #define PG8_BAR __builtin_amdgcn_s_barrier()
; #define PG8_SCHED __builtin_amdgcn_sched_barrier(0)
; template <class Epi>
; __device__ __forceinline__ void gemm_phase(ldsp lds, const Gemm g, const StaticOrder& S, const Epi& E, int wave0) {
;     ...
;         for (int t = 0; t < nt; t += 2) {
;             const bool last = (t == nt - 2);
;             const char* a1 = cA + (size_t)(t + 1) * kstep;
;             const char* a2 = last ? nA : cA + (size_t)(t + 2) * kstep; const char* b2 = last ? nB : cB + (size_t)(t + 2) * kstep;
;             const char* a3 = a2 + kstep; const char* b3 = b2 + kstep;
;             PG8_LDB(B0, 0, 0); PG8_LDB(B1, 0, 1); PG8_SCHED; PG8_LDA(At, 0, 0); PG8_STAGE(PG8_SA(1, 1), a1 + hstep, voffA);
;             PG8_WAIT_V(8); PG8_WAIT_L(0); PG8_BAR; PG8_MMA(0, 0, At, B0); PG8_MMA(0, 1, At, B1); PG8_BAR; PG8_SCHED;
;             PG8_LDA(At, 0, 1); PG8_STAGE(PG8_SB(0, 0), b2, voffB); PG8_STAGE(PG8_SB(0, 1), b2 + hstep, voffB); PG8_STAGE(PG8_SA(0, 0), a2, voffA);
;             PG8_WAIT_V(8); PG8_WAIT_L(0); PG8_BAR; PG8_MMA(1, 0, At, B0); PG8_MMA(1, 1, At, B1); PG8_BAR; PG8_SCHED;
.LBB0_961:
	s_add_u32 s36, s34, 0x100
	s_addc_u32 s37, s35, 0
	s_cmpk_eq_i32 s67, 0x54
	s_cselect_b32 s41, s5, s37
	s_cselect_b32 s40, s4, s36
	s_cselect_b32 s39, s31, s66
	s_cselect_b32 s38, s30, s65
	s_add_i32 m0, s49, 0xc000
	s_nop 0
	global_load_lds_dwordx4 v138, s[34:35]
	s_add_i32 m0, s49, 0xe000
	s_nop 0
	global_load_lds_dwordx4 v136, s[34:35]
	ds_read_b128 v[152:155], v149
	ds_read_b128 v[156:159], v149 offset:1024
	ds_read_b128 v[160:163], v149 offset:2048
	ds_read_b128 v[164:167], v149 offset:3072
	ds_read_b128 v[168:171], v150
	ds_read_b128 v[172:175], v150 offset:1024
	ds_read_b128 v[176:179], v150 offset:2048
	ds_read_b128 v[180:183], v150 offset:3072
	ds_read_b128 v[184:187], v151
	ds_read_b128 v[188:191], v151 offset:1024
	ds_read_b128 v[192:195], v151 offset:2048
	ds_read_b128 v[196:199], v151 offset:3072
	ds_read_b128 v[200:203], v151 offset:4096
	ds_read_b128 v[204:207], v151 offset:5120
	ds_read_b128 v[208:211], v151 offset:6144
	ds_read_b128 v[212:215], v151 offset:7168
	s_waitcnt vmcnt(8)
	s_waitcnt lgkmcnt(0)
	s_barrier
	s_setprio 1
	s_waitcnt lgkmcnt(0)
	v_mfma_f32_16x16x32_bf16 v[124:127], v[152:155], v[184:187], v[124:127]
	v_mfma_f32_16x16x32_bf16 v[120:123], v[160:163], v[184:187], v[120:123]
	v_mfma_f32_16x16x32_bf16 v[108:111], v[152:155], v[192:195], v[108:111]
	v_mfma_f32_16x16x32_bf16 v[104:107], v[160:163], v[192:195], v[104:107]
	v_mfma_f32_16x16x32_bf16 v[92:95], v[152:155], v[200:203], v[92:95]
	v_mfma_f32_16x16x32_bf16 v[88:91], v[160:163], v[200:203], v[88:91]
	v_mfma_f32_16x16x32_bf16 v[76:79], v[152:155], v[208:211], v[76:79]
	v_mfma_f32_16x16x32_bf16 v[72:75], v[160:163], v[208:211], v[72:75]
	v_mfma_f32_16x16x32_bf16 v[124:127], v[156:159], v[188:191], v[124:127]
	v_mfma_f32_16x16x32_bf16 v[120:123], v[164:167], v[188:191], v[120:123]
	v_mfma_f32_16x16x32_bf16 v[108:111], v[156:159], v[196:199], v[108:111]
	v_mfma_f32_16x16x32_bf16 v[104:107], v[164:167], v[196:199], v[104:107]
	v_mfma_f32_16x16x32_bf16 v[92:95], v[156:159], v[204:207], v[92:95]
	v_mfma_f32_16x16x32_bf16 v[88:91], v[164:167], v[204:207], v[88:91]
	v_mfma_f32_16x16x32_bf16 v[76:79], v[156:159], v[212:215], v[76:79]
	v_mfma_f32_16x16x32_bf16 v[72:75], v[164:167], v[212:215], v[72:75]
	s_setprio 0
	s_setprio 1
	v_mfma_f32_16x16x32_bf16 v[116:119], v[168:171], v[184:187], v[116:119]
	v_mfma_f32_16x16x32_bf16 v[112:115], v[176:179], v[184:187], v[112:115]
	v_mfma_f32_16x16x32_bf16 v[100:103], v[168:171], v[192:195], v[100:103]
	v_mfma_f32_16x16x32_bf16 v[96:99], v[176:179], v[192:195], v[96:99]
	v_mfma_f32_16x16x32_bf16 v[84:87], v[168:171], v[200:203], v[84:87]
	v_mfma_f32_16x16x32_bf16 v[80:83], v[176:179], v[200:203], v[80:83]
	v_mfma_f32_16x16x32_bf16 v[68:71], v[168:171], v[208:211], v[68:71]
	v_mfma_f32_16x16x32_bf16 v[64:67], v[176:179], v[208:211], v[64:67]
	v_mfma_f32_16x16x32_bf16 v[116:119], v[172:175], v[188:191], v[116:119]
	v_mfma_f32_16x16x32_bf16 v[112:115], v[180:183], v[188:191], v[112:115]
	v_mfma_f32_16x16x32_bf16 v[100:103], v[172:175], v[196:199], v[100:103]
	v_mfma_f32_16x16x32_bf16 v[96:99], v[180:183], v[196:199], v[96:99]
	v_mfma_f32_16x16x32_bf16 v[84:87], v[172:175], v[204:207], v[84:87]
	v_mfma_f32_16x16x32_bf16 v[80:83], v[180:183], v[204:207], v[80:83]
	v_mfma_f32_16x16x32_bf16 v[68:71], v[172:175], v[212:215], v[68:71]
	v_mfma_f32_16x16x32_bf16 v[64:67], v[180:183], v[212:215], v[64:67]
	s_setprio 0
	s_barrier
	s_add_i32 s34, s59, s48
	s_mov_b32 m0, s34
	s_nop 0
	global_load_lds_dwordx4 v130, s[38:39]
	s_add_i32 m0, s34, 0x2000
	s_add_u32 s34, s38, 0x160000
	s_addc_u32 s35, s39, 0
	s_add_i32 s68, s60, s48
	global_load_lds_dwordx4 v134, s[38:39]
	s_mov_b32 m0, s68
	s_nop 0
	global_load_lds_dwordx4 v130, s[34:35]
	s_add_i32 m0, s68, 0x2000
	s_nop 0
	global_load_lds_dwordx4 v134, s[34:35]
	s_mov_b32 m0, s49
	s_nop 0
	global_load_lds_dwordx4 v128, s[40:41]
	s_mov_b32 m0, s50
	s_nop 0
	global_load_lds_dwordx4 v132, s[40:41]
	ds_read_b128 v[184:187], v151 offset:16384
	ds_read_b128 v[188:191], v151 offset:17408
	ds_read_b128 v[192:195], v151 offset:18432
	ds_read_b128 v[196:199], v151 offset:19456
	ds_read_b128 v[200:203], v151 offset:20480
	ds_read_b128 v[204:207], v151 offset:21504
	ds_read_b128 v[208:211], v151 offset:22528
	ds_read_b128 v[212:215], v151 offset:23552
	s_waitcnt vmcnt(8)
	s_waitcnt lgkmcnt(0)
	s_barrier
	s_setprio 1
	s_waitcnt lgkmcnt(0)
	v_mfma_f32_16x16x32_bf16 v[60:63], v[152:155], v[184:187], v[60:63]
	v_mfma_f32_16x16x32_bf16 v[56:59], v[160:163], v[184:187], v[56:59]
	v_mfma_f32_16x16x32_bf16 v[44:47], v[152:155], v[192:195], v[44:47]
	v_mfma_f32_16x16x32_bf16 v[40:43], v[160:163], v[192:195], v[40:43]
	v_mfma_f32_16x16x32_bf16 v[28:31], v[152:155], v[200:203], v[28:31]
	v_mfma_f32_16x16x32_bf16 v[24:27], v[160:163], v[200:203], v[24:27]
	v_mfma_f32_16x16x32_bf16 v[12:15], v[152:155], v[208:211], v[12:15]
	v_mfma_f32_16x16x32_bf16 v[8:11], v[160:163], v[208:211], v[8:11]
	v_mfma_f32_16x16x32_bf16 v[60:63], v[156:159], v[188:191], v[60:63]
	v_mfma_f32_16x16x32_bf16 v[56:59], v[164:167], v[188:191], v[56:59]
	v_mfma_f32_16x16x32_bf16 v[44:47], v[156:159], v[196:199], v[44:47]
	v_mfma_f32_16x16x32_bf16 v[40:43], v[164:167], v[196:199], v[40:43]
	v_mfma_f32_16x16x32_bf16 v[28:31], v[156:159], v[204:207], v[28:31]
	v_mfma_f32_16x16x32_bf16 v[24:27], v[164:167], v[204:207], v[24:27]
	v_mfma_f32_16x16x32_bf16 v[12:15], v[156:159], v[212:215], v[12:15]
	v_mfma_f32_16x16x32_bf16 v[8:11], v[164:167], v[212:215], v[8:11]
	s_setprio 0
	s_setprio 1
	v_mfma_f32_16x16x32_bf16 v[52:55], v[168:171], v[184:187], v[52:55]
	v_mfma_f32_16x16x32_bf16 v[48:51], v[176:179], v[184:187], v[48:51]
	v_mfma_f32_16x16x32_bf16 v[36:39], v[168:171], v[192:195], v[36:39]
	v_mfma_f32_16x16x32_bf16 v[32:35], v[176:179], v[192:195], v[32:35]
	v_mfma_f32_16x16x32_bf16 v[20:23], v[168:171], v[200:203], v[20:23]
	v_mfma_f32_16x16x32_bf16 v[16:19], v[176:179], v[200:203], v[16:19]
	v_mfma_f32_16x16x32_bf16 v[4:7], v[168:171], v[208:211], v[4:7]
	v_mfma_f32_16x16x32_bf16 v[0:3], v[176:179], v[208:211], v[0:3]
	v_mfma_f32_16x16x32_bf16 v[52:55], v[172:175], v[188:191], v[52:55]
	v_mfma_f32_16x16x32_bf16 v[48:51], v[180:183], v[188:191], v[48:51]
	v_mfma_f32_16x16x32_bf16 v[36:39], v[172:175], v[196:199], v[36:39]
	v_mfma_f32_16x16x32_bf16 v[32:35], v[180:183], v[196:199], v[32:35]
	v_mfma_f32_16x16x32_bf16 v[20:23], v[172:175], v[204:207], v[20:23]
	v_mfma_f32_16x16x32_bf16 v[16:19], v[180:183], v[204:207], v[16:19]
	v_mfma_f32_16x16x32_bf16 v[4:7], v[172:175], v[212:215], v[4:7]
	v_mfma_f32_16x16x32_bf16 v[0:3], v[180:183], v[212:215], v[0:3]
	s_setprio 0
	s_barrier
; #define PG8_STAGE(bufoff, gbase, voff) do { _Pragma("unroll") for (int _i = 0; _i < 2; ++_i) \
;         __builtin_amdgcn_global_load_lds((const unsigned*)((const char*)(gbase) + (voff)[_i]), (LAS unsigned*)(lds + (bufoff) + ldsw + _i * 8192), 16, 0, 0); } while (0)
; #define PG8_LDA(dst, b, h) do { _Pragma("unroll") for (int m = 0; m < 4; ++m) _Pragma("unroll") for (int k = 0; k < 2; ++k) dst[m][k] = *(const LAS bf16x8*)(lds + PG8_SA(b, h) + aoff + m * 2048 + k * 1024); } while (0)
; #define PG8_LDB(dst, b, h) do { _Pragma("unroll") for (int n = 0; n < 2; ++n) _Pragma("unroll") for (int k = 0; k < 2; ++k) dst[n][k] = *(const LAS bf16x8*)(lds + PG8_SB(b, h) + boff + n * 2048 + k * 1024); } while (0)
; #define PG8_MMA(ai, bj, At, Bt) do { __builtin_amdgcn_s_setprio(1); _Pragma("unroll") for (int m = 0; m < 4; ++m) _Pragma("unroll") for (int n = 0; n < 2; ++n) _Pragma("unroll") for (int k = 0; k < 2; ++k) \
;         acc[ai][bj][m][n] = __builtin_amdgcn_mfma_f32_16x16x32_bf16(Bt[n][k], At[m][k], acc[ai][bj][m][n], 0, 0, 0); __builtin_amdgcn_s_setprio(0); } while (0)
; #define PG8_WAIT_V(n) asm volatile("s_waitcnt vmcnt(" #n ")" ::: "memory")
; #define PG8_WAIT_L(n) asm volatile("s_waitcnt lgkmcnt(" #n ")" ::: "memory")
; #define PG8_BAR __builtin_amdgcn_s_barrier()
; #define PG8_SCHED __builtin_amdgcn_sched_barrier(0)
; template <class Epi>
; __device__ __forceinline__ void gemm_phase(ldsp lds, const Gemm g, const StaticOrder& S, const Epi& E, int wave0) {
;     ...
;             PG8_LDB(B0, 1, 0); PG8_LDB(B1, 1, 1); PG8_SCHED; PG8_LDA(At, 1, 0); PG8_STAGE(PG8_SA(0, 1), a2 + hstep, voffA);
;             PG8_WAIT_V(8); PG8_WAIT_L(0); PG8_BAR; PG8_MMA(0, 0, At, B0); PG8_MMA(0, 1, At, B1); PG8_BAR; PG8_SCHED;
;             PG8_LDA(At, 1, 1); PG8_STAGE(PG8_SB(1, 0), b3, voffB); PG8_STAGE(PG8_SB(1, 1), b3 + hstep, voffB); PG8_STAGE(PG8_SA(1, 0), a3, voffA);
;             PG8_WAIT_V(8); PG8_WAIT_L(0); PG8_BAR; PG8_MMA(1, 0, At, B0); PG8_MMA(1, 1, At, B1); PG8_BAR; PG8_SCHED;
;         }
;         if (wr == 0) PG8_BAR;
	s_add_i32 s68, 0, 0x18000
	s_add_i32 s69, 0, 0x1c000
	v_add_u32_e32 v164, s68, v148
	v_add_u32_e32 v180, s69, v148
	s_add_u32 s34, s40, 0x160000
	s_addc_u32 s35, s41, 0
	s_mov_b32 m0, s51
	s_nop 0
	global_load_lds_dwordx4 v128, s[34:35]
	s_mov_b32 m0, s52
	s_nop 0
	global_load_lds_dwordx4 v132, s[34:35]
	ds_read_b128 v[152:155], v164
	ds_read_b128 v[156:159], v164 offset:1024
	ds_read_b128 v[160:163], v164 offset:2048
	ds_read_b128 v[164:167], v164 offset:3072
	ds_read_b128 v[168:171], v180
	ds_read_b128 v[172:175], v180 offset:1024
	ds_read_b128 v[176:179], v180 offset:2048
	ds_read_b128 v[180:183], v180 offset:3072
	ds_read_b128 v[184:187], v151 offset:32768
	ds_read_b128 v[188:191], v151 offset:33792
	ds_read_b128 v[192:195], v151 offset:34816
	ds_read_b128 v[196:199], v151 offset:35840
	ds_read_b128 v[200:203], v151 offset:36864
	ds_read_b128 v[204:207], v151 offset:37888
	ds_read_b128 v[208:211], v151 offset:38912
	ds_read_b128 v[212:215], v151 offset:39936
	s_waitcnt vmcnt(8)
	s_waitcnt lgkmcnt(0)
	s_barrier
	s_setprio 1
	s_waitcnt lgkmcnt(0)
	v_mfma_f32_16x16x32_bf16 v[124:127], v[152:155], v[184:187], v[124:127]
	v_mfma_f32_16x16x32_bf16 v[120:123], v[160:163], v[184:187], v[120:123]
	v_mfma_f32_16x16x32_bf16 v[108:111], v[152:155], v[192:195], v[108:111]
	v_mfma_f32_16x16x32_bf16 v[104:107], v[160:163], v[192:195], v[104:107]
	v_mfma_f32_16x16x32_bf16 v[92:95], v[152:155], v[200:203], v[92:95]
	v_mfma_f32_16x16x32_bf16 v[88:91], v[160:163], v[200:203], v[88:91]
	v_mfma_f32_16x16x32_bf16 v[76:79], v[152:155], v[208:211], v[76:79]
	v_mfma_f32_16x16x32_bf16 v[72:75], v[160:163], v[208:211], v[72:75]
	v_mfma_f32_16x16x32_bf16 v[124:127], v[156:159], v[188:191], v[124:127]
	v_mfma_f32_16x16x32_bf16 v[120:123], v[164:167], v[188:191], v[120:123]
	v_mfma_f32_16x16x32_bf16 v[108:111], v[156:159], v[196:199], v[108:111]
	v_mfma_f32_16x16x32_bf16 v[104:107], v[164:167], v[196:199], v[104:107]
	v_mfma_f32_16x16x32_bf16 v[92:95], v[156:159], v[204:207], v[92:95]
	v_mfma_f32_16x16x32_bf16 v[88:91], v[164:167], v[204:207], v[88:91]
	v_mfma_f32_16x16x32_bf16 v[76:79], v[156:159], v[212:215], v[76:79]
	v_mfma_f32_16x16x32_bf16 v[72:75], v[164:167], v[212:215], v[72:75]
	s_setprio 0
	s_setprio 1
	v_mfma_f32_16x16x32_bf16 v[116:119], v[168:171], v[184:187], v[116:119]
	v_mfma_f32_16x16x32_bf16 v[112:115], v[176:179], v[184:187], v[112:115]
	v_mfma_f32_16x16x32_bf16 v[100:103], v[168:171], v[192:195], v[100:103]
	v_mfma_f32_16x16x32_bf16 v[96:99], v[176:179], v[192:195], v[96:99]
	v_mfma_f32_16x16x32_bf16 v[84:87], v[168:171], v[200:203], v[84:87]
	v_mfma_f32_16x16x32_bf16 v[80:83], v[176:179], v[200:203], v[80:83]
	v_mfma_f32_16x16x32_bf16 v[68:71], v[168:171], v[208:211], v[68:71]
	v_mfma_f32_16x16x32_bf16 v[64:67], v[176:179], v[208:211], v[64:67]
	v_mfma_f32_16x16x32_bf16 v[116:119], v[172:175], v[188:191], v[116:119]
	v_mfma_f32_16x16x32_bf16 v[112:115], v[180:183], v[188:191], v[112:115]
	v_mfma_f32_16x16x32_bf16 v[100:103], v[172:175], v[196:199], v[100:103]
	v_mfma_f32_16x16x32_bf16 v[96:99], v[180:183], v[196:199], v[96:99]
	v_mfma_f32_16x16x32_bf16 v[84:87], v[172:175], v[204:207], v[84:87]
	v_mfma_f32_16x16x32_bf16 v[80:83], v[180:183], v[204:207], v[80:83]
	v_mfma_f32_16x16x32_bf16 v[68:71], v[172:175], v[212:215], v[68:71]
	v_mfma_f32_16x16x32_bf16 v[64:67], v[180:183], v[212:215], v[64:67]
	s_setprio 0
	s_barrier
	s_add_i32 s34, s68, s48
	s_add_u32 s100, s38, 0x80
	s_addc_u32 s101, s39, 0
	s_add_u32 s98, s40, 0x80
	s_addc_u32 s99, s41, 0
	s_mov_b32 m0, s34
	s_nop 0
	global_load_lds_dwordx4 v130, s[100:101]
	s_add_i32 m0, s34, 0x2000
	s_add_u32 s34, s38, 0x160080
	s_addc_u32 s35, s39, 0
	s_add_i32 s38, s69, s48
	global_load_lds_dwordx4 v134, s[100:101]
	s_mov_b32 m0, s38
	s_nop 0
	global_load_lds_dwordx4 v130, s[34:35]
	s_add_i32 m0, s38, 0x2000
	s_nop 0
	global_load_lds_dwordx4 v134, s[34:35]
	s_mov_b32 m0, s56
	s_nop 0
	global_load_lds_dwordx4 v128, s[98:99]
	s_mov_b32 m0, s57
	s_nop 0
	global_load_lds_dwordx4 v132, s[98:99]
	ds_read_b128 v[184:187], v151 offset:49152
	ds_read_b128 v[188:191], v151 offset:50176
	ds_read_b128 v[192:195], v151 offset:51200
	ds_read_b128 v[196:199], v151 offset:52224
	ds_read_b128 v[200:203], v151 offset:53248
	ds_read_b128 v[204:207], v151 offset:54272
	ds_read_b128 v[208:211], v151 offset:55296
	ds_read_b128 v[212:215], v151 offset:56320
	s_waitcnt vmcnt(8)
	s_waitcnt lgkmcnt(0)
	s_barrier
	s_setprio 1
	s_waitcnt lgkmcnt(0)
	v_mfma_f32_16x16x32_bf16 v[60:63], v[152:155], v[184:187], v[60:63]
	v_mfma_f32_16x16x32_bf16 v[56:59], v[160:163], v[184:187], v[56:59]
	v_mfma_f32_16x16x32_bf16 v[44:47], v[152:155], v[192:195], v[44:47]
	v_mfma_f32_16x16x32_bf16 v[40:43], v[160:163], v[192:195], v[40:43]
	v_mfma_f32_16x16x32_bf16 v[28:31], v[152:155], v[200:203], v[28:31]
	v_mfma_f32_16x16x32_bf16 v[24:27], v[160:163], v[200:203], v[24:27]
	v_mfma_f32_16x16x32_bf16 v[12:15], v[152:155], v[208:211], v[12:15]
	v_mfma_f32_16x16x32_bf16 v[8:11], v[160:163], v[208:211], v[8:11]
	v_mfma_f32_16x16x32_bf16 v[60:63], v[156:159], v[188:191], v[60:63]
	v_mfma_f32_16x16x32_bf16 v[56:59], v[164:167], v[188:191], v[56:59]
	v_mfma_f32_16x16x32_bf16 v[44:47], v[156:159], v[196:199], v[44:47]
	v_mfma_f32_16x16x32_bf16 v[40:43], v[164:167], v[196:199], v[40:43]
	v_mfma_f32_16x16x32_bf16 v[28:31], v[156:159], v[204:207], v[28:31]
	v_mfma_f32_16x16x32_bf16 v[24:27], v[164:167], v[204:207], v[24:27]
	v_mfma_f32_16x16x32_bf16 v[12:15], v[156:159], v[212:215], v[12:15]
	v_mfma_f32_16x16x32_bf16 v[8:11], v[164:167], v[212:215], v[8:11]
	s_setprio 0
	s_setprio 1
	v_mfma_f32_16x16x32_bf16 v[52:55], v[168:171], v[184:187], v[52:55]
	v_mfma_f32_16x16x32_bf16 v[48:51], v[176:179], v[184:187], v[48:51]
	v_mfma_f32_16x16x32_bf16 v[36:39], v[168:171], v[192:195], v[36:39]
	v_mfma_f32_16x16x32_bf16 v[32:35], v[176:179], v[192:195], v[32:35]
	v_mfma_f32_16x16x32_bf16 v[20:23], v[168:171], v[200:203], v[20:23]
	v_mfma_f32_16x16x32_bf16 v[16:19], v[176:179], v[200:203], v[16:19]
	v_mfma_f32_16x16x32_bf16 v[4:7], v[168:171], v[208:211], v[4:7]
	v_mfma_f32_16x16x32_bf16 v[0:3], v[176:179], v[208:211], v[0:3]
	v_mfma_f32_16x16x32_bf16 v[52:55], v[172:175], v[188:191], v[52:55]
	v_mfma_f32_16x16x32_bf16 v[48:51], v[180:183], v[188:191], v[48:51]
	v_mfma_f32_16x16x32_bf16 v[36:39], v[172:175], v[196:199], v[36:39]
	v_mfma_f32_16x16x32_bf16 v[32:35], v[180:183], v[196:199], v[32:35]
	v_mfma_f32_16x16x32_bf16 v[20:23], v[172:175], v[204:207], v[20:23]
	v_mfma_f32_16x16x32_bf16 v[16:19], v[180:183], v[204:207], v[16:19]
	v_mfma_f32_16x16x32_bf16 v[4:7], v[172:175], v[212:215], v[4:7]
	v_mfma_f32_16x16x32_bf16 v[0:3], v[180:183], v[212:215], v[0:3]
	s_setprio 0
	s_barrier
	s_add_i32 s67, s67, 2
	s_add_u32 s65, s65, 0x100
	s_addc_u32 s66, s66, 0
	s_cmpk_gt_u32 s67, 0x55
	s_mov_b64 s[34:35], s[36:37]
	s_cbranch_scc0 .LBB0_961
	s_and_b64 vcc, exec, s[12:13]
	s_cbranch_vccz .LBB0_964
	s_barrier

; #define PG8_STAGE(bufoff, gbase, voff) do { _Pragma("unroll") for (int _i = 0; _i < 2; ++_i) \
;         __builtin_amdgcn_global_load_lds((const unsigned*)((const char*)(gbase) + (voff)[_i]), (LAS unsigned*)(lds + (bufoff) + ldsw + _i * 8192), 16, 0, 0); } while (0)
; #define PG8_LDA(dst, b, h) do { _Pragma("unroll") for (int m = 0; m < 4; ++m) _Pragma("unroll") for (int k = 0; k < 2; ++k) dst[m][k] = *(const LAS bf16x8*)(lds + PG8_SA(b, h) + aoff + m * 2048 + k * 1024); } while (0)
; #define PG8_LDB(dst, b, h) do { _Pragma("unroll") for (int n = 0; n < 2; ++n) _Pragma("unroll") for (int k = 0; k < 2; ++k) dst[n][k] = *(const LAS bf16x8*)(lds + PG8_SB(b, h) + boff + n * 2048 + k * 1024); } while (0)
; #define PG8_MMA(ai, bj, At, Bt) do { __builtin_amdgcn_s_setprio(1); _Pragma("unroll") for (int m = 0; m < 4; ++m) _Pragma("unroll") for (int n = 0; n < 2; ++n) _Pragma("unroll") for (int k = 0; k < 2; ++k) \
;         acc[ai][bj][m][n] = __builtin_amdgcn_mfma_f32_16x16x32_bf16(Bt[n][k], At[m][k], acc[ai][bj][m][n], 0, 0, 0); __builtin_amdgcn_s_setprio(0); } while (0)
; #define PG8_WAIT_V(n) asm volatile("s_waitcnt vmcnt(" #n ")" ::: "memory")
; #define PG8_WAIT_L(n) asm volatile("s_waitcnt lgkmcnt(" #n ")" ::: "memory")
; #define PG8_BAR __builtin_amdgcn_s_barrier()
; #define PG8_SCHED __builtin_amdgcn_sched_barrier(0)
; template <class Epi>
; __device__ __forceinline__ void gemm_phase(ldsp lds, const Gemm g, const StaticOrder& S, const Epi& E, int wave0) {
;     ...
;             const char* a1 = cA + (size_t)(t + 1) * kstep;
;             const char* a2 = last ? nA : cA + (size_t)(t + 2) * kstep; const char* b2 = last ? nB : cB + (size_t)(t + 2) * kstep;
;             const char* a3 = a2 + kstep; const char* b3 = b2 + kstep;
;             PG8_LDB(B0, 0, 0); PG8_LDB(B1, 0, 1); PG8_SCHED; PG8_LDA(At, 0, 0); PG8_STAGE(PG8_SA(1, 1), a1 + hstep, voffA);
;             PG8_WAIT_V(8); PG8_WAIT_L(0); PG8_BAR; PG8_MMA(0, 0, At, B0); PG8_MMA(0, 1, At, B1); PG8_BAR; PG8_SCHED;
;             PG8_LDA(At, 0, 1); PG8_STAGE(PG8_SB(0, 0), b2, voffB); PG8_STAGE(PG8_SB(0, 1), b2 + hstep, voffB); PG8_STAGE(PG8_SA(0, 0), a2, voffA);
;             PG8_WAIT_V(8); PG8_WAIT_L(0); PG8_BAR; PG8_MMA(1, 0, At, B0); PG8_MMA(1, 1, At, B1); PG8_BAR; PG8_SCHED;
.LBB0_1099:
	s_add_u32 s44, s42, 0xfff80080
	s_addc_u32 s45, s43, -1
	s_cmp_eq_u32 s69, 28
	s_cselect_b32 s47, s35, s45
	s_cselect_b32 s46, s65, s44
	s_cselect_b32 s45, s31, s68
	s_cselect_b32 s44, s66, s67
	s_add_i32 m0, s41, 0xc000
	s_nop 0
	global_load_lds_dwordx4 v138, s[42:43]
	s_add_i32 m0, s41, 0xe000
	s_nop 0
	global_load_lds_dwordx4 v136, s[42:43]
	ds_read_b128 v[152:155], v149
	ds_read_b128 v[156:159], v149 offset:1024
	ds_read_b128 v[160:163], v149 offset:2048
	ds_read_b128 v[164:167], v149 offset:3072
	ds_read_b128 v[168:171], v150
	ds_read_b128 v[172:175], v150 offset:1024
	ds_read_b128 v[176:179], v150 offset:2048
	ds_read_b128 v[180:183], v150 offset:3072
	ds_read_b128 v[184:187], v151
	ds_read_b128 v[188:191], v151 offset:1024
	ds_read_b128 v[192:195], v151 offset:2048
	ds_read_b128 v[196:199], v151 offset:3072
	ds_read_b128 v[200:203], v151 offset:4096
	ds_read_b128 v[204:207], v151 offset:5120
	ds_read_b128 v[208:211], v151 offset:6144
	ds_read_b128 v[212:215], v151 offset:7168
	s_waitcnt vmcnt(8)
	s_waitcnt lgkmcnt(0)
	s_barrier
	s_setprio 1
	s_waitcnt lgkmcnt(0)
	v_mfma_f32_16x16x32_bf16 v[124:127], v[152:155], v[184:187], v[124:127]
	v_mfma_f32_16x16x32_bf16 v[120:123], v[160:163], v[184:187], v[120:123]
	v_mfma_f32_16x16x32_bf16 v[108:111], v[152:155], v[192:195], v[108:111]
	v_mfma_f32_16x16x32_bf16 v[104:107], v[160:163], v[192:195], v[104:107]
	v_mfma_f32_16x16x32_bf16 v[92:95], v[152:155], v[200:203], v[92:95]
	v_mfma_f32_16x16x32_bf16 v[88:91], v[160:163], v[200:203], v[88:91]
	v_mfma_f32_16x16x32_bf16 v[76:79], v[152:155], v[208:211], v[76:79]
	v_mfma_f32_16x16x32_bf16 v[72:75], v[160:163], v[208:211], v[72:75]
	v_mfma_f32_16x16x32_bf16 v[124:127], v[156:159], v[188:191], v[124:127]
	v_mfma_f32_16x16x32_bf16 v[120:123], v[164:167], v[188:191], v[120:123]
	v_mfma_f32_16x16x32_bf16 v[108:111], v[156:159], v[196:199], v[108:111]
	v_mfma_f32_16x16x32_bf16 v[104:107], v[164:167], v[196:199], v[104:107]
	v_mfma_f32_16x16x32_bf16 v[92:95], v[156:159], v[204:207], v[92:95]
	v_mfma_f32_16x16x32_bf16 v[88:91], v[164:167], v[204:207], v[88:91]
	v_mfma_f32_16x16x32_bf16 v[76:79], v[156:159], v[212:215], v[76:79]
	v_mfma_f32_16x16x32_bf16 v[72:75], v[164:167], v[212:215], v[72:75]
	s_setprio 0
	s_setprio 1
	v_mfma_f32_16x16x32_bf16 v[116:119], v[168:171], v[184:187], v[116:119]
	v_mfma_f32_16x16x32_bf16 v[112:115], v[176:179], v[184:187], v[112:115]
	v_mfma_f32_16x16x32_bf16 v[100:103], v[168:171], v[192:195], v[100:103]
	v_mfma_f32_16x16x32_bf16 v[96:99], v[176:179], v[192:195], v[96:99]
	v_mfma_f32_16x16x32_bf16 v[84:87], v[168:171], v[200:203], v[84:87]
	v_mfma_f32_16x16x32_bf16 v[80:83], v[176:179], v[200:203], v[80:83]
	v_mfma_f32_16x16x32_bf16 v[68:71], v[168:171], v[208:211], v[68:71]
	v_mfma_f32_16x16x32_bf16 v[64:67], v[176:179], v[208:211], v[64:67]
	v_mfma_f32_16x16x32_bf16 v[116:119], v[172:175], v[188:191], v[116:119]
	v_mfma_f32_16x16x32_bf16 v[112:115], v[180:183], v[188:191], v[112:115]
	v_mfma_f32_16x16x32_bf16 v[100:103], v[172:175], v[196:199], v[100:103]
	v_mfma_f32_16x16x32_bf16 v[96:99], v[180:183], v[196:199], v[96:99]
	v_mfma_f32_16x16x32_bf16 v[84:87], v[172:175], v[204:207], v[84:87]
	v_mfma_f32_16x16x32_bf16 v[80:83], v[180:183], v[204:207], v[80:83]
	v_mfma_f32_16x16x32_bf16 v[68:71], v[172:175], v[212:215], v[68:71]
	v_mfma_f32_16x16x32_bf16 v[64:67], v[180:183], v[212:215], v[64:67]
	s_setprio 0
	s_barrier
	s_add_i32 s70, s62, s52
	s_add_u32 s100, s46, 0x80
	s_addc_u32 s101, s47, 0
	s_mov_b32 m0, s70
	s_nop 0
	global_load_lds_dwordx4 v130, s[44:45]
	s_add_i32 m0, s70, 0x2000
	s_add_u32 s70, s44, 0x80000
	s_addc_u32 s71, s45, 0
	s_add_i32 s72, s63, s52
	global_load_lds_dwordx4 v134, s[44:45]
	s_mov_b32 m0, s72
	s_nop 0
	global_load_lds_dwordx4 v130, s[70:71]
	s_add_i32 m0, s72, 0x2000
	s_nop 0
	global_load_lds_dwordx4 v134, s[70:71]
	s_mov_b32 m0, s41
	s_nop 0
	global_load_lds_dwordx4 v128, s[46:47]
	s_mov_b32 m0, s53
	s_nop 0
	global_load_lds_dwordx4 v132, s[46:47]
	ds_read_b128 v[184:187], v151 offset:16384
	ds_read_b128 v[188:191], v151 offset:17408
	ds_read_b128 v[192:195], v151 offset:18432
	ds_read_b128 v[196:199], v151 offset:19456
	ds_read_b128 v[200:203], v151 offset:20480
	ds_read_b128 v[204:207], v151 offset:21504
	ds_read_b128 v[208:211], v151 offset:22528
	ds_read_b128 v[212:215], v151 offset:23552
	s_waitcnt vmcnt(8)
	s_waitcnt lgkmcnt(0)
	s_barrier
	s_setprio 1
	s_waitcnt lgkmcnt(0)
	v_mfma_f32_16x16x32_bf16 v[60:63], v[152:155], v[184:187], v[60:63]
	v_mfma_f32_16x16x32_bf16 v[56:59], v[160:163], v[184:187], v[56:59]
	v_mfma_f32_16x16x32_bf16 v[44:47], v[152:155], v[192:195], v[44:47]
	v_mfma_f32_16x16x32_bf16 v[40:43], v[160:163], v[192:195], v[40:43]
	v_mfma_f32_16x16x32_bf16 v[28:31], v[152:155], v[200:203], v[28:31]
	v_mfma_f32_16x16x32_bf16 v[24:27], v[160:163], v[200:203], v[24:27]
	v_mfma_f32_16x16x32_bf16 v[12:15], v[152:155], v[208:211], v[12:15]
	v_mfma_f32_16x16x32_bf16 v[8:11], v[160:163], v[208:211], v[8:11]
	v_mfma_f32_16x16x32_bf16 v[60:63], v[156:159], v[188:191], v[60:63]
	v_mfma_f32_16x16x32_bf16 v[56:59], v[164:167], v[188:191], v[56:59]
	v_mfma_f32_16x16x32_bf16 v[44:47], v[156:159], v[196:199], v[44:47]
	v_mfma_f32_16x16x32_bf16 v[40:43], v[164:167], v[196:199], v[40:43]
	v_mfma_f32_16x16x32_bf16 v[28:31], v[156:159], v[204:207], v[28:31]
	v_mfma_f32_16x16x32_bf16 v[24:27], v[164:167], v[204:207], v[24:27]
	v_mfma_f32_16x16x32_bf16 v[12:15], v[156:159], v[212:215], v[12:15]
	v_mfma_f32_16x16x32_bf16 v[8:11], v[164:167], v[212:215], v[8:11]
	s_setprio 0
	s_setprio 1
	v_mfma_f32_16x16x32_bf16 v[52:55], v[168:171], v[184:187], v[52:55]
	v_mfma_f32_16x16x32_bf16 v[48:51], v[176:179], v[184:187], v[48:51]
	v_mfma_f32_16x16x32_bf16 v[36:39], v[168:171], v[192:195], v[36:39]
	v_mfma_f32_16x16x32_bf16 v[32:35], v[176:179], v[192:195], v[32:35]
	v_mfma_f32_16x16x32_bf16 v[20:23], v[168:171], v[200:203], v[20:23]
	v_mfma_f32_16x16x32_bf16 v[16:19], v[176:179], v[200:203], v[16:19]
	v_mfma_f32_16x16x32_bf16 v[4:7], v[168:171], v[208:211], v[4:7]
	v_mfma_f32_16x16x32_bf16 v[0:3], v[176:179], v[208:211], v[0:3]
	v_mfma_f32_16x16x32_bf16 v[52:55], v[172:175], v[188:191], v[52:55]
	v_mfma_f32_16x16x32_bf16 v[48:51], v[180:183], v[188:191], v[48:51]
	v_mfma_f32_16x16x32_bf16 v[36:39], v[172:175], v[196:199], v[36:39]
	v_mfma_f32_16x16x32_bf16 v[32:35], v[180:183], v[196:199], v[32:35]
	v_mfma_f32_16x16x32_bf16 v[20:23], v[172:175], v[204:207], v[20:23]
	v_mfma_f32_16x16x32_bf16 v[16:19], v[180:183], v[204:207], v[16:19]
	v_mfma_f32_16x16x32_bf16 v[4:7], v[172:175], v[212:215], v[4:7]
	v_mfma_f32_16x16x32_bf16 v[0:3], v[180:183], v[212:215], v[0:3]
	s_setprio 0
	s_barrier
; #define PG8_STAGE(bufoff, gbase, voff) do { _Pragma("unroll") for (int _i = 0; _i < 2; ++_i) \
;         __builtin_amdgcn_global_load_lds((const unsigned*)((const char*)(gbase) + (voff)[_i]), (LAS unsigned*)(lds + (bufoff) + ldsw + _i * 8192), 16, 0, 0); } while (0)
; #define PG8_LDA(dst, b, h) do { _Pragma("unroll") for (int m = 0; m < 4; ++m) _Pragma("unroll") for (int k = 0; k < 2; ++k) dst[m][k] = *(const LAS bf16x8*)(lds + PG8_SA(b, h) + aoff + m * 2048 + k * 1024); } while (0)
; #define PG8_LDB(dst, b, h) do { _Pragma("unroll") for (int n = 0; n < 2; ++n) _Pragma("unroll") for (int k = 0; k < 2; ++k) dst[n][k] = *(const LAS bf16x8*)(lds + PG8_SB(b, h) + boff + n * 2048 + k * 1024); } while (0)
; #define PG8_MMA(ai, bj, At, Bt) do { __builtin_amdgcn_s_setprio(1); _Pragma("unroll") for (int m = 0; m < 4; ++m) _Pragma("unroll") for (int n = 0; n < 2; ++n) _Pragma("unroll") for (int k = 0; k < 2; ++k) \
;         acc[ai][bj][m][n] = __builtin_amdgcn_mfma_f32_16x16x32_bf16(Bt[n][k], At[m][k], acc[ai][bj][m][n], 0, 0, 0); __builtin_amdgcn_s_setprio(0); } while (0)
; #define PG8_WAIT_V(n) asm volatile("s_waitcnt vmcnt(" #n ")" ::: "memory")
; #define PG8_WAIT_L(n) asm volatile("s_waitcnt lgkmcnt(" #n ")" ::: "memory")
; #define PG8_BAR __builtin_amdgcn_s_barrier()
; #define PG8_SCHED __builtin_amdgcn_sched_barrier(0)
; template <class Epi>
; __device__ __forceinline__ void gemm_phase(ldsp lds, const Gemm g, const StaticOrder& S, const Epi& E, int wave0) {
;     ...
;             PG8_LDB(B0, 1, 0); PG8_LDB(B1, 1, 1); PG8_SCHED; PG8_LDA(At, 1, 0); PG8_STAGE(PG8_SA(0, 1), a2 + hstep, voffA);
;             PG8_WAIT_V(8); PG8_WAIT_L(0); PG8_BAR; PG8_MMA(0, 0, At, B0); PG8_MMA(0, 1, At, B1); PG8_BAR; PG8_SCHED;
;             PG8_LDA(At, 1, 1); PG8_STAGE(PG8_SB(1, 0), b3, voffB); PG8_STAGE(PG8_SB(1, 1), b3 + hstep, voffB); PG8_STAGE(PG8_SA(1, 0), a3, voffA);
;             PG8_WAIT_V(8); PG8_WAIT_L(0); PG8_BAR; PG8_MMA(1, 0, At, B0); PG8_MMA(1, 1, At, B1); PG8_BAR; PG8_SCHED;
;         }
;         if (wr == 0) PG8_BAR;
	s_add_i32 s70, 0, 0x18000
	s_add_i32 s71, 0, 0x1c000
	v_add_u32_e32 v164, s70, v148
	v_add_u32_e32 v180, s71, v148
	s_add_u32 s46, s46, 0x80000
	s_addc_u32 s47, s47, 0
	s_mov_b32 m0, s54
	s_nop 0
	global_load_lds_dwordx4 v128, s[46:47]
	s_mov_b32 m0, s55
	s_nop 0
	global_load_lds_dwordx4 v132, s[46:47]
	ds_read_b128 v[152:155], v164
	ds_read_b128 v[156:159], v164 offset:1024
	ds_read_b128 v[160:163], v164 offset:2048
	ds_read_b128 v[164:167], v164 offset:3072
	ds_read_b128 v[168:171], v180
	ds_read_b128 v[172:175], v180 offset:1024
	ds_read_b128 v[176:179], v180 offset:2048
	ds_read_b128 v[180:183], v180 offset:3072
	ds_read_b128 v[184:187], v151 offset:32768
	ds_read_b128 v[188:191], v151 offset:33792
	ds_read_b128 v[192:195], v151 offset:34816
	ds_read_b128 v[196:199], v151 offset:35840
	ds_read_b128 v[200:203], v151 offset:36864
	ds_read_b128 v[204:207], v151 offset:37888
	ds_read_b128 v[208:211], v151 offset:38912
	ds_read_b128 v[212:215], v151 offset:39936
	s_waitcnt vmcnt(8)
	s_waitcnt lgkmcnt(0)
	s_barrier
	s_setprio 1
	s_waitcnt lgkmcnt(0)
	v_mfma_f32_16x16x32_bf16 v[124:127], v[152:155], v[184:187], v[124:127]
	v_mfma_f32_16x16x32_bf16 v[120:123], v[160:163], v[184:187], v[120:123]
	v_mfma_f32_16x16x32_bf16 v[108:111], v[152:155], v[192:195], v[108:111]
	v_mfma_f32_16x16x32_bf16 v[104:107], v[160:163], v[192:195], v[104:107]
	v_mfma_f32_16x16x32_bf16 v[92:95], v[152:155], v[200:203], v[92:95]
	v_mfma_f32_16x16x32_bf16 v[88:91], v[160:163], v[200:203], v[88:91]
	v_mfma_f32_16x16x32_bf16 v[76:79], v[152:155], v[208:211], v[76:79]
	v_mfma_f32_16x16x32_bf16 v[72:75], v[160:163], v[208:211], v[72:75]
	v_mfma_f32_16x16x32_bf16 v[124:127], v[156:159], v[188:191], v[124:127]
	v_mfma_f32_16x16x32_bf16 v[120:123], v[164:167], v[188:191], v[120:123]
	v_mfma_f32_16x16x32_bf16 v[108:111], v[156:159], v[196:199], v[108:111]
	v_mfma_f32_16x16x32_bf16 v[104:107], v[164:167], v[196:199], v[104:107]
	v_mfma_f32_16x16x32_bf16 v[92:95], v[156:159], v[204:207], v[92:95]
	v_mfma_f32_16x16x32_bf16 v[88:91], v[164:167], v[204:207], v[88:91]
	v_mfma_f32_16x16x32_bf16 v[76:79], v[156:159], v[212:215], v[76:79]
	v_mfma_f32_16x16x32_bf16 v[72:75], v[164:167], v[212:215], v[72:75]
	s_setprio 0
	s_setprio 1
	v_mfma_f32_16x16x32_bf16 v[116:119], v[168:171], v[184:187], v[116:119]
	v_mfma_f32_16x16x32_bf16 v[112:115], v[176:179], v[184:187], v[112:115]
	v_mfma_f32_16x16x32_bf16 v[100:103], v[168:171], v[192:195], v[100:103]
	v_mfma_f32_16x16x32_bf16 v[96:99], v[176:179], v[192:195], v[96:99]
	v_mfma_f32_16x16x32_bf16 v[84:87], v[168:171], v[200:203], v[84:87]
	v_mfma_f32_16x16x32_bf16 v[80:83], v[176:179], v[200:203], v[80:83]
	v_mfma_f32_16x16x32_bf16 v[68:71], v[168:171], v[208:211], v[68:71]
	v_mfma_f32_16x16x32_bf16 v[64:67], v[176:179], v[208:211], v[64:67]
	v_mfma_f32_16x16x32_bf16 v[116:119], v[172:175], v[188:191], v[116:119]
	v_mfma_f32_16x16x32_bf16 v[112:115], v[180:183], v[188:191], v[112:115]
	v_mfma_f32_16x16x32_bf16 v[100:103], v[172:175], v[196:199], v[100:103]
	v_mfma_f32_16x16x32_bf16 v[96:99], v[180:183], v[196:199], v[96:99]
	v_mfma_f32_16x16x32_bf16 v[84:87], v[172:175], v[204:207], v[84:87]
	v_mfma_f32_16x16x32_bf16 v[80:83], v[180:183], v[204:207], v[80:83]
	v_mfma_f32_16x16x32_bf16 v[68:71], v[172:175], v[212:215], v[68:71]
	v_mfma_f32_16x16x32_bf16 v[64:67], v[180:183], v[212:215], v[64:67]
	s_setprio 0
	s_barrier
	s_add_i32 s46, s70, s52
	s_add_u32 s44, s44, 0x80
	s_addc_u32 s45, s45, 0
	s_mov_b32 m0, s46
	s_nop 0
	global_load_lds_dwordx4 v130, s[44:45]
	s_add_i32 m0, s46, 0x2000
	s_add_i32 s46, s71, s52
	global_load_lds_dwordx4 v134, s[44:45]
	s_add_u32 s44, s44, 0x80000
	s_addc_u32 s45, s45, 0
	s_mov_b32 m0, s46
	s_nop 0
	global_load_lds_dwordx4 v130, s[44:45]
	s_add_i32 m0, s46, 0x2000
	s_nop 0
	global_load_lds_dwordx4 v134, s[44:45]
	s_mov_b32 m0, s59
	s_nop 0
	global_load_lds_dwordx4 v128, s[100:101]
	s_mov_b32 m0, s60
	s_nop 0
	global_load_lds_dwordx4 v132, s[100:101]
	ds_read_b128 v[184:187], v151 offset:49152
	ds_read_b128 v[188:191], v151 offset:50176
	ds_read_b128 v[192:195], v151 offset:51200
	ds_read_b128 v[196:199], v151 offset:52224
	ds_read_b128 v[200:203], v151 offset:53248
	ds_read_b128 v[204:207], v151 offset:54272
	ds_read_b128 v[208:211], v151 offset:55296
	ds_read_b128 v[212:215], v151 offset:56320
	s_waitcnt vmcnt(8)
	s_waitcnt lgkmcnt(0)
	s_barrier
	s_setprio 1
	s_waitcnt lgkmcnt(0)
	v_mfma_f32_16x16x32_bf16 v[60:63], v[152:155], v[184:187], v[60:63]
	v_mfma_f32_16x16x32_bf16 v[56:59], v[160:163], v[184:187], v[56:59]
	v_mfma_f32_16x16x32_bf16 v[44:47], v[152:155], v[192:195], v[44:47]
	v_mfma_f32_16x16x32_bf16 v[40:43], v[160:163], v[192:195], v[40:43]
	v_mfma_f32_16x16x32_bf16 v[28:31], v[152:155], v[200:203], v[28:31]
	v_mfma_f32_16x16x32_bf16 v[24:27], v[160:163], v[200:203], v[24:27]
	v_mfma_f32_16x16x32_bf16 v[12:15], v[152:155], v[208:211], v[12:15]
	v_mfma_f32_16x16x32_bf16 v[8:11], v[160:163], v[208:211], v[8:11]
	v_mfma_f32_16x16x32_bf16 v[60:63], v[156:159], v[188:191], v[60:63]
	v_mfma_f32_16x16x32_bf16 v[56:59], v[164:167], v[188:191], v[56:59]
	v_mfma_f32_16x16x32_bf16 v[44:47], v[156:159], v[196:199], v[44:47]
	v_mfma_f32_16x16x32_bf16 v[40:43], v[164:167], v[196:199], v[40:43]
	v_mfma_f32_16x16x32_bf16 v[28:31], v[156:159], v[204:207], v[28:31]
	v_mfma_f32_16x16x32_bf16 v[24:27], v[164:167], v[204:207], v[24:27]
	v_mfma_f32_16x16x32_bf16 v[12:15], v[156:159], v[212:215], v[12:15]
	v_mfma_f32_16x16x32_bf16 v[8:11], v[164:167], v[212:215], v[8:11]
	s_setprio 0
	s_setprio 1
	v_mfma_f32_16x16x32_bf16 v[52:55], v[168:171], v[184:187], v[52:55]
	v_mfma_f32_16x16x32_bf16 v[48:51], v[176:179], v[184:187], v[48:51]
	v_mfma_f32_16x16x32_bf16 v[36:39], v[168:171], v[192:195], v[36:39]
	v_mfma_f32_16x16x32_bf16 v[32:35], v[176:179], v[192:195], v[32:35]
	v_mfma_f32_16x16x32_bf16 v[20:23], v[168:171], v[200:203], v[20:23]
	v_mfma_f32_16x16x32_bf16 v[16:19], v[176:179], v[200:203], v[16:19]
	v_mfma_f32_16x16x32_bf16 v[4:7], v[168:171], v[208:211], v[4:7]
	v_mfma_f32_16x16x32_bf16 v[0:3], v[176:179], v[208:211], v[0:3]
	v_mfma_f32_16x16x32_bf16 v[52:55], v[172:175], v[188:191], v[52:55]
	v_mfma_f32_16x16x32_bf16 v[48:51], v[180:183], v[188:191], v[48:51]
	v_mfma_f32_16x16x32_bf16 v[36:39], v[172:175], v[196:199], v[36:39]
	v_mfma_f32_16x16x32_bf16 v[32:35], v[180:183], v[196:199], v[32:35]
	v_mfma_f32_16x16x32_bf16 v[20:23], v[172:175], v[204:207], v[20:23]
	v_mfma_f32_16x16x32_bf16 v[16:19], v[180:183], v[204:207], v[16:19]
	v_mfma_f32_16x16x32_bf16 v[4:7], v[172:175], v[212:215], v[4:7]
	v_mfma_f32_16x16x32_bf16 v[0:3], v[180:183], v[212:215], v[0:3]
	s_setprio 0
	s_barrier
	s_add_i32 s69, s69, 2
	s_add_u32 s67, s67, 0x100
	s_addc_u32 s68, s68, 0
	s_add_u32 s42, s42, 0x100
	s_addc_u32 s43, s43, 0
	s_cmp_gt_u32 s69, 29
	s_cbranch_scc0 .LBB0_1099
	s_and_b64 vcc, exec, s[12:13]
	s_cbranch_vccz .LBB0_1102
	s_barrier
